# P4: conv-A loop rewritten (hoisted weights, batched loads, 2 sets); sample_task loads hoisted; scan u_base ring x4 + loader 3-set prefetch
# speedup vs baseline: 1.0030x; 1.0030x over previous
; __device__ __forceinline__ bf16_t f2bf(float f) { return (bf16_t)(pk2(f, 0.f) & 0xffffu); }
; __device__ __forceinline__ float silu_f(float x) { return x * rcp_f(1.f + exp_f(-x)); }
; __device__ __forceinline__ void sample_task(LAS unsigned char* lds, const SampP& P, int task, int tid, int lane, int wave) {
;     ...
;     if (tid < 128) {
;         const int cc = h * 128 + tid;
;         { const float ch = zr[1024 + cc] * zr[2048 + cc]; const float s0a = P.sca[(bs * 2 + 0) * 1024 + cc], s1a = P.sca[(bs * 2 + 1) * 1024 + cc];
;           const float conv = P.caw[cc] * s0a + P.caw[1024 + cc] * s1a + P.caw[2048 + cc] * ch;
;           P.ycat[(size_t)(MP + bs) * DM + cc] = f2bf(zr[cc] * conv * silu_f(zr[3072 + cc]));
;           P.oca[(bs * 2 + 0) * 1024 + cc] = s1a; P.oca[(bs * 2 + 1) * 1024 + cc] = ch; }
; #pragma unroll
;         for (int m = 0; m < 3; ++m) { const int c3 = m * 1024 + cc; const float pre = zr[4096 + c3];
;             const float a0 = P.scq[(bs * 3 + 0) * 3072 + c3], a1 = P.scq[(bs * 3 + 1) * 3072 + c3], a2 = P.scq[(bs * 3 + 2) * 3072 + c3];
;             qkv[m] = silu_f(P.cqw[c3] * a0 + P.cqw[3072 + c3] * a1 + P.cqw[2 * 3072 + c3] * a2 + P.cqw[3 * 3072 + c3] * pre);
;             P.ocq[(bs * 3 + 0) * 3072 + c3] = a1; P.ocq[(bs * 3 + 1) * 3072 + c3] = a2; P.ocq[(bs * 3 + 2) * 3072 + c3] = pre; }
.LBB0_481:
	s_or_b64 exec, exec, s[10:11]
	v_mov_b32_e32 v134, 0
	v_mov_b32_e32 v135, 0
	s_and_saveexec_b64 s[10:11], s[6:7]
	s_cbranch_execz .LBB0_485
	v_lshl_add_u64 v[222:223], v[64:65], 2, v[138:139]
	v_lshl_add_u64 v[224:225], v[66:67], 2, v[138:139]
	v_lshl_add_u64 v[226:227], v[62:63], 2, v[138:139]
	global_load_dword v174, v[222:223], off
	global_load_dword v175, v[224:225], off
	global_load_dword v176, v[226:227], off
	s_mov_b64 s[28:29], 0x4000
	v_lshl_add_u64 v[222:223], v[222:223], 0, s[28:29]
	v_lshl_add_u64 v[224:225], v[224:225], 0, s[28:29]
	v_lshl_add_u64 v[226:227], v[226:227], 0, s[28:29]
	global_load_dword v177, v[222:223], off
	global_load_dword v178, v[224:225], off
	global_load_dword v179, v[226:227], off
	global_load_dword v180, v[226:227], off offset:-4096
	v_lshl_add_u32 v228, s26, 11, v62
	v_ashrrev_i32_e32 v229, 31, v228
	v_lshlrev_b64 v[228:229], 2, v[228:229]
	v_lshl_add_u64 v[230:231], v[48:49], 0, v[228:229]
	global_load_dword v181, v[230:231], off
	v_lshl_add_u64 v[230:231], v[230:231], 0, s[52:53]
	global_load_dword v182, v[230:231], off
	global_load_dword v183, v[68:69], off
	global_load_dword v184, v[70:71], off
	global_load_dword v185, v[72:73], off
	s_mul_i32 s19, s26, 0x2400
	v_add_u32_e32 v228, s19, v62
	v_ashrrev_i32_e32 v229, 31, v228
	v_lshlrev_b64 v[228:229], 2, v[228:229]
	v_lshl_add_u64 v[230:231], v[50:51], 0, v[228:229]
	v_lshl_add_u64 v[230:231], v[230:231], 0, s[52:53]
	global_load_dword v186, v[230:231], off offset:-4096
	global_load_dword v187, v[230:231], off
	v_lshl_add_u64 v[230:231], v[230:231], 0, s[48:49]
	global_load_dword v188, v[230:231], off offset:-4096
	global_load_dword v189, v[230:231], off
	v_lshl_add_u64 v[230:231], v[230:231], 0, s[48:49]
	global_load_dword v190, v[230:231], off offset:-4096
	global_load_dword v191, v[230:231], off
	v_lshl_add_u64 v[230:231], v[230:231], 0, s[48:49]
	global_load_dword v200, v[230:231], off offset:-4096
	global_load_dword v201, v[230:231], off
	v_lshl_add_u64 v[230:231], v[230:231], 0, s[48:49]
	global_load_dword v202, v[230:231], off offset:-4096
	global_load_dword v204, v[76:77], off
	global_load_dword v205, v[78:79], off
	global_load_dword v206, v[80:81], off
	global_load_dword v207, v[82:83], off
	global_load_dword v208, v[84:85], off
	global_load_dword v209, v[86:87], off
	global_load_dword v210, v[88:89], off
	global_load_dword v211, v[90:91], off
	global_load_dword v212, v[92:93], off
	global_load_dword v213, v[94:95], off
	global_load_dword v214, v[96:97], off
	global_load_dword v215, v[98:99], off
	s_waitcnt vmcnt(0)
	v_lshl_add_u64 v[134:135], v[64:65], 2, v[138:139]
	v_lshl_add_u64 v[136:137], v[66:67], 2, v[138:139]
	v_mov_b32_e32 v140, v174
	v_mov_b32_e32 v141, v175
	v_lshl_add_u64 v[138:139], v[62:63], 2, v[138:139]
	s_ashr_i32 s27, s26, 31
	s_lshl_b64 s[28:29], s[26:27], 12
	s_brev_b32 s19, 64
	v_mul_f32_e32 v166, v140, v141
	v_lshl_add_u32 v140, s26, 11, v62
	v_add_u32_e32 v146, 0x400, v140
	v_ashrrev_i32_e32 v141, 31, v140
	v_ashrrev_i32_e32 v147, 31, v146
	v_lshlrev_b64 v[142:143], 2, v[140:141]
	v_lshlrev_b64 v[146:147], 2, v[146:147]
	v_lshl_add_u64 v[144:145], v[48:49], 0, v[142:143]
	v_lshl_add_u64 v[148:149], v[48:49], 0, v[146:147]
	v_mov_b32_e32 v144, v181
	s_nop 0
	v_mov_b32_e32 v145, v182
	s_nop 0
	v_mov_b32_e32 v148, v183
	v_mov_b32_e32 v149, v184
	v_mov_b32_e32 v164, v176
	v_add_co_u32_e32 v138, vcc, s77, v138
	v_mov_b32_e32 v141, v185
	s_nop 0
	v_addc_co_u32_e32 v139, vcc, 0, v139, vcc
	v_mov_b32_e32 v165, v180
	v_lshl_add_u64 v[142:143], v[52:53], 0, v[142:143]
	global_store_dword v[142:143], v145, off
	v_lshl_add_u64 v[142:143], v[52:53], 0, v[146:147]
	v_pk_mul_f32 v[148:149], v[144:145], v[148:149]
	global_store_dword v[142:143], v166, off
	v_add_f32_e32 v148, v148, v149
	v_mov_b32_e32 v138, v179
	v_fmac_f32_e32 v148, v166, v141
	v_mul_f32_e32 v141, 0xbfb8aa3b, v165
	v_exp_f32_e32 v141, v141
	s_nop 0
	v_add_f32_e32 v141, 1.0, v141
	v_rcp_f32_e32 v149, v141
	s_nop 0
	v_pk_mul_f32 v[148:149], v[164:165], v[148:149]
	s_nop 0
	v_mul_f32_e32 v141, v148, v149
	v_lshl_add_u64 v[148:149], v[74:75], 0, s[28:29]
	v_add_co_u32_e32 v148, vcc, s19, v148
	s_mul_i32 s19, s26, 0x2400
	s_add_i32 s27, s19, 0xc00
	s_mul_i32 s28, s26, 0x1c00
	v_cvt_pk_bf16_f32 v141, v141, v153
	v_addc_co_u32_e32 v149, vcc, 0, v149, vcc
	v_add_u32_e32 v140, s28, v140
	v_add_u32_e32 v142, s27, v62
	global_store_short v[148:149], v141, off
	v_ashrrev_i32_e32 v141, 31, v140
	v_ashrrev_i32_e32 v143, 31, v142
	v_lshlrev_b64 v[144:145], 2, v[140:141]
	v_lshlrev_b64 v[146:147], 2, v[142:143]
	v_lshl_add_u64 v[140:141], v[50:51], 0, v[144:145]
	v_lshl_add_u64 v[142:143], v[50:51], 0, v[146:147]
	s_add_i32 s25, s19, 0x1800
	v_mov_b32_e32 v140, v186
	v_add_u32_e32 v148, s25, v62
	v_mov_b32_e32 v142, v189
	v_ashrrev_i32_e32 v149, 31, v148
	v_lshlrev_b64 v[148:149], 2, v[148:149]
	v_lshl_add_u64 v[164:165], v[50:51], 0, v[148:149]
	v_mov_b32_e32 v164, v200
	s_nop 0
	v_mov_b32_e32 v166, v204
	v_mov_b32_e32 v168, v205
	v_mov_b32_e32 v170, v206
	v_mov_b32_e32 v172, v207
	v_lshl_add_u64 v[144:145], v[54:55], 0, v[144:145]
	v_add_co_u32_e32 v134, vcc, s77, v134
	global_store_dword v[144:145], v142, off
; __device__ __forceinline__ float silu_f(float x) { return x * rcp_f(1.f + exp_f(-x)); }
; __device__ __forceinline__ void sample_task(LAS unsigned char* lds, const SampP& P, int task, int tid, int lane, int wave) {
;     ...
;         for (int m = 0; m < 3; ++m) { const int c3 = m * 1024 + cc; const float pre = zr[4096 + c3];
;             const float a0 = P.scq[(bs * 3 + 0) * 3072 + c3], a1 = P.scq[(bs * 3 + 1) * 3072 + c3], a2 = P.scq[(bs * 3 + 2) * 3072 + c3];
;             qkv[m] = silu_f(P.cqw[c3] * a0 + P.cqw[3072 + c3] * a1 + P.cqw[2 * 3072 + c3] * a2 + P.cqw[3 * 3072 + c3] * pre);
;             P.ocq[(bs * 3 + 0) * 3072 + c3] = a1; P.ocq[(bs * 3 + 1) * 3072 + c3] = a2; P.ocq[(bs * 3 + 2) * 3072 + c3] = pre; }
;         const float sq = wave_sum(qkv[0] * qkv[0]), sk = wave_sum(qkv[1] * qkv[1]);
;         if (lane == 0) { part[wave * 2] = sq; part[wave * 2 + 1] = sk; }
	v_lshl_add_u64 v[144:145], v[54:55], 0, v[146:147]
	global_store_dword v[144:145], v164, off
	v_lshl_add_u64 v[144:145], v[54:55], 0, v[148:149]
	global_store_dword v[144:145], v138, off
	v_addc_co_u32_e32 v135, vcc, 0, v135, vcc
	v_mov_b32_e32 v139, v177
	v_add_u32_e32 v134, s19, v64
	v_ashrrev_i32_e32 v135, 31, v134
	v_lshlrev_b64 v[144:145], 2, v[134:135]
	v_lshl_add_u64 v[134:135], v[50:51], 0, v[144:145]
	v_mov_b32_e32 v141, v187
	v_add_u32_e32 v134, s27, v64
	v_ashrrev_i32_e32 v135, 31, v134
	v_lshlrev_b64 v[146:147], 2, v[134:135]
	v_lshl_add_u64 v[134:135], v[50:51], 0, v[146:147]
	v_mov_b32_e32 v143, v190
	v_add_u32_e32 v134, s25, v64
	v_ashrrev_i32_e32 v135, 31, v134
	v_lshlrev_b64 v[148:149], 2, v[134:135]
	v_lshl_add_u64 v[134:135], v[50:51], 0, v[148:149]
	v_mov_b32_e32 v165, v201
	v_mov_b32_e32 v167, v208
	v_mov_b32_e32 v169, v209
	v_mov_b32_e32 v171, v210
	v_mov_b32_e32 v173, v211
	v_add_co_u32_e32 v136, vcc, s77, v136
	v_pk_mul_f32 v[134:135], v[142:143], v[168:169]
	s_nop 0
	v_pk_fma_f32 v[134:135], v[140:141], v[166:167], v[134:135]
	v_addc_co_u32_e32 v137, vcc, 0, v137, vcc
	v_pk_fma_f32 v[134:135], v[164:165], v[170:171], v[134:135]
	v_pk_fma_f32 v[134:135], v[138:139], v[172:173], v[134:135]
	s_nop 0
	v_mul_f32_e32 v138, 0xbfb8aa3b, v134
	v_exp_f32_e32 v138, v138
	s_nop 0
	v_add_f32_e32 v138, 1.0, v138
	v_rcp_f32_e32 v140, v138
	v_mul_f32_e32 v138, 0xbfb8aa3b, v135
	v_exp_f32_e32 v138, v138
	s_nop 0
	v_add_f32_e32 v138, 1.0, v138
	v_rcp_f32_e32 v141, v138
	v_add_u32_e32 v138, s19, v66
	v_pk_mul_f32 v[134:135], v[134:135], v[140:141]
	v_lshl_add_u64 v[140:141], v[54:55], 0, v[144:145]
	global_store_dword v[140:141], v143, off
	v_lshl_add_u64 v[140:141], v[54:55], 0, v[146:147]
	global_store_dword v[140:141], v165, off
	v_lshl_add_u64 v[140:141], v[54:55], 0, v[148:149]
	global_store_dword v[140:141], v139, off
	v_add_u32_e32 v140, s27, v66
	v_ashrrev_i32_e32 v139, 31, v138
	v_ashrrev_i32_e32 v141, 31, v140
	v_lshlrev_b64 v[144:145], 2, v[138:139]
	v_lshlrev_b64 v[146:147], 2, v[140:141]
	v_lshl_add_u64 v[138:139], v[50:51], 0, v[144:145]
	v_lshl_add_u64 v[140:141], v[50:51], 0, v[146:147]
	v_mov_b32_e32 v138, v188
	v_lshl_add_u64 v[144:145], v[54:55], 0, v[144:145]
	v_mov_b32_e32 v139, v191
	v_add_u32_e32 v140, s25, v66
	v_mov_b32_e32 v137, v178
	v_ashrrev_i32_e32 v141, 31, v140
	v_lshlrev_b64 v[148:149], 2, v[140:141]
	v_lshl_add_u64 v[140:141], v[50:51], 0, v[148:149]
	v_mov_b32_e32 v136, v202
	v_mov_b32_e32 v142, v212
	v_mov_b32_e32 v143, v213
	s_nop 0
	v_mov_b32_e32 v140, v214
	v_mov_b32_e32 v141, v215
	global_store_dword v[144:145], v139, off
	v_lshl_add_u64 v[144:145], v[54:55], 0, v[146:147]
	global_store_dword v[144:145], v136, off
	v_lshl_add_u64 v[144:145], v[54:55], 0, v[148:149]
	global_store_dword v[144:145], v137, off
	v_and_b32_e32 v144, 64, v192
	v_add_u32_e32 v144, 64, v144
	v_xor_b32_e32 v145, 1, v192
	v_cmp_lt_i32_e32 vcc, v145, v144
	s_nop 1
	v_cndmask_b32_e32 v145, v192, v145, vcc
	v_lshlrev_b32_e32 v146, 2, v145
	v_xor_b32_e32 v145, 2, v192
	v_cmp_lt_i32_e32 vcc, v145, v144
	s_nop 1
	v_cndmask_b32_e32 v145, v192, v145, vcc
	v_lshlrev_b32_e32 v147, 2, v145
	v_xor_b32_e32 v145, 4, v192
	v_cmp_lt_i32_e32 vcc, v145, v144
	s_nop 1
	v_cndmask_b32_e32 v145, v192, v145, vcc
	v_lshlrev_b32_e32 v148, 2, v145
	v_xor_b32_e32 v145, 8, v192
	v_cmp_lt_i32_e32 vcc, v145, v144
	s_nop 1
	v_cndmask_b32_e32 v145, v192, v145, vcc
	v_lshlrev_b32_e32 v149, 2, v145
	v_xor_b32_e32 v145, 16, v192
	v_cmp_lt_i32_e32 vcc, v145, v144
	s_nop 1
	v_cndmask_b32_e32 v145, v192, v145, vcc
	v_lshlrev_b32_e32 v164, 2, v145
	v_xor_b32_e32 v145, 32, v192
	v_cmp_lt_i32_e32 vcc, v145, v144
	s_nop 1
	v_cndmask_b32_e32 v144, v192, v145, vcc
	v_lshlrev_b32_e32 v165, 2, v144
	v_pk_mul_f32 v[144:145], v[134:135], v[134:135]
	ds_bpermute_b32 v144, v146, v144
	ds_bpermute_b32 v145, v146, v145
	s_waitcnt lgkmcnt(0)
	v_pk_fma_f32 v[144:145], v[134:135], v[134:135], v[144:145]
	ds_bpermute_b32 v146, v147, v144
	ds_bpermute_b32 v147, v147, v145
	s_waitcnt lgkmcnt(0)
	v_pk_add_f32 v[144:145], v[144:145], v[146:147]
	ds_bpermute_b32 v146, v148, v144
	ds_bpermute_b32 v147, v148, v145
	s_waitcnt lgkmcnt(0)
	v_pk_add_f32 v[144:145], v[144:145], v[146:147]
	ds_bpermute_b32 v146, v149, v144
	ds_bpermute_b32 v147, v149, v145
	s_waitcnt lgkmcnt(0)
	v_pk_add_f32 v[144:145], v[144:145], v[146:147]
	ds_bpermute_b32 v146, v164, v144
	ds_bpermute_b32 v147, v164, v145
	s_waitcnt lgkmcnt(0)
	v_pk_add_f32 v[144:145], v[144:145], v[146:147]
	ds_bpermute_b32 v146, v165, v144
	ds_bpermute_b32 v147, v165, v145
	s_and_saveexec_b64 s[28:29], s[8:9]
	s_cbranch_execz .LBB0_484
	s_waitcnt lgkmcnt(0)
	v_pk_add_f32 v[144:145], v[144:145], v[146:147]
	v_mov_b32_e32 v146, s31
	ds_write_b64 v146, v[144:145] offset:1536
.LBB0_484:
	s_or_b64 exec, exec, s[28:29]
	v_pk_mul_f32 v[138:139], v[138:139], v[142:143]
	v_pk_mul_f32 v[136:137], v[136:137], v[140:141]
	v_add_f32_e32 v138, v138, v139
	v_add_f32_e32 v136, v138, v136
	v_add_f32_e32 v136, v136, v137
	v_mul_f32_e32 v137, 0xbfb8aa3b, v136
	v_exp_f32_e32 v137, v137
	s_nop 0
	v_add_f32_e32 v137, 1.0, v137
	v_rcp_f32_e32 v137, v137
	s_nop 0
	v_mul_f32_e32 v136, v136, v137

; __device__ __forceinline__ float bflo(unsigned w) { return __uint_as_float(w << 16); }
; __device__ __forceinline__ float bfhi(unsigned w) { return __uint_as_float(w & 0xffff0000u); }
; __device__ __forceinline__ void conva_prompt(const bf16_t* z, const float* caw, bf16_t* ycat, int gt, int GT) {
; #pragma unroll 2
;     for (int idx = gt; idx < MP * 128; idx += GT) {
;         const int row = idx >> 7, c8 = (idx & 127) * 8, t = row & (SEQ - 1);
;         const bf16_t* zr = z + (size_t)row * NZ + c8;
;         float conv[8];
; #pragma unroll
;         for (int i = 0; i < 8; ++i) conv[i] = 0.f;
; #pragma unroll
;         for (int j = 0; j < 3; ++j) {
;             const bool ok = t - 2 + j >= 0; const ptrdiff_t ro = (ptrdiff_t)(ok ? j - 2 : 0) * NZ;
;             u32x4 c = *(const u32x4*)(zr + ro + 1024); const u32x4 hh = *(const u32x4*)(zr + ro + 2048);
;             if (!ok) c = (u32x4){0u, 0u, 0u, 0u};
;             const f32x4 w0 = *(const f32x4*)(caw + j * 1024 + c8), w1 = *(const f32x4*)(caw + j * 1024 + c8 + 4);
;             conv[0] += w0.x * (bflo(c.x) * bflo(hh.x)); conv[1] += w0.y * (bfhi(c.x) * bfhi(hh.x)); conv[2] += w0.z * (bflo(c.y) * bflo(hh.y)); conv[3] += w0.w * (bfhi(c.y) * bfhi(hh.y));
;             conv[4] += w1.x * (bflo(c.z) * bflo(hh.z)); conv[5] += w1.y * (bfhi(c.z) * bfhi(hh.z)); conv[6] += w1.z * (bflo(c.w) * bflo(hh.w)); conv[7] += w1.w * (bfhi(c.w) * bfhi(hh.w));
;         }
.LBB0_494:
	s_mov_b64 s[4:5], 0x13c00000
	v_lshl_add_u32 v4, s18, 9, v150
	v_lshl_add_u64 v[0:1], v[2:3], 0, s[4:5]
	s_mov_b32 s4, 0x100000
	v_cmp_gt_i32_e32 vcc, s4, v4
	s_and_saveexec_b64 s[6:7], vcc
	s_cbranch_execz .LBB0_497
	s_waitcnt vmcnt(0) lgkmcnt(0)
	s_load_dwordx2 s[48:49], s[0:1], 0x98
	s_load_dwordx2 s[16:17], s[0:1], 0x58
	s_mul_i32 s4, s92, 0x3000
	s_cmp_lt_u32 s18, 0x80
	s_cselect_b32 s18, 9, 8
	s_mov_b32 s32, 0xffff0000
	s_mov_b32 s35, 0xbfb8aa3b
	v_and_b32_e32 v32, 0x7f, v4
	v_lshlrev_b32_e32 v34, 5, v32
	v_lshlrev_b32_e32 v32, 4, v32
	v_add_u32_e32 v38, 0x1000, v34
	v_add_u32_e32 v39, 0x2000, v34
	v_add_u32_e32 v46, 0x1000, v32
	v_mov_b32_e32 v33, v4
	s_waitcnt lgkmcnt(0)
	s_add_u32 s52, s48, 0x20300000
	s_addc_u32 s53, s49, 0
	s_add_u32 s48, s48, 0x13c00000
	s_addc_u32 s49, s49, 0
	s_add_u32 s16, s16, s4
	s_addc_u32 s17, s17, 0
	global_load_dwordx4 v[8:11], v34, s[16:17]
	global_load_dwordx4 v[12:15], v34, s[16:17] offset:16
	global_load_dwordx4 v[16:19], v38, s[16:17]
	global_load_dwordx4 v[20:23], v38, s[16:17] offset:16
	global_load_dwordx4 v[24:27], v39, s[16:17]
	global_load_dwordx4 v[28:31], v39, s[16:17] offset:16
	v_lshrrev_b32_e32 v34, 7, v33
	v_and_b32_e32 v89, 0x7ff, v34
	v_lshl_add_u32 v35, v34, 14, v46
	v_min_u32_e32 v36, 2, v89
	v_min_u32_e32 v37, 1, v89
	v_lshlrev_b32_e32 v36, 14, v36
	v_lshlrev_b32_e32 v37, 14, v37
	v_sub_u32_e32 v36, v35, v36
	v_sub_u32_e32 v37, v35, v37
	v_lshl_add_u32 v88, v34, 12, v32
	global_load_dwordx4 v[56:59], v36, s[48:49] offset:-2048
	global_load_dwordx4 v[60:63], v36, s[48:49]
	global_load_dwordx4 v[64:67], v37, s[48:49] offset:-2048
	global_load_dwordx4 v[68:71], v37, s[48:49]
	global_load_dwordx4 v[72:75], v35, s[48:49] offset:-2048
	global_load_dwordx4 v[76:79], v35, s[48:49]
	global_load_dwordx4 v[80:83], v35, s[48:49] offset:-4096
	global_load_dwordx4 v[84:87], v35, s[48:49] offset:2048
	v_add_u32_e32 v33, 0x18000, v33
	v_lshrrev_b32_e32 v34, 7, v33
	v_and_b32_e32 v125, 0x7ff, v34
	v_lshl_add_u32 v35, v34, 14, v46
	v_min_u32_e32 v36, 2, v125
	v_min_u32_e32 v37, 1, v125
	v_lshlrev_b32_e32 v36, 14, v36
	v_lshlrev_b32_e32 v37, 14, v37
	v_sub_u32_e32 v36, v35, v36
	v_sub_u32_e32 v37, v35, v37
	v_lshl_add_u32 v124, v34, 12, v32
	global_load_dwordx4 v[92:95], v36, s[48:49] offset:-2048
	global_load_dwordx4 v[96:99], v36, s[48:49]
	global_load_dwordx4 v[100:103], v37, s[48:49] offset:-2048
	global_load_dwordx4 v[104:107], v37, s[48:49]
	global_load_dwordx4 v[108:111], v35, s[48:49] offset:-2048
	global_load_dwordx4 v[112:115], v35, s[48:49]
	global_load_dwordx4 v[116:119], v35, s[48:49] offset:-4096
	global_load_dwordx4 v[120:123], v35, s[48:49] offset:2048
	v_add_u32_e32 v33, 0x18000, v33
	s_waitcnt vmcnt(8)
	v_cmp_lt_u32_e32 vcc, 1, v89
	v_lshlrev_b32_e32 v136, 16, v60
	v_and_b32_e32 v137, s32, v60
	v_lshlrev_b32_e32 v138, 16, v61
	v_and_b32_e32 v139, s32, v61
	v_lshlrev_b32_e32 v140, 16, v62
	v_and_b32_e32 v141, s32, v62
	v_lshlrev_b32_e32 v142, 16, v63
	v_and_b32_e32 v143, s32, v63
	v_cndmask_b32_e32 v56, 0, v56, vcc
	v_cndmask_b32_e32 v57, 0, v57, vcc
	v_cndmask_b32_e32 v58, 0, v58, vcc
	v_cndmask_b32_e32 v59, 0, v59, vcc
	v_cmp_ne_u32_e32 vcc, 0, v89
	v_lshlrev_b32_e32 v128, 16, v56
	v_and_b32_e32 v129, s32, v56
	v_lshlrev_b32_e32 v130, 16, v57
	v_and_b32_e32 v131, s32, v57
	v_lshlrev_b32_e32 v132, 16, v58
	v_and_b32_e32 v133, s32, v58
	v_lshlrev_b32_e32 v134, 16, v59
	v_and_b32_e32 v135, s32, v59
	v_cndmask_b32_e32 v64, 0, v64, vcc
	v_cndmask_b32_e32 v65, 0, v65, vcc
	v_cndmask_b32_e32 v66, 0, v66, vcc
	v_cndmask_b32_e32 v67, 0, v67, vcc
	v_pk_mul_f32 v[128:129], v[128:129], v[136:137]
	v_pk_mul_f32 v[130:131], v[130:131], v[138:139]
	v_pk_mul_f32 v[132:133], v[132:133], v[140:141]
	v_pk_mul_f32 v[134:135], v[134:135], v[142:143]
	v_pk_mul_f32 v[160:161], v[8:9], v[128:129]
	v_pk_mul_f32 v[162:163], v[10:11], v[130:131]
	v_pk_mul_f32 v[164:165], v[12:13], v[132:133]
	v_pk_mul_f32 v[166:167], v[14:15], v[134:135]
	v_lshlrev_b32_e32 v128, 16, v64
	v_and_b32_e32 v129, s32, v64
	v_lshlrev_b32_e32 v130, 16, v65
	v_and_b32_e32 v131, s32, v65
	v_lshlrev_b32_e32 v132, 16, v66
	v_and_b32_e32 v133, s32, v66
	v_lshlrev_b32_e32 v134, 16, v67
	v_and_b32_e32 v135, s32, v67
	v_lshlrev_b32_e32 v136, 16, v68
	v_and_b32_e32 v137, s32, v68
	v_lshlrev_b32_e32 v138, 16, v69
	v_and_b32_e32 v139, s32, v69
	v_lshlrev_b32_e32 v140, 16, v70
	v_and_b32_e32 v141, s32, v70
	v_lshlrev_b32_e32 v142, 16, v71
	v_and_b32_e32 v143, s32, v71
	v_pk_mul_f32 v[128:129], v[128:129], v[136:137]
	v_pk_mul_f32 v[130:131], v[130:131], v[138:139]
	v_pk_mul_f32 v[132:133], v[132:133], v[140:141]
	v_pk_mul_f32 v[134:135], v[134:135], v[142:143]
	v_pk_fma_f32 v[160:161], v[16:17], v[128:129], v[160:161]
	v_pk_fma_f32 v[162:163], v[18:19], v[130:131], v[162:163]
	v_pk_fma_f32 v[164:165], v[20:21], v[132:133], v[164:165]
	v_pk_fma_f32 v[166:167], v[22:23], v[134:135], v[166:167]
	v_lshlrev_b32_e32 v128, 16, v72
	v_and_b32_e32 v129, s32, v72
	v_lshlrev_b32_e32 v130, 16, v73
	v_and_b32_e32 v131, s32, v73
	v_lshlrev_b32_e32 v132, 16, v74
	v_and_b32_e32 v133, s32, v74
	v_lshlrev_b32_e32 v134, 16, v75
	v_and_b32_e32 v135, s32, v75
	v_lshlrev_b32_e32 v136, 16, v76
	v_and_b32_e32 v137, s32, v76
	v_lshlrev_b32_e32 v138, 16, v77
	v_and_b32_e32 v139, s32, v77
	v_lshlrev_b32_e32 v140, 16, v78
	v_and_b32_e32 v141, s32, v78
	v_lshlrev_b32_e32 v142, 16, v79
	v_and_b32_e32 v143, s32, v79
	v_pk_mul_f32 v[128:129], v[128:129], v[136:137]
	v_pk_mul_f32 v[130:131], v[130:131], v[138:139]
	v_pk_mul_f32 v[132:133], v[132:133], v[140:141]
	v_pk_mul_f32 v[134:135], v[134:135], v[142:143]
	v_pk_fma_f32 v[160:161], v[24:25], v[128:129], v[160:161]
; __device__ __forceinline__ float bflo(unsigned w) { return __uint_as_float(w << 16); }
; __device__ __forceinline__ float bfhi(unsigned w) { return __uint_as_float(w & 0xffff0000u); }
; __device__ __forceinline__ float silu_f(float x) { return x * rcp_f(1.f + exp_f(-x)); }
; __device__ __forceinline__ u32x4 pack8(const float* v) { u32x4 o; o.x = pk2(v[0], v[1]); o.y = pk2(v[2], v[3]); o.z = pk2(v[4], v[5]); o.w = pk2(v[6], v[7]); return o; }
; __device__ __forceinline__ void conva_prompt(const bf16_t* z, const float* caw, bf16_t* ycat, int gt, int GT) {
; #pragma unroll 2
;     for (int idx = gt; idx < MP * 128; idx += GT) {
;         const int row = idx >> 7, c8 = (idx & 127) * 8, t = row & (SEQ - 1);
;         const bf16_t* zr = z + (size_t)row * NZ + c8;
;         float conv[8];
; #pragma unroll
;         for (int i = 0; i < 8; ++i) conv[i] = 0.f;
; #pragma unroll
;         for (int j = 0; j < 3; ++j) {
;             const bool ok = t - 2 + j >= 0; const ptrdiff_t ro = (ptrdiff_t)(ok ? j - 2 : 0) * NZ;
;             u32x4 c = *(const u32x4*)(zr + ro + 1024); const u32x4 hh = *(const u32x4*)(zr + ro + 2048);
;             if (!ok) c = (u32x4){0u, 0u, 0u, 0u};
;             const f32x4 w0 = *(const f32x4*)(caw + j * 1024 + c8), w1 = *(const f32x4*)(caw + j * 1024 + c8 + 4);
;             conv[0] += w0.x * (bflo(c.x) * bflo(hh.x)); conv[1] += w0.y * (bfhi(c.x) * bfhi(hh.x)); conv[2] += w0.z * (bflo(c.y) * bflo(hh.y)); conv[3] += w0.w * (bfhi(c.y) * bfhi(hh.y));
;             conv[4] += w1.x * (bflo(c.z) * bflo(hh.z)); conv[5] += w1.y * (bfhi(c.z) * bfhi(hh.z)); conv[6] += w1.z * (bflo(c.w) * bflo(hh.w)); conv[7] += w1.w * (bfhi(c.w) * bfhi(hh.w));
;         }
;         const u32x4 bb = *(const u32x4*)zr, gg = *(const u32x4*)(zr + 3072);
;         float y[8];
;         y[0] = bflo(bb.x) * conv[0] * silu_f(bflo(gg.x)); y[1] = bfhi(bb.x) * conv[1] * silu_f(bfhi(gg.x)); y[2] = bflo(bb.y) * conv[2] * silu_f(bflo(gg.y)); y[3] = bfhi(bb.y) * conv[3] * silu_f(bfhi(gg.y));
;         y[4] = bflo(bb.z) * conv[4] * silu_f(bflo(gg.z)); y[5] = bfhi(bb.z) * conv[5] * silu_f(bfhi(gg.z)); y[6] = bflo(bb.w) * conv[6] * silu_f(bflo(gg.w)); y[7] = bfhi(bb.w) * conv[7] * silu_f(bfhi(gg.w));
;         *(u32x4*)(ycat + (size_t)row * DM + c8) = pack8(y);
;     }
	v_pk_fma_f32 v[162:163], v[26:27], v[130:131], v[162:163]
	v_pk_fma_f32 v[164:165], v[28:29], v[132:133], v[164:165]
	v_pk_fma_f32 v[166:167], v[30:31], v[134:135], v[166:167]
	v_lshlrev_b32_e32 v176, 16, v84
	v_and_b32_e32 v177, s32, v84
	v_lshlrev_b32_e32 v178, 16, v85
	v_and_b32_e32 v179, s32, v85
	v_lshlrev_b32_e32 v180, 16, v86
	v_and_b32_e32 v181, s32, v86
	v_lshlrev_b32_e32 v182, 16, v87
	v_and_b32_e32 v183, s32, v87
	v_mul_f32_e32 v184, s35, v176
	v_mul_f32_e32 v185, s35, v177
	v_mul_f32_e32 v186, s35, v178
	v_mul_f32_e32 v187, s35, v179
	v_mul_f32_e32 v188, s35, v180
	v_mul_f32_e32 v189, s35, v181
	v_mul_f32_e32 v190, s35, v182
	v_mul_f32_e32 v191, s35, v183
	v_exp_f32_e32 v184, v184
	v_exp_f32_e32 v185, v185
	v_exp_f32_e32 v186, v186
	v_exp_f32_e32 v187, v187
	v_exp_f32_e32 v188, v188
	v_exp_f32_e32 v189, v189
	v_exp_f32_e32 v190, v190
	v_exp_f32_e32 v191, v191
	v_lshlrev_b32_e32 v168, 16, v80
	v_and_b32_e32 v169, s32, v80
	v_lshlrev_b32_e32 v170, 16, v81
	v_and_b32_e32 v171, s32, v81
	v_lshlrev_b32_e32 v172, 16, v82
	v_and_b32_e32 v173, s32, v82
	v_lshlrev_b32_e32 v174, 16, v83
	v_and_b32_e32 v175, s32, v83
	v_add_f32_e32 v184, 1.0, v184
	v_add_f32_e32 v185, 1.0, v185
	v_add_f32_e32 v186, 1.0, v186
	v_add_f32_e32 v187, 1.0, v187
	v_add_f32_e32 v188, 1.0, v188
	v_add_f32_e32 v189, 1.0, v189
	v_add_f32_e32 v190, 1.0, v190
	v_add_f32_e32 v191, 1.0, v191
	v_rcp_f32_e32 v184, v184
	v_rcp_f32_e32 v185, v185
	v_rcp_f32_e32 v186, v186
	v_rcp_f32_e32 v187, v187
	v_rcp_f32_e32 v188, v188
	v_rcp_f32_e32 v189, v189
	v_rcp_f32_e32 v190, v190
	v_rcp_f32_e32 v191, v191
	v_pk_mul_f32 v[168:169], v[168:169], v[160:161]
	v_pk_mul_f32 v[170:171], v[170:171], v[162:163]
	v_pk_mul_f32 v[172:173], v[172:173], v[164:165]
	v_pk_mul_f32 v[174:175], v[174:175], v[166:167]
	v_pk_mul_f32 v[176:177], v[176:177], v[184:185]
	v_pk_mul_f32 v[178:179], v[178:179], v[186:187]
	v_pk_mul_f32 v[180:181], v[180:181], v[188:189]
	v_pk_mul_f32 v[182:183], v[182:183], v[190:191]
	v_pk_mul_f32 v[168:169], v[168:169], v[176:177]
	v_pk_mul_f32 v[170:171], v[170:171], v[178:179]
	v_pk_mul_f32 v[172:173], v[172:173], v[180:181]
	v_pk_mul_f32 v[174:175], v[174:175], v[182:183]
	v_cvt_pk_bf16_f32 v40, v168, v169
	v_cvt_pk_bf16_f32 v41, v170, v171
	v_cvt_pk_bf16_f32 v42, v172, v173
	v_cvt_pk_bf16_f32 v43, v174, v175
	global_store_dwordx4 v88, v[40:43], s[52:53]
.Lconva_loop:
	v_lshrrev_b32_e32 v34, 7, v33
	v_and_b32_e32 v89, 0x7ff, v34
	v_lshl_add_u32 v35, v34, 14, v46
	v_min_u32_e32 v36, 2, v89
	v_min_u32_e32 v37, 1, v89
	v_lshlrev_b32_e32 v36, 14, v36
	v_lshlrev_b32_e32 v37, 14, v37
	v_sub_u32_e32 v36, v35, v36
	v_sub_u32_e32 v37, v35, v37
	v_lshl_add_u32 v88, v34, 12, v32
	global_load_dwordx4 v[56:59], v36, s[48:49] offset:-2048
	global_load_dwordx4 v[60:63], v36, s[48:49]
	global_load_dwordx4 v[64:67], v37, s[48:49] offset:-2048
	global_load_dwordx4 v[68:71], v37, s[48:49]
	global_load_dwordx4 v[72:75], v35, s[48:49] offset:-2048
	global_load_dwordx4 v[76:79], v35, s[48:49]
	global_load_dwordx4 v[80:83], v35, s[48:49] offset:-4096
	global_load_dwordx4 v[84:87], v35, s[48:49] offset:2048
	v_add_u32_e32 v33, 0x18000, v33
	s_waitcnt vmcnt(9)
	v_cmp_lt_u32_e32 vcc, 1, v125
	v_lshlrev_b32_e32 v136, 16, v96
	v_and_b32_e32 v137, s32, v96
	v_lshlrev_b32_e32 v138, 16, v97
	v_and_b32_e32 v139, s32, v97
	v_lshlrev_b32_e32 v140, 16, v98
	v_and_b32_e32 v141, s32, v98
	v_lshlrev_b32_e32 v142, 16, v99
	v_and_b32_e32 v143, s32, v99
	v_cndmask_b32_e32 v92, 0, v92, vcc
	v_cndmask_b32_e32 v93, 0, v93, vcc
	v_cndmask_b32_e32 v94, 0, v94, vcc
	v_cndmask_b32_e32 v95, 0, v95, vcc
	v_cmp_ne_u32_e32 vcc, 0, v125
	v_lshlrev_b32_e32 v128, 16, v92
	v_and_b32_e32 v129, s32, v92
	v_lshlrev_b32_e32 v130, 16, v93
	v_and_b32_e32 v131, s32, v93
	v_lshlrev_b32_e32 v132, 16, v94
	v_and_b32_e32 v133, s32, v94
	v_lshlrev_b32_e32 v134, 16, v95
	v_and_b32_e32 v135, s32, v95
	v_cndmask_b32_e32 v100, 0, v100, vcc
	v_cndmask_b32_e32 v101, 0, v101, vcc
	v_cndmask_b32_e32 v102, 0, v102, vcc
	v_cndmask_b32_e32 v103, 0, v103, vcc
	v_pk_mul_f32 v[128:129], v[128:129], v[136:137]
	v_pk_mul_f32 v[130:131], v[130:131], v[138:139]
	v_pk_mul_f32 v[132:133], v[132:133], v[140:141]
	v_pk_mul_f32 v[134:135], v[134:135], v[142:143]
	v_pk_mul_f32 v[160:161], v[8:9], v[128:129]
	v_pk_mul_f32 v[162:163], v[10:11], v[130:131]
	v_pk_mul_f32 v[164:165], v[12:13], v[132:133]
	v_pk_mul_f32 v[166:167], v[14:15], v[134:135]
	v_lshlrev_b32_e32 v128, 16, v100
	v_and_b32_e32 v129, s32, v100
	v_lshlrev_b32_e32 v130, 16, v101
	v_and_b32_e32 v131, s32, v101
	v_lshlrev_b32_e32 v132, 16, v102
	v_and_b32_e32 v133, s32, v102
	v_lshlrev_b32_e32 v134, 16, v103
	v_and_b32_e32 v135, s32, v103
	v_lshlrev_b32_e32 v136, 16, v104
	v_and_b32_e32 v137, s32, v104
	v_lshlrev_b32_e32 v138, 16, v105
	v_and_b32_e32 v139, s32, v105
	v_lshlrev_b32_e32 v140, 16, v106
	v_and_b32_e32 v141, s32, v106
	v_lshlrev_b32_e32 v142, 16, v107
	v_and_b32_e32 v143, s32, v107
	v_pk_mul_f32 v[128:129], v[128:129], v[136:137]
	v_pk_mul_f32 v[130:131], v[130:131], v[138:139]
	v_pk_mul_f32 v[132:133], v[132:133], v[140:141]
	v_pk_mul_f32 v[134:135], v[134:135], v[142:143]
	v_pk_fma_f32 v[160:161], v[16:17], v[128:129], v[160:161]
	v_pk_fma_f32 v[162:163], v[18:19], v[130:131], v[162:163]
	v_pk_fma_f32 v[164:165], v[20:21], v[132:133], v[164:165]
	v_pk_fma_f32 v[166:167], v[22:23], v[134:135], v[166:167]
	v_lshlrev_b32_e32 v128, 16, v108
	v_and_b32_e32 v129, s32, v108
	v_lshlrev_b32_e32 v130, 16, v109
	v_and_b32_e32 v131, s32, v109
	v_lshlrev_b32_e32 v132, 16, v110
	v_and_b32_e32 v133, s32, v110
	v_lshlrev_b32_e32 v134, 16, v111
	v_and_b32_e32 v135, s32, v111
	v_lshlrev_b32_e32 v136, 16, v112
; __device__ __forceinline__ float bflo(unsigned w) { return __uint_as_float(w << 16); }
; __device__ __forceinline__ float bfhi(unsigned w) { return __uint_as_float(w & 0xffff0000u); }
; __device__ __forceinline__ float silu_f(float x) { return x * rcp_f(1.f + exp_f(-x)); }
; __device__ __forceinline__ u32x4 pack8(const float* v) { u32x4 o; o.x = pk2(v[0], v[1]); o.y = pk2(v[2], v[3]); o.z = pk2(v[4], v[5]); o.w = pk2(v[6], v[7]); return o; }
; __device__ __forceinline__ void conva_prompt(const bf16_t* z, const float* caw, bf16_t* ycat, int gt, int GT) {
; #pragma unroll 2
;     for (int idx = gt; idx < MP * 128; idx += GT) {
;         const int row = idx >> 7, c8 = (idx & 127) * 8, t = row & (SEQ - 1);
;         const bf16_t* zr = z + (size_t)row * NZ + c8;
;         float conv[8];
; #pragma unroll
;         for (int i = 0; i < 8; ++i) conv[i] = 0.f;
; #pragma unroll
;         for (int j = 0; j < 3; ++j) {
;             const bool ok = t - 2 + j >= 0; const ptrdiff_t ro = (ptrdiff_t)(ok ? j - 2 : 0) * NZ;
;             u32x4 c = *(const u32x4*)(zr + ro + 1024); const u32x4 hh = *(const u32x4*)(zr + ro + 2048);
;             if (!ok) c = (u32x4){0u, 0u, 0u, 0u};
;             const f32x4 w0 = *(const f32x4*)(caw + j * 1024 + c8), w1 = *(const f32x4*)(caw + j * 1024 + c8 + 4);
;             conv[0] += w0.x * (bflo(c.x) * bflo(hh.x)); conv[1] += w0.y * (bfhi(c.x) * bfhi(hh.x)); conv[2] += w0.z * (bflo(c.y) * bflo(hh.y)); conv[3] += w0.w * (bfhi(c.y) * bfhi(hh.y));
;             conv[4] += w1.x * (bflo(c.z) * bflo(hh.z)); conv[5] += w1.y * (bfhi(c.z) * bfhi(hh.z)); conv[6] += w1.z * (bflo(c.w) * bflo(hh.w)); conv[7] += w1.w * (bfhi(c.w) * bfhi(hh.w));
;         }
;         const u32x4 bb = *(const u32x4*)zr, gg = *(const u32x4*)(zr + 3072);
;         float y[8];
;         y[0] = bflo(bb.x) * conv[0] * silu_f(bflo(gg.x)); y[1] = bfhi(bb.x) * conv[1] * silu_f(bfhi(gg.x)); y[2] = bflo(bb.y) * conv[2] * silu_f(bflo(gg.y)); y[3] = bfhi(bb.y) * conv[3] * silu_f(bfhi(gg.y));
;         y[4] = bflo(bb.z) * conv[4] * silu_f(bflo(gg.z)); y[5] = bfhi(bb.z) * conv[5] * silu_f(bfhi(gg.z)); y[6] = bflo(bb.w) * conv[6] * silu_f(bflo(gg.w)); y[7] = bfhi(bb.w) * conv[7] * silu_f(bfhi(gg.w));
;         *(u32x4*)(ycat + (size_t)row * DM + c8) = pack8(y);
;     }
	v_and_b32_e32 v137, s32, v112
	v_lshlrev_b32_e32 v138, 16, v113
	v_and_b32_e32 v139, s32, v113
	v_lshlrev_b32_e32 v140, 16, v114
	v_and_b32_e32 v141, s32, v114
	v_lshlrev_b32_e32 v142, 16, v115
	v_and_b32_e32 v143, s32, v115
	v_pk_mul_f32 v[128:129], v[128:129], v[136:137]
	v_pk_mul_f32 v[130:131], v[130:131], v[138:139]
	v_pk_mul_f32 v[132:133], v[132:133], v[140:141]
	v_pk_mul_f32 v[134:135], v[134:135], v[142:143]
	v_pk_fma_f32 v[160:161], v[24:25], v[128:129], v[160:161]
	v_pk_fma_f32 v[162:163], v[26:27], v[130:131], v[162:163]
	v_pk_fma_f32 v[164:165], v[28:29], v[132:133], v[164:165]
	v_pk_fma_f32 v[166:167], v[30:31], v[134:135], v[166:167]
	v_lshlrev_b32_e32 v176, 16, v120
	v_and_b32_e32 v177, s32, v120
	v_lshlrev_b32_e32 v178, 16, v121
	v_and_b32_e32 v179, s32, v121
	v_lshlrev_b32_e32 v180, 16, v122
	v_and_b32_e32 v181, s32, v122
	v_lshlrev_b32_e32 v182, 16, v123
	v_and_b32_e32 v183, s32, v123
	v_mul_f32_e32 v184, s35, v176
	v_mul_f32_e32 v185, s35, v177
	v_mul_f32_e32 v186, s35, v178
	v_mul_f32_e32 v187, s35, v179
	v_mul_f32_e32 v188, s35, v180
	v_mul_f32_e32 v189, s35, v181
	v_mul_f32_e32 v190, s35, v182
	v_mul_f32_e32 v191, s35, v183
	v_exp_f32_e32 v184, v184
	v_exp_f32_e32 v185, v185
	v_exp_f32_e32 v186, v186
	v_exp_f32_e32 v187, v187
	v_exp_f32_e32 v188, v188
	v_exp_f32_e32 v189, v189
	v_exp_f32_e32 v190, v190
	v_exp_f32_e32 v191, v191
	v_lshlrev_b32_e32 v168, 16, v116
	v_and_b32_e32 v169, s32, v116
	v_lshlrev_b32_e32 v170, 16, v117
	v_and_b32_e32 v171, s32, v117
	v_lshlrev_b32_e32 v172, 16, v118
	v_and_b32_e32 v173, s32, v118
	v_lshlrev_b32_e32 v174, 16, v119
	v_and_b32_e32 v175, s32, v119
	v_add_f32_e32 v184, 1.0, v184
	v_add_f32_e32 v185, 1.0, v185
	v_add_f32_e32 v186, 1.0, v186
	v_add_f32_e32 v187, 1.0, v187
	v_add_f32_e32 v188, 1.0, v188
	v_add_f32_e32 v189, 1.0, v189
	v_add_f32_e32 v190, 1.0, v190
	v_add_f32_e32 v191, 1.0, v191
	v_rcp_f32_e32 v184, v184
	v_rcp_f32_e32 v185, v185
	v_rcp_f32_e32 v186, v186
	v_rcp_f32_e32 v187, v187
	v_rcp_f32_e32 v188, v188
	v_rcp_f32_e32 v189, v189
	v_rcp_f32_e32 v190, v190
	v_rcp_f32_e32 v191, v191
	v_pk_mul_f32 v[168:169], v[168:169], v[160:161]
	v_pk_mul_f32 v[170:171], v[170:171], v[162:163]
	v_pk_mul_f32 v[172:173], v[172:173], v[164:165]
	v_pk_mul_f32 v[174:175], v[174:175], v[166:167]
	v_pk_mul_f32 v[176:177], v[176:177], v[184:185]
	v_pk_mul_f32 v[178:179], v[178:179], v[186:187]
	v_pk_mul_f32 v[180:181], v[180:181], v[188:189]
	v_pk_mul_f32 v[182:183], v[182:183], v[190:191]
	v_pk_mul_f32 v[168:169], v[168:169], v[176:177]
	v_pk_mul_f32 v[170:171], v[170:171], v[178:179]
	v_pk_mul_f32 v[172:173], v[172:173], v[180:181]
	v_pk_mul_f32 v[174:175], v[174:175], v[182:183]
	v_cvt_pk_bf16_f32 v40, v168, v169
	v_cvt_pk_bf16_f32 v41, v170, v171
	v_cvt_pk_bf16_f32 v42, v172, v173
	v_cvt_pk_bf16_f32 v43, v174, v175
	global_store_dwordx4 v124, v[40:43], s[52:53]
	s_cmp_eq_u32 s18, 0
	s_cbranch_scc1 .Lconva_done
	s_add_i32 s18, s18, -1
	v_lshrrev_b32_e32 v34, 7, v33
	v_and_b32_e32 v125, 0x7ff, v34
	v_lshl_add_u32 v35, v34, 14, v46
	v_min_u32_e32 v36, 2, v125
	v_min_u32_e32 v37, 1, v125
	v_lshlrev_b32_e32 v36, 14, v36
	v_lshlrev_b32_e32 v37, 14, v37
	v_sub_u32_e32 v36, v35, v36
	v_sub_u32_e32 v37, v35, v37
	v_lshl_add_u32 v124, v34, 12, v32
	global_load_dwordx4 v[92:95], v36, s[48:49] offset:-2048
	global_load_dwordx4 v[96:99], v36, s[48:49]
	global_load_dwordx4 v[100:103], v37, s[48:49] offset:-2048
	global_load_dwordx4 v[104:107], v37, s[48:49]
	global_load_dwordx4 v[108:111], v35, s[48:49] offset:-2048
	global_load_dwordx4 v[112:115], v35, s[48:49]
	global_load_dwordx4 v[116:119], v35, s[48:49] offset:-4096
	global_load_dwordx4 v[120:123], v35, s[48:49] offset:2048
	v_add_u32_e32 v33, 0x18000, v33
	s_waitcnt vmcnt(9)
; __device__ __forceinline__ float bflo(unsigned w) { return __uint_as_float(w << 16); }
; __device__ __forceinline__ float bfhi(unsigned w) { return __uint_as_float(w & 0xffff0000u); }
; __device__ __forceinline__ float silu_f(float x) { return x * rcp_f(1.f + exp_f(-x)); }
; __device__ __forceinline__ u32x4 pack8(const float* v) { u32x4 o; o.x = pk2(v[0], v[1]); o.y = pk2(v[2], v[3]); o.z = pk2(v[4], v[5]); o.w = pk2(v[6], v[7]); return o; }
; __device__ __forceinline__ void conva_prompt(const bf16_t* z, const float* caw, bf16_t* ycat, int gt, int GT) {
; #pragma unroll 2
;     for (int idx = gt; idx < MP * 128; idx += GT) {
;         const int row = idx >> 7, c8 = (idx & 127) * 8, t = row & (SEQ - 1);
;         const bf16_t* zr = z + (size_t)row * NZ + c8;
;         float conv[8];
; #pragma unroll
;         for (int i = 0; i < 8; ++i) conv[i] = 0.f;
; #pragma unroll
;         for (int j = 0; j < 3; ++j) {
;             const bool ok = t - 2 + j >= 0; const ptrdiff_t ro = (ptrdiff_t)(ok ? j - 2 : 0) * NZ;
;             u32x4 c = *(const u32x4*)(zr + ro + 1024); const u32x4 hh = *(const u32x4*)(zr + ro + 2048);
;             if (!ok) c = (u32x4){0u, 0u, 0u, 0u};
;             const f32x4 w0 = *(const f32x4*)(caw + j * 1024 + c8), w1 = *(const f32x4*)(caw + j * 1024 + c8 + 4);
;             conv[0] += w0.x * (bflo(c.x) * bflo(hh.x)); conv[1] += w0.y * (bfhi(c.x) * bfhi(hh.x)); conv[2] += w0.z * (bflo(c.y) * bflo(hh.y)); conv[3] += w0.w * (bfhi(c.y) * bfhi(hh.y));
;             conv[4] += w1.x * (bflo(c.z) * bflo(hh.z)); conv[5] += w1.y * (bfhi(c.z) * bfhi(hh.z)); conv[6] += w1.z * (bflo(c.w) * bflo(hh.w)); conv[7] += w1.w * (bfhi(c.w) * bfhi(hh.w));
;         }
;         const u32x4 bb = *(const u32x4*)zr, gg = *(const u32x4*)(zr + 3072);
;         float y[8];
;         y[0] = bflo(bb.x) * conv[0] * silu_f(bflo(gg.x)); y[1] = bfhi(bb.x) * conv[1] * silu_f(bfhi(gg.x)); y[2] = bflo(bb.y) * conv[2] * silu_f(bflo(gg.y)); y[3] = bfhi(bb.y) * conv[3] * silu_f(bfhi(gg.y));
;         y[4] = bflo(bb.z) * conv[4] * silu_f(bflo(gg.z)); y[5] = bfhi(bb.z) * conv[5] * silu_f(bfhi(gg.z)); y[6] = bflo(bb.w) * conv[6] * silu_f(bflo(gg.w)); y[7] = bfhi(bb.w) * conv[7] * silu_f(bfhi(gg.w));
;         *(u32x4*)(ycat + (size_t)row * DM + c8) = pack8(y);
;     }
	v_cmp_lt_u32_e32 vcc, 1, v89
	v_lshlrev_b32_e32 v136, 16, v60
	v_and_b32_e32 v137, s32, v60
	v_lshlrev_b32_e32 v138, 16, v61
	v_and_b32_e32 v139, s32, v61
	v_lshlrev_b32_e32 v140, 16, v62
	v_and_b32_e32 v141, s32, v62
	v_lshlrev_b32_e32 v142, 16, v63
	v_and_b32_e32 v143, s32, v63
	v_cndmask_b32_e32 v56, 0, v56, vcc
	v_cndmask_b32_e32 v57, 0, v57, vcc
	v_cndmask_b32_e32 v58, 0, v58, vcc
	v_cndmask_b32_e32 v59, 0, v59, vcc
	v_cmp_ne_u32_e32 vcc, 0, v89
	v_lshlrev_b32_e32 v128, 16, v56
	v_and_b32_e32 v129, s32, v56
	v_lshlrev_b32_e32 v130, 16, v57
	v_and_b32_e32 v131, s32, v57
	v_lshlrev_b32_e32 v132, 16, v58
	v_and_b32_e32 v133, s32, v58
	v_lshlrev_b32_e32 v134, 16, v59
	v_and_b32_e32 v135, s32, v59
	v_cndmask_b32_e32 v64, 0, v64, vcc
	v_cndmask_b32_e32 v65, 0, v65, vcc
	v_cndmask_b32_e32 v66, 0, v66, vcc
	v_cndmask_b32_e32 v67, 0, v67, vcc
	v_pk_mul_f32 v[128:129], v[128:129], v[136:137]
	v_pk_mul_f32 v[130:131], v[130:131], v[138:139]
	v_pk_mul_f32 v[132:133], v[132:133], v[140:141]
	v_pk_mul_f32 v[134:135], v[134:135], v[142:143]
	v_pk_mul_f32 v[160:161], v[8:9], v[128:129]
	v_pk_mul_f32 v[162:163], v[10:11], v[130:131]
	v_pk_mul_f32 v[164:165], v[12:13], v[132:133]
	v_pk_mul_f32 v[166:167], v[14:15], v[134:135]
	v_lshlrev_b32_e32 v128, 16, v64
	v_and_b32_e32 v129, s32, v64
	v_lshlrev_b32_e32 v130, 16, v65
	v_and_b32_e32 v131, s32, v65
	v_lshlrev_b32_e32 v132, 16, v66
	v_and_b32_e32 v133, s32, v66
	v_lshlrev_b32_e32 v134, 16, v67
	v_and_b32_e32 v135, s32, v67
	v_lshlrev_b32_e32 v136, 16, v68
	v_and_b32_e32 v137, s32, v68
	v_lshlrev_b32_e32 v138, 16, v69
	v_and_b32_e32 v139, s32, v69
	v_lshlrev_b32_e32 v140, 16, v70
	v_and_b32_e32 v141, s32, v70
	v_lshlrev_b32_e32 v142, 16, v71
	v_and_b32_e32 v143, s32, v71
	v_pk_mul_f32 v[128:129], v[128:129], v[136:137]
	v_pk_mul_f32 v[130:131], v[130:131], v[138:139]
	v_pk_mul_f32 v[132:133], v[132:133], v[140:141]
	v_pk_mul_f32 v[134:135], v[134:135], v[142:143]
	v_pk_fma_f32 v[160:161], v[16:17], v[128:129], v[160:161]
	v_pk_fma_f32 v[162:163], v[18:19], v[130:131], v[162:163]
	v_pk_fma_f32 v[164:165], v[20:21], v[132:133], v[164:165]
	v_pk_fma_f32 v[166:167], v[22:23], v[134:135], v[166:167]
	v_lshlrev_b32_e32 v128, 16, v72
	v_and_b32_e32 v129, s32, v72
	v_lshlrev_b32_e32 v130, 16, v73
	v_and_b32_e32 v131, s32, v73
	v_lshlrev_b32_e32 v132, 16, v74
	v_and_b32_e32 v133, s32, v74
	v_lshlrev_b32_e32 v134, 16, v75
	v_and_b32_e32 v135, s32, v75
	v_lshlrev_b32_e32 v136, 16, v76
	v_and_b32_e32 v137, s32, v76
	v_lshlrev_b32_e32 v138, 16, v77
	v_and_b32_e32 v139, s32, v77
	v_lshlrev_b32_e32 v140, 16, v78
	v_and_b32_e32 v141, s32, v78
	v_lshlrev_b32_e32 v142, 16, v79
	v_and_b32_e32 v143, s32, v79
	v_pk_mul_f32 v[128:129], v[128:129], v[136:137]
	v_pk_mul_f32 v[130:131], v[130:131], v[138:139]
	v_pk_mul_f32 v[132:133], v[132:133], v[140:141]
	v_pk_mul_f32 v[134:135], v[134:135], v[142:143]
	v_pk_fma_f32 v[160:161], v[24:25], v[128:129], v[160:161]
	v_pk_fma_f32 v[162:163], v[26:27], v[130:131], v[162:163]
	v_pk_fma_f32 v[164:165], v[28:29], v[132:133], v[164:165]
	v_pk_fma_f32 v[166:167], v[30:31], v[134:135], v[166:167]
	v_lshlrev_b32_e32 v176, 16, v84
	v_and_b32_e32 v177, s32, v84
	v_lshlrev_b32_e32 v178, 16, v85
	v_and_b32_e32 v179, s32, v85
	v_lshlrev_b32_e32 v180, 16, v86
	v_and_b32_e32 v181, s32, v86
	v_lshlrev_b32_e32 v182, 16, v87
	v_and_b32_e32 v183, s32, v87
	v_mul_f32_e32 v184, s35, v176
	v_mul_f32_e32 v185, s35, v177
	v_mul_f32_e32 v186, s35, v178
	v_mul_f32_e32 v187, s35, v179
	v_mul_f32_e32 v188, s35, v180
	v_mul_f32_e32 v189, s35, v181
	v_mul_f32_e32 v190, s35, v182
	v_mul_f32_e32 v191, s35, v183
	v_exp_f32_e32 v184, v184
	v_exp_f32_e32 v185, v185
	v_exp_f32_e32 v186, v186
	v_exp_f32_e32 v187, v187
	v_exp_f32_e32 v188, v188
	v_exp_f32_e32 v189, v189
	v_exp_f32_e32 v190, v190
	v_exp_f32_e32 v191, v191
	v_lshlrev_b32_e32 v168, 16, v80
	v_and_b32_e32 v169, s32, v80
	v_lshlrev_b32_e32 v170, 16, v81
	v_and_b32_e32 v171, s32, v81
	v_lshlrev_b32_e32 v172, 16, v82
	v_and_b32_e32 v173, s32, v82
	v_lshlrev_b32_e32 v174, 16, v83
	v_and_b32_e32 v175, s32, v83
	v_add_f32_e32 v184, 1.0, v184
	v_add_f32_e32 v185, 1.0, v185
	v_add_f32_e32 v186, 1.0, v186
	v_add_f32_e32 v187, 1.0, v187
	v_add_f32_e32 v188, 1.0, v188
	v_add_f32_e32 v189, 1.0, v189
	v_add_f32_e32 v190, 1.0, v190
	v_add_f32_e32 v191, 1.0, v191
	v_rcp_f32_e32 v184, v184
	v_rcp_f32_e32 v185, v185
	v_rcp_f32_e32 v186, v186
	v_rcp_f32_e32 v187, v187
	v_rcp_f32_e32 v188, v188
	v_rcp_f32_e32 v189, v189
	v_rcp_f32_e32 v190, v190
	v_rcp_f32_e32 v191, v191
	v_pk_mul_f32 v[168:169], v[168:169], v[160:161]
	v_pk_mul_f32 v[170:171], v[170:171], v[162:163]
	v_pk_mul_f32 v[172:173], v[172:173], v[164:165]
	v_pk_mul_f32 v[174:175], v[174:175], v[166:167]
	v_pk_mul_f32 v[176:177], v[176:177], v[184:185]
	v_pk_mul_f32 v[178:179], v[178:179], v[186:187]
	v_pk_mul_f32 v[180:181], v[180:181], v[188:189]
	v_pk_mul_f32 v[182:183], v[182:183], v[190:191]
	v_pk_mul_f32 v[168:169], v[168:169], v[176:177]
	v_pk_mul_f32 v[170:171], v[170:171], v[178:179]
	v_pk_mul_f32 v[172:173], v[172:173], v[180:181]
	v_pk_mul_f32 v[174:175], v[174:175], v[182:183]
	v_cvt_pk_bf16_f32 v40, v168, v169
	v_cvt_pk_bf16_f32 v41, v170, v171
	v_cvt_pk_bf16_f32 v42, v172, v173
	v_cvt_pk_bf16_f32 v43, v174, v175
	global_store_dwordx4 v88, v[40:43], s[52:53]
	s_cmp_eq_u32 s18, 0
	s_cbranch_scc1 .Lconva_done
	s_add_i32 s18, s18, -1
	s_branch .Lconva_loop
.Lconva_done:
	s_waitcnt vmcnt(0)
.LBB0_497:
	s_or_b64 exec, exec, s[6:7]
	v_mov_b64_e32 v[2:3], s[14:15]
	flat_load_dwordx2 v[2:3], v[2:3] offset:144
	v_cmp_gt_i32_e32 vcc, s96, v4
	s_and_saveexec_b64 s[4:5], vcc
	s_mov_b64 s[14:15], 0x60000
	s_cbranch_execz .LBB0_505
	v_and_b32_e32 v5, 0x3ff, v4
	v_lshlrev_b32_e32 v152, 1, v5
	v_max_i32_e32 v5, 0xfffea000, v4
	v_add_u32_e32 v5, 0x8000, v5
	v_sub_u32_e32 v8, v5, v150
	s_lshl_b32 s6, s30, 9
	v_cmp_ne_u32_e32 vcc, s6, v8
	s_waitcnt vmcnt(0) lgkmcnt(0)
	v_lshl_add_u64 v[6:7], v[0:1], 0, v[152:153]
	s_mov_b64 s[8:9], -1
	v_cndmask_b32_e64 v8, 1, 2, vcc
	v_subb_co_u32_e32 v5, vcc, v5, v150, vcc
	v_subrev_u32_e32 v5, s6, v5
	v_mul_hi_u32 v5, v5, s56
	v_add_u32_sdwa v12, v8, v5 dst_sel:DWORD dst_unused:UNUSED_PAD src0_sel:DWORD src1_sel:WORD_1
	v_cmp_lt_u32_e32 vcc, 1, v12
	v_mov_b32_e32 v8, v4
	s_and_saveexec_b64 s[6:7], vcc
	s_cbranch_execz .LBB0_502
	s_lshl_b64 s[8:9], s[92:93], 15
	v_lshl_add_u64 v[8:9], v[2:3], 0, s[8:9]
	s_mov_b64 s[8:9], 0x4100000
	v_and_b32_e32 v13, 0x1fffe, v12
	v_add_u32_e32 v5, 0x18000, v4
	v_lshl_add_u64 v[8:9], v[8:9], 0, s[8:9]
	s_mov_b64 s[8:9], 0
	v_mov_b32_e32 v14, v13
	v_mov_b64_e32 v[10:11], v[4:5]

; __device__ __forceinline__ void scan_bh(LAS unsigned char* lds, const ScanP& P, int b, int h, int half, int tid, int lane, int wave) {
;     ...
;     if (!cw) {
;         const int lt = tid - 256, wrow = lt >> 4, wc16 = lt & 15, arow = lt >> 3, ac16 = lt & 7;
;         const int wperm = (wc16 >> 2) * 32 + ((((wc16 & 3) * 8) & 15) >> 2) * 8 + (((wc16 & 3) * 8) >> 4) * 4, aperm = (ac16 >> 2) * 32 + ((((ac16 & 3) * 8) & 15) >> 2) * 8 + (((ac16 & 3) * 8) >> 4) * 4;
;         const unsigned oW = (unsigned)TR_W + (unsigned)(wrow * 128 + wc16 * 8) * 2u, oQ = oW + (unsigned)(TR_Q - TR_W), oA = (unsigned)TR_A + (unsigned)(arow * 64 + ac16 * 8) * 2u, oK = oA + (unsigned)(TR_K - TR_A);
;         const unsigned lW = (unsigned)(wrow * PS + wperm) * 2u, lA = (unsigned)(arow * TS + aperm) * 2u;
;         u32x4 sa[14], sb[14];
;     ...
;         L_LOAD(0, sa); L_STORE(lds, sa); L_LOAD(1, sa);
;         __syncthreads();
.LBB0_514:
	s_and_b64 vcc, exec, s[4:5]
	s_mov_b32 s54, s13
	s_mov_b64 s[20:21], 0x28e00000
	s_cbranch_vccz .LBB0_534
	s_mov_b32 s4, -1
	s_mov_b32 s10, s2
	s_waitcnt vmcnt(0)
	v_mbcnt_lo_u32_b32 v0, s4, 0
	v_mbcnt_hi_u32_b32 v0, s4, v0
	v_or_b32_e32 v145, s3, v0
	s_mov_b64 s[4:5], s[0:1]
	s_and_b32 s8, s10, 7
	v_mov_b64_e32 v[0:1], s[4:5]
	s_waitcnt lgkmcnt(0)
	flat_load_dwordx4 v[0:3], v[0:1] offset:144
	v_readfirstlane_b32 s4, v145
	s_ashr_i32 s9, s10, 4
	s_ashr_i32 s11, s4, 6
	s_mov_b64 s[4:5], 0x22400000
	v_and_b32_e32 v144, 15, v145
	s_cmp_gt_i32 s11, 3
	s_waitcnt vmcnt(0) lgkmcnt(0)
	v_lshl_add_u64 v[116:117], v[2:3], 0, s[4:5]
	s_mov_b64 s[4:5], -1
	s_cbranch_scc0 .LBB0_525
	v_add_u32_e32 v4, 0xffffff00, v145
	v_ashrrev_i32_e32 v147, 4, v4
	v_ashrrev_i32_e32 v150, 3, v4
	v_lshlrev_b32_e32 v146, 3, v144
	v_lshlrev_b32_e32 v148, 1, v145
	v_and_b32_e32 v151, 0x60, v146
	v_lshlrev_b32_e32 v146, 4, v145
	v_and_b32_e32 v148, 4, v148
	v_lshlrev_b32_e32 v149, 3, v145
	v_and_or_b32 v146, v146, 16, v148
	v_and_b32_e32 v156, 32, v149
	v_mad_u64_u32 v[148:149], s[4:5], v147, s50, v[146:147]
	s_movk_i32 s4, 0x48
	s_nop 0
	v_mad_u64_u32 v[146:147], s[4:5], v150, s4, v[146:147]
	v_add_lshl_u32 v160, v148, v151, 1
	v_add_u32_e32 v147, 0, v160
	v_add_lshl_u32 v146, v146, v156, 1
	v_add_u32_e32 v16, 0x0, v160
	v_add_u32_e32 v17, 0x1100, v160
	v_add_u32_e32 v18, 0x2200, v160
	v_add_u32_e32 v19, 0x3300, v160
	v_add_u32_e32 v20, 0x4400, v160
	v_add_u32_e32 v21, 0x5500, v160
	v_add_u32_e32 v22, 0x6600, v160
	v_add_u32_e32 v23, 0x7700, v160
	v_add_u32_e32 v24, 0x8800, v146
	v_add_u32_e32 v25, 0x9a00, v146
	v_add_u32_e32 v26, 0xac00, v146
	v_add_u32_e32 v27, 0xbe00, v146
	v_add_u32_e32 v28, 0xd000, v146
	v_add_u32_e32 v29, 0xe200, v146
	v_lshlrev_b32_e32 v5, 4, v4
	v_add_u32_e32 v6, 0x1000, v5
	v_add_u32_e32 v7, 0x3000, v5
	v_add_u32_e32 v8, 0x5000, v5
	v_add_u32_e32 v9, 0x7000, v5
	v_add_u32_e32 v10, 0x9000, v5
	v_add_u32_e32 v11, 0xb000, v5
	v_add_u32_e32 v12, 0xd000, v5
	v_readfirstlane_b32 s6, v116
	v_readfirstlane_b32 s7, v117
	s_lshl_b32 s18, s9, 8
	s_or_b32 s18, s18, s8
	s_mul_hi_u32 s15, s18, 0x1a000
	s_mul_i32 s14, s18, 0x1a000
	s_add_u32 s14, s14, s6
	s_addc_u32 s15, s15, s7
	s_mov_b32 s16, 0
	s_mov_b32 s17, 0
	global_load_dwordx4 v[32:35], v6, s[14:15] offset:-4096
	global_load_dwordx4 v[36:39], v6, s[14:15]
	global_load_dwordx4 v[40:43], v7, s[14:15] offset:-4096
	global_load_dwordx4 v[44:47], v7, s[14:15]
	global_load_dwordx4 v[48:51], v8, s[14:15] offset:-4096
	global_load_dwordx4 v[52:55], v8, s[14:15]
	global_load_dwordx4 v[56:59], v9, s[14:15] offset:-4096
	global_load_dwordx4 v[60:63], v9, s[14:15]
	global_load_dwordx4 v[64:67], v10, s[14:15] offset:-4096
	global_load_dwordx4 v[68:71], v10, s[14:15]
	global_load_dwordx4 v[72:75], v11, s[14:15] offset:-4096
	global_load_dwordx4 v[76:79], v11, s[14:15]
	global_load_dwordx4 v[80:83], v12, s[14:15] offset:-4096
	global_load_dwordx4 v[84:87], v12, s[14:15]
	s_add_u32 s14, s14, 0xd0000
	s_addc_u32 s15, s15, 0
	global_load_dwordx4 v[88:91], v6, s[14:15] offset:-4096
	global_load_dwordx4 v[92:95], v6, s[14:15]
	global_load_dwordx4 v[96:99], v7, s[14:15] offset:-4096
	global_load_dwordx4 v[100:103], v7, s[14:15]
	global_load_dwordx4 v[104:107], v8, s[14:15] offset:-4096
	global_load_dwordx4 v[108:111], v8, s[14:15]
	global_load_dwordx4 v[112:115], v9, s[14:15] offset:-4096
	global_load_dwordx4 v[116:119], v9, s[14:15]
	global_load_dwordx4 v[120:123], v10, s[14:15] offset:-4096
	global_load_dwordx4 v[124:127], v10, s[14:15]
	global_load_dwordx4 v[128:131], v11, s[14:15] offset:-4096
	global_load_dwordx4 v[132:135], v11, s[14:15]
	global_load_dwordx4 v[136:139], v12, s[14:15] offset:-4096
	global_load_dwordx4 v[140:143], v12, s[14:15]
	s_add_u32 s14, s14, 0xd0000
	s_addc_u32 s15, s15, 0
	global_load_dwordx4 v[156:159], v6, s[14:15] offset:-4096
	global_load_dwordx4 v[160:163], v6, s[14:15]
	global_load_dwordx4 v[164:167], v7, s[14:15] offset:-4096
	global_load_dwordx4 v[168:171], v7, s[14:15]
	global_load_dwordx4 v[172:175], v8, s[14:15] offset:-4096
	global_load_dwordx4 v[176:179], v8, s[14:15]
	global_load_dwordx4 v[180:183], v9, s[14:15] offset:-4096
	global_load_dwordx4 v[184:187], v9, s[14:15]
	global_load_dwordx4 v[188:191], v10, s[14:15] offset:-4096
	global_load_dwordx4 v[200:203], v10, s[14:15]
	global_load_dwordx4 v[204:207], v11, s[14:15] offset:-4096
	global_load_dwordx4 v[208:211], v11, s[14:15]
	global_load_dwordx4 v[212:215], v12, s[14:15] offset:-4096
	global_load_dwordx4 v[216:219], v12, s[14:15]
	s_add_u32 s14, s14, 0xd0000
	s_addc_u32 s15, s15, 0
	v_add_u32_e32 v13, s17, v16
	s_waitcnt vmcnt(41)
	ds_write2_b64 v13, v[32:33], v[34:35] offset1:2
	v_add_u32_e32 v13, s17, v17
	s_waitcnt vmcnt(40)
	ds_write2_b64 v13, v[36:37], v[38:39] offset1:2
	v_add_u32_e32 v13, s17, v18
	s_waitcnt vmcnt(39)
	ds_write2_b64 v13, v[40:41], v[42:43] offset1:2
	v_add_u32_e32 v13, s17, v19
	s_waitcnt vmcnt(38)
	ds_write2_b64 v13, v[44:45], v[46:47] offset1:2
	v_add_u32_e32 v13, s17, v20
	s_waitcnt vmcnt(37)
	ds_write2_b64 v13, v[48:49], v[50:51] offset1:2
	v_add_u32_e32 v13, s17, v21
	s_waitcnt vmcnt(36)
	ds_write2_b64 v13, v[52:53], v[54:55] offset1:2
	v_add_u32_e32 v13, s17, v22
	s_waitcnt vmcnt(35)
	ds_write2_b64 v13, v[56:57], v[58:59] offset1:2
	v_add_u32_e32 v13, s17, v23
	s_waitcnt vmcnt(34)
	ds_write2_b64 v13, v[60:61], v[62:63] offset1:2
	v_add_u32_e32 v13, s17, v24
	s_waitcnt vmcnt(33)
	ds_write2_b64 v13, v[64:65], v[66:67] offset1:2
	v_add_u32_e32 v13, s17, v25
	s_waitcnt vmcnt(32)
	ds_write2_b64 v13, v[68:69], v[70:71] offset1:2
	v_add_u32_e32 v13, s17, v26
	s_waitcnt vmcnt(31)
	ds_write2_b64 v13, v[72:73], v[74:75] offset1:2
	v_add_u32_e32 v13, s17, v27
	s_waitcnt vmcnt(30)
	ds_write2_b64 v13, v[76:77], v[78:79] offset1:2
	v_add_u32_e32 v13, s17, v28
	s_waitcnt vmcnt(29)
	ds_write2_b64 v13, v[80:81], v[82:83] offset1:2
	v_add_u32_e32 v13, s17, v29
	s_waitcnt vmcnt(28)
	ds_write2_b64 v13, v[84:85], v[86:87] offset1:2
	s_waitcnt lgkmcnt(0)
	s_barrier
	s_mov_b32 s17, 0xf400
; #define LBAR() do { asm volatile("s_waitcnt lgkmcnt(0)" ::: "memory"); __builtin_amdgcn_s_barrier(); asm volatile("" ::: "memory"); } while (0)
; __device__ __forceinline__ void scan_bh(LAS unsigned char* lds, const ScanP& P, int b, int h, int half, int tid, int lane, int wave) {
;     ...
; #pragma unroll 1
;         for (int n = 0; n < 32; n += 2) {
;             if (n + 2 < 32) L_LOAD(n + 2, sb);
;             L_STORE(lds + ((n + 1) & 1) * SB_SZ, sa);
;             LBAR();
;             if (n + 3 < 32) L_LOAD(n + 3, sa);
;             if (n + 2 < 32) L_STORE(lds + ((n + 2) & 1) * SB_SZ, sb);
;             LBAR();
;         }
.Lscan_ld:
	global_load_dwordx4 v[32:35], v6, s[14:15] offset:-4096
	global_load_dwordx4 v[36:39], v6, s[14:15]
	global_load_dwordx4 v[40:43], v7, s[14:15] offset:-4096
	global_load_dwordx4 v[44:47], v7, s[14:15]
	global_load_dwordx4 v[48:51], v8, s[14:15] offset:-4096
	global_load_dwordx4 v[52:55], v8, s[14:15]
	global_load_dwordx4 v[56:59], v9, s[14:15] offset:-4096
	global_load_dwordx4 v[60:63], v9, s[14:15]
	global_load_dwordx4 v[64:67], v10, s[14:15] offset:-4096
	global_load_dwordx4 v[68:71], v10, s[14:15]
	global_load_dwordx4 v[72:75], v11, s[14:15] offset:-4096
	global_load_dwordx4 v[76:79], v11, s[14:15]
	global_load_dwordx4 v[80:83], v12, s[14:15] offset:-4096
	global_load_dwordx4 v[84:87], v12, s[14:15]
	s_cmp_lt_u32 s16, 28
	s_cselect_b32 s19, 0xd0000, 0
	s_add_u32 s14, s14, s19
	s_addc_u32 s15, s15, 0
	v_add_u32_e32 v13, s17, v16
	s_waitcnt vmcnt(41)
	ds_write2_b64 v13, v[88:89], v[90:91] offset1:2
	v_add_u32_e32 v13, s17, v17
	s_waitcnt vmcnt(40)
	ds_write2_b64 v13, v[92:93], v[94:95] offset1:2
	v_add_u32_e32 v13, s17, v18
	s_waitcnt vmcnt(39)
	ds_write2_b64 v13, v[96:97], v[98:99] offset1:2
	v_add_u32_e32 v13, s17, v19
	s_waitcnt vmcnt(38)
	ds_write2_b64 v13, v[100:101], v[102:103] offset1:2
	v_add_u32_e32 v13, s17, v20
	s_waitcnt vmcnt(37)
	ds_write2_b64 v13, v[104:105], v[106:107] offset1:2
	v_add_u32_e32 v13, s17, v21
	s_waitcnt vmcnt(36)
	ds_write2_b64 v13, v[108:109], v[110:111] offset1:2
	v_add_u32_e32 v13, s17, v22
	s_waitcnt vmcnt(35)
	ds_write2_b64 v13, v[112:113], v[114:115] offset1:2
	v_add_u32_e32 v13, s17, v23
	s_waitcnt vmcnt(34)
	ds_write2_b64 v13, v[116:117], v[118:119] offset1:2
	v_add_u32_e32 v13, s17, v24
	s_waitcnt vmcnt(33)
	ds_write2_b64 v13, v[120:121], v[122:123] offset1:2
	v_add_u32_e32 v13, s17, v25
	s_waitcnt vmcnt(32)
	ds_write2_b64 v13, v[124:125], v[126:127] offset1:2
	v_add_u32_e32 v13, s17, v26
	s_waitcnt vmcnt(31)
	ds_write2_b64 v13, v[128:129], v[130:131] offset1:2
	v_add_u32_e32 v13, s17, v27
	s_waitcnt vmcnt(30)
	ds_write2_b64 v13, v[132:133], v[134:135] offset1:2
	v_add_u32_e32 v13, s17, v28
	s_waitcnt vmcnt(29)
	ds_write2_b64 v13, v[136:137], v[138:139] offset1:2
	v_add_u32_e32 v13, s17, v29
	s_waitcnt vmcnt(28)
	ds_write2_b64 v13, v[140:141], v[142:143] offset1:2
	s_waitcnt lgkmcnt(0)
	s_barrier
	s_xor_b32 s17, s17, 0xf400
	s_add_i32 s16, s16, 1
	s_cmp_eq_u32 s16, 31
	s_cbranch_scc1 .Lscan_ld_last
	global_load_dwordx4 v[88:91], v6, s[14:15] offset:-4096
	global_load_dwordx4 v[92:95], v6, s[14:15]
	global_load_dwordx4 v[96:99], v7, s[14:15] offset:-4096
	global_load_dwordx4 v[100:103], v7, s[14:15]
	global_load_dwordx4 v[104:107], v8, s[14:15] offset:-4096
	global_load_dwordx4 v[108:111], v8, s[14:15]
	global_load_dwordx4 v[112:115], v9, s[14:15] offset:-4096
	global_load_dwordx4 v[116:119], v9, s[14:15]
	global_load_dwordx4 v[120:123], v10, s[14:15] offset:-4096
	global_load_dwordx4 v[124:127], v10, s[14:15]
	global_load_dwordx4 v[128:131], v11, s[14:15] offset:-4096
	global_load_dwordx4 v[132:135], v11, s[14:15]
	global_load_dwordx4 v[136:139], v12, s[14:15] offset:-4096
	global_load_dwordx4 v[140:143], v12, s[14:15]
	s_cmp_lt_u32 s16, 28
	s_cselect_b32 s19, 0xd0000, 0
	s_add_u32 s14, s14, s19
	s_addc_u32 s15, s15, 0
	v_add_u32_e32 v13, s17, v16
	s_waitcnt vmcnt(41)
	ds_write2_b64 v13, v[156:157], v[158:159] offset1:2
	v_add_u32_e32 v13, s17, v17
	s_waitcnt vmcnt(40)
	ds_write2_b64 v13, v[160:161], v[162:163] offset1:2
	v_add_u32_e32 v13, s17, v18
	s_waitcnt vmcnt(39)
	ds_write2_b64 v13, v[164:165], v[166:167] offset1:2
	v_add_u32_e32 v13, s17, v19
	s_waitcnt vmcnt(38)
	ds_write2_b64 v13, v[168:169], v[170:171] offset1:2
	v_add_u32_e32 v13, s17, v20
	s_waitcnt vmcnt(37)
	ds_write2_b64 v13, v[172:173], v[174:175] offset1:2
	v_add_u32_e32 v13, s17, v21
	s_waitcnt vmcnt(36)
	ds_write2_b64 v13, v[176:177], v[178:179] offset1:2
	v_add_u32_e32 v13, s17, v22
	s_waitcnt vmcnt(35)
	ds_write2_b64 v13, v[180:181], v[182:183] offset1:2
	v_add_u32_e32 v13, s17, v23
	s_waitcnt vmcnt(34)
	ds_write2_b64 v13, v[184:185], v[186:187] offset1:2
	v_add_u32_e32 v13, s17, v24
	s_waitcnt vmcnt(33)
	ds_write2_b64 v13, v[188:189], v[190:191] offset1:2
	v_add_u32_e32 v13, s17, v25
	s_waitcnt vmcnt(32)
	ds_write2_b64 v13, v[200:201], v[202:203] offset1:2
	v_add_u32_e32 v13, s17, v26
	s_waitcnt vmcnt(31)
	ds_write2_b64 v13, v[204:205], v[206:207] offset1:2
	v_add_u32_e32 v13, s17, v27
	s_waitcnt vmcnt(30)
	ds_write2_b64 v13, v[208:209], v[210:211] offset1:2
	v_add_u32_e32 v13, s17, v28
	s_waitcnt vmcnt(29)
	ds_write2_b64 v13, v[212:213], v[214:215] offset1:2
	v_add_u32_e32 v13, s17, v29
	s_waitcnt vmcnt(28)
	ds_write2_b64 v13, v[216:217], v[218:219] offset1:2
	s_waitcnt lgkmcnt(0)
	s_barrier
; #define LBAR() do { asm volatile("s_waitcnt lgkmcnt(0)" ::: "memory"); __builtin_amdgcn_s_barrier(); asm volatile("" ::: "memory"); } while (0)
; __device__ __forceinline__ void scan_bh(LAS unsigned char* lds, const ScanP& P, int b, int h, int half, int tid, int lane, int wave) {
;     ...
; #pragma unroll 1
;         for (int n = 0; n < 32; n += 2) {
;             if (n + 2 < 32) L_LOAD(n + 2, sb);
;             L_STORE(lds + ((n + 1) & 1) * SB_SZ, sa);
;             LBAR();
;             if (n + 3 < 32) L_LOAD(n + 3, sa);
;             if (n + 2 < 32) L_STORE(lds + ((n + 2) & 1) * SB_SZ, sb);
;             LBAR();
;         }
	s_xor_b32 s17, s17, 0xf400
	s_add_i32 s16, s16, 1
	s_cmp_eq_u32 s16, 31
	s_cbranch_scc1 .Lscan_ld_last
	global_load_dwordx4 v[156:159], v6, s[14:15] offset:-4096
	global_load_dwordx4 v[160:163], v6, s[14:15]
	global_load_dwordx4 v[164:167], v7, s[14:15] offset:-4096
	global_load_dwordx4 v[168:171], v7, s[14:15]
	global_load_dwordx4 v[172:175], v8, s[14:15] offset:-4096
	global_load_dwordx4 v[176:179], v8, s[14:15]
	global_load_dwordx4 v[180:183], v9, s[14:15] offset:-4096
	global_load_dwordx4 v[184:187], v9, s[14:15]
	global_load_dwordx4 v[188:191], v10, s[14:15] offset:-4096
	global_load_dwordx4 v[200:203], v10, s[14:15]
	global_load_dwordx4 v[204:207], v11, s[14:15] offset:-4096
	global_load_dwordx4 v[208:211], v11, s[14:15]
	global_load_dwordx4 v[212:215], v12, s[14:15] offset:-4096
	global_load_dwordx4 v[216:219], v12, s[14:15]
	s_cmp_lt_u32 s16, 28
	s_cselect_b32 s19, 0xd0000, 0
	s_add_u32 s14, s14, s19
	s_addc_u32 s15, s15, 0
	v_add_u32_e32 v13, s17, v16
	s_waitcnt vmcnt(41)
	ds_write2_b64 v13, v[32:33], v[34:35] offset1:2
	v_add_u32_e32 v13, s17, v17
	s_waitcnt vmcnt(40)
	ds_write2_b64 v13, v[36:37], v[38:39] offset1:2
	v_add_u32_e32 v13, s17, v18
	s_waitcnt vmcnt(39)
	ds_write2_b64 v13, v[40:41], v[42:43] offset1:2
	v_add_u32_e32 v13, s17, v19
	s_waitcnt vmcnt(38)
	ds_write2_b64 v13, v[44:45], v[46:47] offset1:2
	v_add_u32_e32 v13, s17, v20
	s_waitcnt vmcnt(37)
	ds_write2_b64 v13, v[48:49], v[50:51] offset1:2
	v_add_u32_e32 v13, s17, v21
	s_waitcnt vmcnt(36)
	ds_write2_b64 v13, v[52:53], v[54:55] offset1:2
	v_add_u32_e32 v13, s17, v22
	s_waitcnt vmcnt(35)
	ds_write2_b64 v13, v[56:57], v[58:59] offset1:2
	v_add_u32_e32 v13, s17, v23
	s_waitcnt vmcnt(34)
	ds_write2_b64 v13, v[60:61], v[62:63] offset1:2
	v_add_u32_e32 v13, s17, v24
	s_waitcnt vmcnt(33)
	ds_write2_b64 v13, v[64:65], v[66:67] offset1:2
	v_add_u32_e32 v13, s17, v25
	s_waitcnt vmcnt(32)
	ds_write2_b64 v13, v[68:69], v[70:71] offset1:2
	v_add_u32_e32 v13, s17, v26
	s_waitcnt vmcnt(31)
	ds_write2_b64 v13, v[72:73], v[74:75] offset1:2
	v_add_u32_e32 v13, s17, v27
	s_waitcnt vmcnt(30)
	ds_write2_b64 v13, v[76:77], v[78:79] offset1:2
	v_add_u32_e32 v13, s17, v28
	s_waitcnt vmcnt(29)
	ds_write2_b64 v13, v[80:81], v[82:83] offset1:2
	v_add_u32_e32 v13, s17, v29
	s_waitcnt vmcnt(28)
	ds_write2_b64 v13, v[84:85], v[86:87] offset1:2
	s_waitcnt lgkmcnt(0)
	s_barrier
	s_xor_b32 s17, s17, 0xf400
	s_add_i32 s16, s16, 1
	s_cmp_eq_u32 s16, 31
	s_cbranch_scc1 .Lscan_ld_last
	s_branch .Lscan_ld
.Lscan_ld_last:
	s_waitcnt vmcnt(0)
	s_barrier
.LBB0_524:
	s_mov_b64 s[4:5], 0

; #define LAS __attribute__((address_space(3)))
; __device__ __forceinline__ bf16x8 packB(const f32x4& a, const f32x4& b) { u32x4 v = {pk2(a[0], a[1]), pk2(a[2], a[3]), pk2(b[0], b[1]), pk2(b[2], b[3])}; return __builtin_bit_cast(bf16x8, v); }
; #define U_LOAD(nn) do { const unsigned char* tr_ = P.tr + (size_t)((b << 8) | ((nn) << 3) | h) * TR_SZ; \
;             _Pragma("unroll") for (int mt_ = 0; mt_ < 4; ++mt_) ubn[mt_] = *(const f32x4*)(tr_ + (oU + (unsigned)mt_ * 1024u)); } while (0)
; #define SBAR() __builtin_amdgcn_sched_barrier(0)
; #define LD4(d, base, mt, stride) do { _Pragma("unroll") for (int ks = 0; ks < 4; ++ks) d[ks] = frag1((base) + ((mt) * 16 + r) * (stride) + ks * 32 + q8 * 8); } while (0)
; __device__ __forceinline__ void scan_bh(LAS unsigned char* lds, const ScanP& P, int b, int h, int half, int tid, int lane, int wave) {
;     ...
;         f32x4 S[8];
; #pragma unroll
;         for (int i = 0; i < 8; ++i) S[i] = (f32x4){0.f, 0.f, 0.f, 0.f};
;         const float glv = (lane < 32) ? P.gl[(b << 8) | (lane << 3) | h] : 0.f;
;         f32x4 ubn[4];
;         const unsigned oU = (unsigned)TR_U + (unsigned)(ct * 256 + lane) * 16u;
;     ...
;         U_LOAD(0);
;         __syncthreads();
; #pragma unroll 1
;         for (int n = 0; n < 32; ++n) {
;             LAS unsigned char* buf = lds + (n & 1) * SB_SZ;
;             const LAS bf16_t* Wl = (const LAS bf16_t*)(buf + SB_W); const LAS bf16_t* Ql = (const LAS bf16_t*)(buf + SB_Q);
;             const LAS bf16_t* Al = (const LAS bf16_t*)(buf + SB_A); const LAS bf16_t* Kl = (const LAS bf16_t*)(buf + SB_K);
;             f32x4 u[4], o[4];
; #pragma unroll
;             for (int mt = 0; mt < 4; ++mt) { u[mt] = ubn[mt]; o[mt] = (f32x4){0.f, 0.f, 0.f, 0.f}; }
;             if (n + 1 < 32) U_LOAD(n + 1);
;         bf16x8 Sb[4];
; #pragma unroll
;         for (int ks = 0; ks < 4; ++ks) Sb[ks] = packB(S[2 * ks], S[2 * ks + 1]);
;     ...
;         {
;             bf16x8 fA[4], fB[4];
;             LD4(fA, Wl, 0, PS); SBAR(); LD4(fB, Ql, 0, PS); SBAR();
;             MM4(u[0], fA); SBAR(); LD4(fA, Wl, 1, PS); SBAR(); MM4(o[0], fB); SBAR(); LD4(fB, Ql, 1, PS); SBAR();
;             MM4(u[1], fA); SBAR(); LD4(fA, Wl, 2, PS); SBAR(); MM4(o[1], fB); SBAR(); LD4(fB, Ql, 2, PS); SBAR();
;             MM4(u[2], fA); SBAR(); LD4(fA, Wl, 3, PS); SBAR(); MM4(o[2], fB); SBAR(); LD4(fB, Ql, 3, PS); SBAR();
.LBB0_528:
	s_or_b64 exec, exec, s[4:5]
	s_lshr_b32 s4, s10, 1
	s_and_b32 s4, s4, 4
	s_and_b32 s5, s11, 3
	s_or_b32 s7, s5, s4
	v_lshlrev_b32_e32 v6, 4, v5
	s_waitcnt vmcnt(11)
	v_lshl_or_b32 v12, s7, 12, v6
	s_or_b32 s6, s6, s8
	v_add_u32_e32 v68, 0x12000, v12
	v_mad_i64_i32 v[6:7], s[4:5], s6, v199, v[116:117]
	v_mov_b32_e32 v69, v153
	v_add_u32_e32 v70, 0x12400, v12
	v_mov_b32_e32 v71, v153
	v_add_u32_e32 v72, 0x12800, v12
	v_mov_b32_e32 v73, v153
	v_add_u32_e32 v74, 0x12c00, v12
	v_mov_b32_e32 v75, v153
	v_lshl_add_u64 v[8:9], v[6:7], 0, v[68:69]
	v_lshl_add_u64 v[10:11], v[6:7], 0, v[72:73]
	v_lshl_add_u64 v[12:13], v[6:7], 0, v[74:75]
	v_lshl_add_u64 v[6:7], v[6:7], 0, v[70:71]
	global_load_dwordx4 v[56:59], v[10:11], off
	global_load_dwordx4 v[52:55], v[12:13], off
	global_load_dwordx4 v[60:63], v[6:7], off
	global_load_dwordx4 v[64:67], v[8:9], off
	s_add_i32 s15, s6, 8
	v_mad_i64_i32 v[44:45], s[16:17], s15, v199, v[116:117]
	v_lshl_add_u64 v[36:37], v[44:45], 0, v[74:75]
	v_lshl_add_u64 v[38:39], v[44:45], 0, v[72:73]
	v_lshl_add_u64 v[46:47], v[44:45], 0, v[70:71]
	v_lshl_add_u64 v[44:45], v[44:45], 0, v[68:69]
	global_load_dwordx4 v[176:179], v[36:37], off
	global_load_dwordx4 v[180:183], v[38:39], off
	global_load_dwordx4 v[184:187], v[46:47], off
	global_load_dwordx4 v[188:191], v[44:45], off
	s_add_i32 s15, s6, 16
	v_mad_i64_i32 v[44:45], s[16:17], s15, v199, v[116:117]
	v_lshl_add_u64 v[36:37], v[44:45], 0, v[74:75]
	v_lshl_add_u64 v[38:39], v[44:45], 0, v[72:73]
	v_lshl_add_u64 v[46:47], v[44:45], 0, v[70:71]
	v_lshl_add_u64 v[44:45], v[44:45], 0, v[68:69]
	global_load_dwordx4 v[200:203], v[36:37], off
	global_load_dwordx4 v[204:207], v[38:39], off
	global_load_dwordx4 v[208:211], v[46:47], off
	global_load_dwordx4 v[212:215], v[44:45], off
	s_add_i32 s15, s6, 24
	v_mad_i64_i32 v[44:45], s[16:17], s15, v199, v[116:117]
	v_lshl_add_u64 v[36:37], v[44:45], 0, v[74:75]
	v_lshl_add_u64 v[38:39], v[44:45], 0, v[72:73]
	v_lshl_add_u64 v[46:47], v[44:45], 0, v[70:71]
	v_lshl_add_u64 v[44:45], v[44:45], 0, v[68:69]
	global_load_dwordx4 v[216:219], v[36:37], off
	global_load_dwordx4 v[220:223], v[38:39], off
	global_load_dwordx4 v[224:227], v[46:47], off
	global_load_dwordx4 v[228:231], v[44:45], off
	s_lshl_b32 s4, s9, 11
	v_lshrrev_b32_e32 v77, 4, v5
	v_or_b32_e32 v6, 48, v5
	v_or_b32_e32 v5, 0x70, v5
	s_ashr_i32 s5, s4, 31
	s_lshl_b32 s7, s7, 4
	v_mul_u32_u24_e32 v81, 0x90, v5
	v_lshlrev_b32_e32 v5, 12, v77
	s_lshl_b64 s[4:5], s[4:5], 12
	s_lshl_b32 s11, s8, 9
	v_or3_b32 v5, v5, v144, s7
	s_or_b32 s4, s4, s11
	v_mul_u32_u24_e32 v7, 0x48, v144
	v_lshlrev_b32_e32 v8, 3, v77
	v_lshlrev_b32_e32 v82, 2, v5
	v_lshlrev_b32_e32 v5, 7, v6
	v_lshl_add_u64 v[2:3], v[2:3], 0, s[4:5]
	v_mul_u32_u24_e32 v78, 0x110, v144
	v_and_b32_e32 v79, 48, v145
	v_mul_u32_u24_e32 v80, 0x110, v6
	s_mov_b32 s10, 0
	v_sub_u32_e32 v83, 0, v5
	v_lshl_add_u64 v[2:3], v[2:3], 0, s[20:21]
	s_mov_b64 s[4:5], 0
	s_mov_b32 s11, 8
	v_lshlrev_b32_e32 v84, 1, v7
	v_lshlrev_b32_e32 v85, 1, v8
	s_mov_b32 s14, 0
	v_mov_b32_e32 v5, v4
	v_mov_b32_e32 v6, v4
	v_mov_b32_e32 v7, v4
	s_waitcnt vmcnt(11)
	v_mov_b32_e32 v28, v4
	v_mov_b32_e32 v29, v4
	v_mov_b32_e32 v30, v4
	v_mov_b32_e32 v31, v4
	s_waitcnt vmcnt(10)
	v_mov_b32_e32 v32, v4
	v_mov_b32_e32 v33, v4
	v_mov_b32_e32 v34, v4
	v_mov_b32_e32 v35, v4
	v_mov_b32_e32 v12, v4
	v_mov_b32_e32 v13, v4
	v_mov_b32_e32 v14, v4
	v_mov_b32_e32 v15, v4
	v_mov_b32_e32 v20, v4
	v_mov_b32_e32 v21, v4
	v_mov_b32_e32 v22, v4
	v_mov_b32_e32 v23, v4
	v_mov_b32_e32 v8, v4
	v_mov_b32_e32 v9, v4
	v_mov_b32_e32 v10, v4
	v_mov_b32_e32 v11, v4
	v_mov_b32_e32 v24, v4
	v_mov_b32_e32 v25, v4
	v_mov_b32_e32 v26, v4
	v_mov_b32_e32 v27, v4
	v_mov_b32_e32 v16, v4
	v_mov_b32_e32 v17, v4
	v_mov_b32_e32 v18, v4
	v_mov_b32_e32 v19, v4
	s_waitcnt lgkmcnt(0)
	s_barrier
	s_waitcnt vmcnt(0)
.Lscan_c0:
	s_add_i32 s15, s11, 24
	s_min_u32 s15, s15, 0xf8
	s_or_b32 s15, s15, s6
	v_mad_i64_i32 v[44:45], s[16:17], s15, v199, v[116:117]
	v_lshl_add_u64 v[36:37], v[44:45], 0, v[74:75]
	v_lshl_add_u64 v[38:39], v[44:45], 0, v[72:73]
	v_lshl_add_u64 v[46:47], v[44:45], 0, v[70:71]
	v_lshl_add_u64 v[44:45], v[44:45], 0, v[68:69]
	global_load_dwordx4 v[160:163], v[36:37], off
	global_load_dwordx4 v[164:167], v[38:39], off
	global_load_dwordx4 v[168:171], v[46:47], off
	global_load_dwordx4 v[172:175], v[44:45], off
	s_waitcnt vmcnt(60)
	s_bitcmp1_b32 s14, 0
	s_cselect_b32 s15, 0xf400, 0
	s_add_i32 s15, s15, 0
	v_add3_u32 v114, s15, v78, v79
	ds_read_b128 v[98:101], v114
	ds_read_b128 v[102:105], v114 offset:64
	ds_read_b128 v[106:109], v114 offset:128
	ds_read_b128 v[110:113], v114 offset:192
	v_cvt_pk_bf16_f32 v86, v4, v5
	v_cvt_pk_bf16_f32 v87, v6, v7
	v_cvt_pk_bf16_f32 v88, v28, v29
	v_cvt_pk_bf16_f32 v89, v30, v31
	v_cvt_pk_bf16_f32 v90, v32, v33
	v_cvt_pk_bf16_f32 v91, v34, v35
	v_cvt_pk_bf16_f32 v92, v12, v13
	v_cvt_pk_bf16_f32 v93, v14, v15
	v_cvt_pk_bf16_f32 v94, v20, v21
	v_cvt_pk_bf16_f32 v95, v22, v23
	v_cvt_pk_bf16_f32 v96, v8, v9
	v_cvt_pk_bf16_f32 v97, v10, v11
	v_cvt_pk_bf16_f32 v118, v24, v25
	v_cvt_pk_bf16_f32 v119, v26, v27
	v_cvt_pk_bf16_f32 v120, v16, v17
	v_cvt_pk_bf16_f32 v121, v18, v19
	ds_read_b128 v[122:125], v114 offset:17408
	ds_read_b128 v[126:129], v114 offset:17472
	ds_read_b128 v[130:133], v114 offset:17536
	ds_read_b128 v[134:137], v114 offset:17600
	s_waitcnt lgkmcnt(7)
	v_mfma_f32_16x16x32_bf16 v[64:67], v[98:101], v[86:89], v[64:67]
	s_waitcnt lgkmcnt(6)
	v_mfma_f32_16x16x32_bf16 v[64:67], v[102:105], v[90:93], v[64:67]
	s_waitcnt lgkmcnt(5)
	v_mfma_f32_16x16x32_bf16 v[64:67], v[106:109], v[94:97], v[64:67]
	s_waitcnt lgkmcnt(4)
; __device__ __forceinline__ bf16x8 packB(const f32x4& a, const f32x4& b) { u32x4 v = {pk2(a[0], a[1]), pk2(a[2], a[3]), pk2(b[0], b[1]), pk2(b[2], b[3])}; return __builtin_bit_cast(bf16x8, v); }
; #define SBAR() __builtin_amdgcn_sched_barrier(0)
; #define LD4(d, base, mt, stride) do { _Pragma("unroll") for (int ks = 0; ks < 4; ++ks) d[ks] = frag1((base) + ((mt) * 16 + r) * (stride) + ks * 32 + q8 * 8); } while (0)
; __device__ __forceinline__ void scan_bh(LAS unsigned char* lds, const ScanP& P, int b, int h, int half, int tid, int lane, int wave) {
;     ...
;         {
;             bf16x8 fA[4], fB[4];
;             LD4(fA, Wl, 0, PS); SBAR(); LD4(fB, Ql, 0, PS); SBAR();
;             MM4(u[0], fA); SBAR(); LD4(fA, Wl, 1, PS); SBAR(); MM4(o[0], fB); SBAR(); LD4(fB, Ql, 1, PS); SBAR();
;             MM4(u[1], fA); SBAR(); LD4(fA, Wl, 2, PS); SBAR(); MM4(o[1], fB); SBAR(); LD4(fB, Ql, 2, PS); SBAR();
;             MM4(u[2], fA); SBAR(); LD4(fA, Wl, 3, PS); SBAR(); MM4(o[2], fB); SBAR(); LD4(fB, Ql, 3, PS); SBAR();
;             MM4(u[3], fA); SBAR(); MM4(o[3], fB); SBAR();
;         }
;         bf16x8 Ub[2];
;         Ub[0] = packB(u[0], u[1]); Ub[1] = packB(u[2], u[3]);
;         const float gl = __shfl(glv, n);
;     ...
;         {
;             bf16x8 aA[6], kA[4], kB[4];
;             aA[0] = frag1(Al + (0 * 16 + r) * TS + q8 * 8); aA[1] = frag1(Al + (1 * 16 + r) * TS + q8 * 8);
;             aA[2] = frag1(Al + (2 * 16 + r) * TS + q8 * 8); aA[3] = frag1(Al + (2 * 16 + r) * TS + 32 + q8 * 8);
;             aA[4] = frag1(Al + (3 * 16 + r) * TS + q8 * 8); aA[5] = frag1(Al + (3 * 16 + r) * TS + 32 + q8 * 8);
;             SBAR(); LDK(kA, 0); SBAR();
;             o[0] = __builtin_amdgcn_mfma_f32_16x16x32_bf16(aA[0], Ub[0], o[0], 0, 0, 0); o[1] = __builtin_amdgcn_mfma_f32_16x16x32_bf16(aA[1], Ub[0], o[1], 0, 0, 0);
;             o[2] = __builtin_amdgcn_mfma_f32_16x16x32_bf16(aA[2], Ub[0], o[2], 0, 0, 0); o[3] = __builtin_amdgcn_mfma_f32_16x16x32_bf16(aA[4], Ub[0], o[3], 0, 0, 0);
;             o[2] = __builtin_amdgcn_mfma_f32_16x16x32_bf16(aA[3], Ub[1], o[2], 0, 0, 0); o[3] = __builtin_amdgcn_mfma_f32_16x16x32_bf16(aA[5], Ub[1], o[3], 0, 0, 0);
;             SBAR(); LDK(kB, 2); SBAR(); MMK(kA, 0); SBAR(); LDK(kA, 4); SBAR(); MMK(kB, 2); SBAR(); LDK(kB, 6); SBAR(); MMK(kA, 4); SBAR(); MMK(kB, 6); SBAR();
	v_mfma_f32_16x16x32_bf16 v[64:67], v[110:113], v[118:121], v[64:67]
	ds_read_b128 v[98:101], v114 offset:4352
	ds_read_b128 v[102:105], v114 offset:4416
	ds_read_b128 v[106:109], v114 offset:4480
	ds_read_b128 v[110:113], v114 offset:4544
	s_waitcnt lgkmcnt(7)
	v_mfma_f32_16x16x32_bf16 v[122:125], v[122:125], v[86:89], 0
	s_waitcnt lgkmcnt(6)
	v_mfma_f32_16x16x32_bf16 v[122:125], v[126:129], v[90:93], v[122:125]
	s_waitcnt lgkmcnt(5)
	v_mfma_f32_16x16x32_bf16 v[122:125], v[130:133], v[94:97], v[122:125]
	s_waitcnt lgkmcnt(4)
	v_mfma_f32_16x16x32_bf16 v[122:125], v[134:137], v[118:121], v[122:125]
	ds_read_b128 v[126:129], v114 offset:21760
	ds_read_b128 v[130:133], v114 offset:21824
	ds_read_b128 v[134:137], v114 offset:21888
	ds_read_b128 v[138:141], v114 offset:21952
	s_waitcnt lgkmcnt(7)
	v_mfma_f32_16x16x32_bf16 v[60:63], v[98:101], v[86:89], v[60:63]
	s_waitcnt lgkmcnt(6)
	v_mfma_f32_16x16x32_bf16 v[60:63], v[102:105], v[90:93], v[60:63]
	s_waitcnt lgkmcnt(5)
	v_mfma_f32_16x16x32_bf16 v[60:63], v[106:109], v[94:97], v[60:63]
	s_waitcnt lgkmcnt(4)
	v_mfma_f32_16x16x32_bf16 v[60:63], v[110:113], v[118:121], v[60:63]
	ds_read_b128 v[98:101], v114 offset:8704
	ds_read_b128 v[102:105], v114 offset:8768
	ds_read_b128 v[106:109], v114 offset:8832
	ds_read_b128 v[110:113], v114 offset:8896
	s_waitcnt lgkmcnt(7)
	v_mfma_f32_16x16x32_bf16 v[126:129], v[126:129], v[86:89], 0
	s_waitcnt lgkmcnt(6)
	v_mfma_f32_16x16x32_bf16 v[126:129], v[130:133], v[90:93], v[126:129]
	s_waitcnt lgkmcnt(5)
	v_mfma_f32_16x16x32_bf16 v[126:129], v[134:137], v[94:97], v[126:129]
	s_waitcnt lgkmcnt(4)
	v_mfma_f32_16x16x32_bf16 v[126:129], v[138:141], v[118:121], v[126:129]
	ds_read_b128 v[130:133], v114 offset:26112
	ds_read_b128 v[134:137], v114 offset:26176
	ds_read_b128 v[138:141], v114 offset:26240
	ds_read_b128 v[146:149], v114 offset:26304
	s_waitcnt lgkmcnt(7)
	v_mfma_f32_16x16x32_bf16 v[56:59], v[98:101], v[86:89], v[56:59]
	s_waitcnt lgkmcnt(6)
	v_mfma_f32_16x16x32_bf16 v[56:59], v[102:105], v[90:93], v[56:59]
	s_waitcnt lgkmcnt(5)
	v_mfma_f32_16x16x32_bf16 v[56:59], v[106:109], v[94:97], v[56:59]
	s_waitcnt lgkmcnt(4)
	v_mfma_f32_16x16x32_bf16 v[56:59], v[110:113], v[118:121], v[56:59]
	v_add_u32_e32 v115, s15, v80
	v_add_u32_e32 v114, v115, v79
	ds_read_b128 v[98:101], v114
	ds_read_b128 v[102:105], v114 offset:64
	ds_read_b128 v[106:109], v114 offset:128
	ds_read_b128 v[110:113], v114 offset:192
	s_waitcnt lgkmcnt(7)
	v_mfma_f32_16x16x32_bf16 v[130:133], v[130:133], v[86:89], 0
	s_waitcnt lgkmcnt(6)
	v_mfma_f32_16x16x32_bf16 v[130:133], v[134:137], v[90:93], v[130:133]
	s_waitcnt lgkmcnt(5)
	v_mfma_f32_16x16x32_bf16 v[130:133], v[138:141], v[94:97], v[130:133]
	s_waitcnt lgkmcnt(4)
	v_mfma_f32_16x16x32_bf16 v[130:133], v[146:149], v[118:121], v[130:133]
	ds_read_b128 v[134:137], v114 offset:17408
	ds_read_b128 v[138:141], v114 offset:17472
	ds_read_b128 v[146:149], v114 offset:17536
	ds_read_b128 v[156:159], v114 offset:17600
	s_waitcnt lgkmcnt(7)
	v_mfma_f32_16x16x32_bf16 v[52:55], v[98:101], v[86:89], v[52:55]
	s_waitcnt lgkmcnt(6)
	v_mfma_f32_16x16x32_bf16 v[52:55], v[102:105], v[90:93], v[52:55]
	s_waitcnt lgkmcnt(5)
	v_mfma_f32_16x16x32_bf16 v[52:55], v[106:109], v[94:97], v[52:55]
	s_waitcnt lgkmcnt(4)
	v_mfma_f32_16x16x32_bf16 v[52:55], v[110:113], v[118:121], v[52:55]
	s_waitcnt lgkmcnt(3)
	v_mfma_f32_16x16x32_bf16 v[86:89], v[134:137], v[86:89], 0
	s_waitcnt lgkmcnt(2)
	v_mfma_f32_16x16x32_bf16 v[86:89], v[138:141], v[90:93], v[86:89]
	s_waitcnt lgkmcnt(1)
	v_mfma_f32_16x16x32_bf16 v[86:89], v[146:149], v[94:97], v[86:89]
	s_waitcnt lgkmcnt(0)
	v_mfma_f32_16x16x32_bf16 v[86:89], v[156:159], v[118:121], v[86:89]
	v_cvt_pk_bf16_f32 v56, v56, v57
	v_cvt_pk_bf16_f32 v57, v58, v59
	v_cvt_pk_bf16_f32 v58, v52, v53
	v_lshlrev_b32_e32 v52, 2, v192
	v_and_b32_e32 v52, 0x100, v52
	v_add_u32_e32 v52, s10, v52
	v_add3_u32 v138, s15, v84, v85
	v_cvt_pk_bf16_f32 v64, v64, v65
	v_cvt_pk_bf16_f32 v65, v66, v67
	v_cvt_pk_bf16_f32 v66, v60, v61
	v_cvt_pk_bf16_f32 v67, v62, v63
	v_cvt_pk_bf16_f32 v59, v54, v55
	ds_bpermute_b32 v114, v52, v76
	ds_read_b128 v[52:55], v138 offset:34816
	ds_read_b128 v[60:63], v138 offset:37120
	ds_read_b128 v[90:93], v138 offset:39424
	ds_read_b128 v[94:97], v138 offset:39488
	v_add3_u32 v115, v115, v83, v85
	ds_read_b128 v[98:101], v115 offset:34816
	ds_read_b128 v[102:105], v115 offset:34880
	ds_read_b128 v[106:109], v138 offset:44032
	ds_read_b128 v[110:113], v138 offset:44096
	ds_read_b128 v[118:121], v138 offset:46336
	ds_read_b128 v[134:137], v138 offset:46400
	s_waitcnt lgkmcnt(9)
	v_mfma_f32_16x16x32_bf16 v[52:55], v[52:55], v[64:67], v[122:125]
	s_waitcnt lgkmcnt(8)
	v_mfma_f32_16x16x32_bf16 v[60:63], v[60:63], v[64:67], v[126:129]
	s_waitcnt lgkmcnt(7)
	v_mfma_f32_16x16x32_bf16 v[90:93], v[90:93], v[64:67], v[130:133]
	s_waitcnt lgkmcnt(5)
	v_mfma_f32_16x16x32_bf16 v[86:89], v[98:101], v[64:67], v[86:89]
	v_mfma_f32_16x16x32_bf16 v[90:93], v[94:97], v[56:59], v[90:93]
	s_waitcnt lgkmcnt(4)
	v_mfma_f32_16x16x32_bf16 v[86:89], v[102:105], v[56:59], v[86:89]
	ds_read_b128 v[94:97], v138 offset:48640
	ds_read_b128 v[98:101], v138 offset:48704
	ds_read_b128 v[102:105], v115 offset:44032
	ds_read_b128 v[122:125], v115 offset:44096
	v_pk_mul_f32 v[6:7], v[6:7], v[114:115] op_sel_hi:[1,0]
	v_pk_mul_f32 v[4:5], v[4:5], v[114:115] op_sel_hi:[1,0]
	v_pk_mul_f32 v[30:31], v[30:31], v[114:115] op_sel_hi:[1,0]
	v_pk_mul_f32 v[28:29], v[28:29], v[114:115] op_sel_hi:[1,0]
	s_waitcnt lgkmcnt(7)
	v_mfma_f32_16x16x32_bf16 v[4:7], v[106:109], v[64:67], v[4:7]
	s_waitcnt lgkmcnt(5)
; #define LBAR() do { asm volatile("s_waitcnt lgkmcnt(0)" ::: "memory"); __builtin_amdgcn_s_barrier(); asm volatile("" ::: "memory"); } while (0)
; #define SBAR() __builtin_amdgcn_sched_barrier(0)
; #define LDK(d, dt0) do { d[0] = frag1(Kl + ((dt0) * 16 + r) * TS + q8 * 8); d[1] = frag1(Kl + ((dt0) * 16 + r) * TS + 32 + q8 * 8); d[2] = frag1(Kl + (((dt0) + 1) * 16 + r) * TS + q8 * 8); d[3] = frag1(Kl + (((dt0) + 1) * 16 + r) * TS + 32 + q8 * 8); } while (0)
; __device__ __forceinline__ void scan_bh(LAS unsigned char* lds, const ScanP& P, int b, int h, int half, int tid, int lane, int wave) {
;     ...
;         {
;             bf16x8 aA[6], kA[4], kB[4];
;             aA[0] = frag1(Al + (0 * 16 + r) * TS + q8 * 8); aA[1] = frag1(Al + (1 * 16 + r) * TS + q8 * 8);
;             aA[2] = frag1(Al + (2 * 16 + r) * TS + q8 * 8); aA[3] = frag1(Al + (2 * 16 + r) * TS + 32 + q8 * 8);
;             aA[4] = frag1(Al + (3 * 16 + r) * TS + q8 * 8); aA[5] = frag1(Al + (3 * 16 + r) * TS + 32 + q8 * 8);
;             SBAR(); LDK(kA, 0); SBAR();
;             o[0] = __builtin_amdgcn_mfma_f32_16x16x32_bf16(aA[0], Ub[0], o[0], 0, 0, 0); o[1] = __builtin_amdgcn_mfma_f32_16x16x32_bf16(aA[1], Ub[0], o[1], 0, 0, 0);
;             o[2] = __builtin_amdgcn_mfma_f32_16x16x32_bf16(aA[2], Ub[0], o[2], 0, 0, 0); o[3] = __builtin_amdgcn_mfma_f32_16x16x32_bf16(aA[4], Ub[0], o[3], 0, 0, 0);
;             o[2] = __builtin_amdgcn_mfma_f32_16x16x32_bf16(aA[3], Ub[1], o[2], 0, 0, 0); o[3] = __builtin_amdgcn_mfma_f32_16x16x32_bf16(aA[5], Ub[1], o[3], 0, 0, 0);
;             SBAR(); LDK(kB, 2); SBAR(); MMK(kA, 0); SBAR(); LDK(kA, 4); SBAR(); MMK(kB, 2); SBAR(); LDK(kB, 6); SBAR(); MMK(kA, 4); SBAR(); MMK(kB, 6); SBAR();
;         }
;     ...
;         { unsigned oO = (unsigned)((q8 * 4) * 1024 + c0 + r) * 4u; asm volatile("" : "+v"(oO));
;           unsigned char* ob = (unsigned char*)(P.obuf + (size_t)(b * SEQ + n * 64) * 1024 + h * 128);
; #pragma unroll
;           for (int mt = 0; mt < 4; ++mt)
; #pragma unroll
;               for (int j = 0; j < 4; ++j) *(float*)(ob + (oO + (unsigned)(mt * 16 + j) * 4096u)) = o[mt][j]; }
;             LBAR();
;         }
	v_mfma_f32_16x16x32_bf16 v[28:31], v[118:121], v[64:67], v[28:31]
	v_mfma_f32_16x16x32_bf16 v[4:7], v[110:113], v[56:59], v[4:7]
	s_waitcnt lgkmcnt(4)
	v_mfma_f32_16x16x32_bf16 v[28:31], v[134:137], v[56:59], v[28:31]
	ds_read_b128 v[106:109], v138 offset:53248
	ds_read_b128 v[110:113], v138 offset:53312
	ds_read_b128 v[118:121], v138 offset:55552
	ds_read_b128 v[126:129], v138 offset:55616
	v_pk_mul_f32 v[34:35], v[34:35], v[114:115] op_sel_hi:[1,0]
	v_pk_mul_f32 v[32:33], v[32:33], v[114:115] op_sel_hi:[1,0]
	v_pk_mul_f32 v[14:15], v[14:15], v[114:115] op_sel_hi:[1,0]
	v_pk_mul_f32 v[12:13], v[12:13], v[114:115] op_sel_hi:[1,0]
	s_waitcnt lgkmcnt(7)
	v_mfma_f32_16x16x32_bf16 v[32:35], v[94:97], v[64:67], v[32:35]
	s_waitcnt lgkmcnt(5)
	v_mfma_f32_16x16x32_bf16 v[12:15], v[102:105], v[64:67], v[12:15]
	v_mfma_f32_16x16x32_bf16 v[32:35], v[98:101], v[56:59], v[32:35]
	s_waitcnt lgkmcnt(4)
	v_mfma_f32_16x16x32_bf16 v[12:15], v[122:125], v[56:59], v[12:15]
	v_add3_u32 v115, s15, v81, v85
	ds_read_b128 v[94:97], v138 offset:57856
	ds_read_b128 v[98:101], v138 offset:57920
	ds_read_b128 v[102:105], v115 offset:44032
	ds_read_b128 v[122:125], v115 offset:44096
	v_pk_mul_f32 v[22:23], v[22:23], v[114:115] op_sel_hi:[1,0]
	v_pk_mul_f32 v[20:21], v[20:21], v[114:115] op_sel_hi:[1,0]
	v_pk_mul_f32 v[10:11], v[10:11], v[114:115] op_sel_hi:[1,0]
	v_pk_mul_f32 v[8:9], v[8:9], v[114:115] op_sel_hi:[1,0]
	s_waitcnt lgkmcnt(7)
	v_mfma_f32_16x16x32_bf16 v[20:23], v[106:109], v[64:67], v[20:23]
	s_waitcnt lgkmcnt(5)
	v_mfma_f32_16x16x32_bf16 v[8:11], v[118:121], v[64:67], v[8:11]
	v_mfma_f32_16x16x32_bf16 v[20:23], v[110:113], v[56:59], v[20:23]
	s_waitcnt lgkmcnt(4)
	v_mfma_f32_16x16x32_bf16 v[8:11], v[126:129], v[56:59], v[8:11]
	v_mul_f32_e64 v26, v26, v114
	v_mul_f32_e64 v27, v27, v114
	v_pk_mul_f32 v[24:25], v[24:25], v[114:115] op_sel_hi:[1,0]
	v_pk_mul_f32 v[18:19], v[18:19], v[114:115] op_sel_hi:[1,0]
	v_pk_mul_f32 v[16:17], v[16:17], v[114:115] op_sel_hi:[1,0]
	s_waitcnt lgkmcnt(3)
	v_mfma_f32_16x16x32_bf16 v[24:27], v[94:97], v[64:67], v[24:27]
	s_waitcnt lgkmcnt(1)
	v_mfma_f32_16x16x32_bf16 v[16:19], v[102:105], v[64:67], v[16:19]
	v_mfma_f32_16x16x32_bf16 v[24:27], v[98:101], v[56:59], v[24:27]
	s_waitcnt lgkmcnt(0)
	v_mfma_f32_16x16x32_bf16 v[16:19], v[122:125], v[56:59], v[16:19]
	v_mov_b32_e32 v152, v82
	v_mov_b64_e32 v[66:67], v[190:191]
	v_lshl_add_u64 v[56:57], s[4:5], 0, v[152:153]
	v_lshl_add_u64 v[56:57], v[2:3], 0, v[56:57]
	global_store_dword v[56:57], v52, off
	v_add_u32_e32 v56, 0x1000, v152
	v_mov_b32_e32 v57, v153
	v_lshl_add_u64 v[56:57], s[4:5], 0, v[56:57]
	v_lshl_add_u64 v[56:57], v[2:3], 0, v[56:57]
	global_store_dword v[56:57], v53, off
	v_add_u32_e32 v52, 0x2000, v152
	v_mov_b32_e32 v53, v153
	v_lshl_add_u64 v[52:53], s[4:5], 0, v[52:53]
	v_lshl_add_u64 v[52:53], v[2:3], 0, v[52:53]
	global_store_dword v[52:53], v54, off
	v_add_u32_e32 v52, 0x3000, v152
	v_mov_b32_e32 v53, v153
	v_lshl_add_u64 v[52:53], s[4:5], 0, v[52:53]
	v_lshl_add_u64 v[52:53], v[2:3], 0, v[52:53]
	global_store_dword v[52:53], v55, off
	v_add_u32_e32 v52, 0x10000, v152
	v_mov_b32_e32 v53, v153
	v_lshl_add_u64 v[52:53], s[4:5], 0, v[52:53]
	v_lshl_add_u64 v[52:53], v[2:3], 0, v[52:53]
	global_store_dword v[52:53], v60, off
	v_add_u32_e32 v52, 0x11000, v152
	v_mov_b32_e32 v53, v153
	v_lshl_add_u64 v[52:53], s[4:5], 0, v[52:53]
	v_lshl_add_u64 v[52:53], v[2:3], 0, v[52:53]
	global_store_dword v[52:53], v61, off
	v_add_u32_e32 v52, 0x12000, v152
	v_mov_b32_e32 v53, v153
	v_lshl_add_u64 v[52:53], s[4:5], 0, v[52:53]
	v_lshl_add_u64 v[52:53], v[2:3], 0, v[52:53]
	global_store_dword v[52:53], v62, off
	v_add_u32_e32 v52, 0x13000, v152
	v_mov_b32_e32 v53, v153
	v_lshl_add_u64 v[52:53], s[4:5], 0, v[52:53]
	v_lshl_add_u64 v[52:53], v[2:3], 0, v[52:53]
	global_store_dword v[52:53], v63, off
	v_add_u32_e32 v52, 0x20000, v152
	v_mov_b32_e32 v53, v153
	v_lshl_add_u64 v[52:53], s[4:5], 0, v[52:53]
	v_lshl_add_u64 v[52:53], v[2:3], 0, v[52:53]
	global_store_dword v[52:53], v90, off
	v_add_u32_e32 v52, 0x21000, v152
	v_mov_b32_e32 v53, v153
	v_lshl_add_u64 v[52:53], s[4:5], 0, v[52:53]
	v_lshl_add_u64 v[52:53], v[2:3], 0, v[52:53]
	global_store_dword v[52:53], v91, off
	v_add_u32_e32 v52, 0x22000, v152
	v_mov_b32_e32 v53, v153
	v_lshl_add_u64 v[52:53], s[4:5], 0, v[52:53]
	v_lshl_add_u64 v[52:53], v[2:3], 0, v[52:53]
	global_store_dword v[52:53], v92, off
	v_add_u32_e32 v52, 0x23000, v152
	v_mov_b32_e32 v53, v153
	v_lshl_add_u64 v[52:53], s[4:5], 0, v[52:53]
	v_lshl_add_u64 v[52:53], v[2:3], 0, v[52:53]
	global_store_dword v[52:53], v93, off
	v_add_u32_e32 v52, 0x30000, v152
	v_mov_b32_e32 v53, v153
	v_lshl_add_u64 v[52:53], s[4:5], 0, v[52:53]
	v_lshl_add_u64 v[52:53], v[2:3], 0, v[52:53]
	global_store_dword v[52:53], v86, off
	v_add_u32_e32 v52, 0x31000, v152
	v_mov_b32_e32 v53, v153
	v_lshl_add_u64 v[52:53], s[4:5], 0, v[52:53]
	v_lshl_add_u64 v[52:53], v[2:3], 0, v[52:53]
	global_store_dword v[52:53], v87, off
	v_add_u32_e32 v52, 0x32000, v152
	v_mov_b32_e32 v53, v153
	v_lshl_add_u64 v[52:53], s[4:5], 0, v[52:53]
	v_lshl_add_u64 v[52:53], v[2:3], 0, v[52:53]
	v_add_u32_e32 v152, 0x33000, v152
	global_store_dword v[52:53], v88, off
	v_lshl_add_u64 v[52:53], s[4:5], 0, v[152:153]
	v_lshl_add_u64 v[52:53], v[2:3], 0, v[52:53]
	global_store_dword v[52:53], v89, off
	s_waitcnt lgkmcnt(0)
	s_barrier
	s_add_u32 s4, s4, 0x40000
	s_addc_u32 s5, s5, 0
	s_add_i32 s10, s10, 4
	s_add_i32 s11, s11, 8
	s_add_i32 s14, s14, 1
	v_mov_b64_e32 v[54:55], v[178:179]
	v_mov_b64_e32 v[58:59], v[182:183]
	v_mov_b64_e32 v[62:63], v[186:187]
	s_cmp_eq_u32 s4, 0x800000
	v_mov_b64_e32 v[52:53], v[176:177]
	v_mov_b64_e32 v[56:57], v[180:181]
	v_mov_b64_e32 v[60:61], v[184:185]
	v_mov_b64_e32 v[64:65], v[188:189]
; #define LAS __attribute__((address_space(3)))
; __device__ __forceinline__ bf16x8 packB(const f32x4& a, const f32x4& b) { u32x4 v = {pk2(a[0], a[1]), pk2(a[2], a[3]), pk2(b[0], b[1]), pk2(b[2], b[3])}; return __builtin_bit_cast(bf16x8, v); }
; #define U_LOAD(nn) do { const unsigned char* tr_ = P.tr + (size_t)((b << 8) | ((nn) << 3) | h) * TR_SZ; \
;             _Pragma("unroll") for (int mt_ = 0; mt_ < 4; ++mt_) ubn[mt_] = *(const f32x4*)(tr_ + (oU + (unsigned)mt_ * 1024u)); } while (0)
; #define SBAR() __builtin_amdgcn_sched_barrier(0)
; #define LD4(d, base, mt, stride) do { _Pragma("unroll") for (int ks = 0; ks < 4; ++ks) d[ks] = frag1((base) + ((mt) * 16 + r) * (stride) + ks * 32 + q8 * 8); } while (0)
; #define MM4(acc, s_) do { _Pragma("unroll") for (int ks = 0; ks < 4; ++ks) acc = __builtin_amdgcn_mfma_f32_16x16x32_bf16(s_[ks], Sb[ks], acc, 0, 0, 0); } while (0)
; __device__ __forceinline__ void scan_bh(LAS unsigned char* lds, const ScanP& P, int b, int h, int half, int tid, int lane, int wave) {
;     ...
;         U_LOAD(0);
;         __syncthreads();
; #pragma unroll 1
;         for (int n = 0; n < 32; ++n) {
;             LAS unsigned char* buf = lds + (n & 1) * SB_SZ;
;             const LAS bf16_t* Wl = (const LAS bf16_t*)(buf + SB_W); const LAS bf16_t* Ql = (const LAS bf16_t*)(buf + SB_Q);
;             const LAS bf16_t* Al = (const LAS bf16_t*)(buf + SB_A); const LAS bf16_t* Kl = (const LAS bf16_t*)(buf + SB_K);
;             f32x4 u[4], o[4];
; #pragma unroll
;             for (int mt = 0; mt < 4; ++mt) { u[mt] = ubn[mt]; o[mt] = (f32x4){0.f, 0.f, 0.f, 0.f}; }
;             if (n + 1 < 32) U_LOAD(n + 1);
;         bf16x8 Sb[4];
; #pragma unroll
;         for (int ks = 0; ks < 4; ++ks) Sb[ks] = packB(S[2 * ks], S[2 * ks + 1]);
;     ...
;         {
;             bf16x8 fA[4], fB[4];
;             LD4(fA, Wl, 0, PS); SBAR(); LD4(fB, Ql, 0, PS); SBAR();
;             MM4(u[0], fA); SBAR(); LD4(fA, Wl, 1, PS); SBAR(); MM4(o[0], fB); SBAR(); LD4(fB, Ql, 1, PS); SBAR();
;             MM4(u[1], fA); SBAR(); LD4(fA, Wl, 2, PS); SBAR(); MM4(o[1], fB); SBAR(); LD4(fB, Ql, 2, PS); SBAR();
;             MM4(u[2], fA); SBAR(); LD4(fA, Wl, 3, PS); SBAR(); MM4(o[2], fB); SBAR(); LD4(fB, Ql, 3, PS); SBAR();
.Lscan_c1:
	s_add_i32 s15, s11, 24
	s_min_u32 s15, s15, 0xf8
	s_or_b32 s15, s15, s6
	v_mad_i64_i32 v[44:45], s[16:17], s15, v199, v[116:117]
	v_lshl_add_u64 v[36:37], v[44:45], 0, v[74:75]
	v_lshl_add_u64 v[38:39], v[44:45], 0, v[72:73]
	v_lshl_add_u64 v[46:47], v[44:45], 0, v[70:71]
	v_lshl_add_u64 v[44:45], v[44:45], 0, v[68:69]
	global_load_dwordx4 v[176:179], v[36:37], off
	global_load_dwordx4 v[180:183], v[38:39], off
	global_load_dwordx4 v[184:187], v[46:47], off
	global_load_dwordx4 v[188:191], v[44:45], off
	s_waitcnt vmcnt(60)
	s_bitcmp1_b32 s14, 0
	s_cselect_b32 s15, 0xf400, 0
	s_add_i32 s15, s15, 0
	v_add3_u32 v114, s15, v78, v79
	ds_read_b128 v[98:101], v114
	ds_read_b128 v[102:105], v114 offset:64
	ds_read_b128 v[106:109], v114 offset:128
	ds_read_b128 v[110:113], v114 offset:192
	v_cvt_pk_bf16_f32 v86, v4, v5
	v_cvt_pk_bf16_f32 v87, v6, v7
	v_cvt_pk_bf16_f32 v88, v28, v29
	v_cvt_pk_bf16_f32 v89, v30, v31
	v_cvt_pk_bf16_f32 v90, v32, v33
	v_cvt_pk_bf16_f32 v91, v34, v35
	v_cvt_pk_bf16_f32 v92, v12, v13
	v_cvt_pk_bf16_f32 v93, v14, v15
	v_cvt_pk_bf16_f32 v94, v20, v21
	v_cvt_pk_bf16_f32 v95, v22, v23
	v_cvt_pk_bf16_f32 v96, v8, v9
	v_cvt_pk_bf16_f32 v97, v10, v11
	v_cvt_pk_bf16_f32 v118, v24, v25
	v_cvt_pk_bf16_f32 v119, v26, v27
	v_cvt_pk_bf16_f32 v120, v16, v17
	v_cvt_pk_bf16_f32 v121, v18, v19
	ds_read_b128 v[122:125], v114 offset:17408
	ds_read_b128 v[126:129], v114 offset:17472
	ds_read_b128 v[130:133], v114 offset:17536
	ds_read_b128 v[134:137], v114 offset:17600
	s_waitcnt lgkmcnt(7)
	v_mfma_f32_16x16x32_bf16 v[64:67], v[98:101], v[86:89], v[64:67]
	s_waitcnt lgkmcnt(6)
	v_mfma_f32_16x16x32_bf16 v[64:67], v[102:105], v[90:93], v[64:67]
	s_waitcnt lgkmcnt(5)
	v_mfma_f32_16x16x32_bf16 v[64:67], v[106:109], v[94:97], v[64:67]
	s_waitcnt lgkmcnt(4)
	v_mfma_f32_16x16x32_bf16 v[64:67], v[110:113], v[118:121], v[64:67]
	ds_read_b128 v[98:101], v114 offset:4352
	ds_read_b128 v[102:105], v114 offset:4416
	ds_read_b128 v[106:109], v114 offset:4480
	ds_read_b128 v[110:113], v114 offset:4544
	s_waitcnt lgkmcnt(7)
	v_mfma_f32_16x16x32_bf16 v[122:125], v[122:125], v[86:89], 0
	s_waitcnt lgkmcnt(6)
	v_mfma_f32_16x16x32_bf16 v[122:125], v[126:129], v[90:93], v[122:125]
	s_waitcnt lgkmcnt(5)
	v_mfma_f32_16x16x32_bf16 v[122:125], v[130:133], v[94:97], v[122:125]
	s_waitcnt lgkmcnt(4)
	v_mfma_f32_16x16x32_bf16 v[122:125], v[134:137], v[118:121], v[122:125]
	ds_read_b128 v[126:129], v114 offset:21760
	ds_read_b128 v[130:133], v114 offset:21824
	ds_read_b128 v[134:137], v114 offset:21888
	ds_read_b128 v[138:141], v114 offset:21952
	s_waitcnt lgkmcnt(7)
	v_mfma_f32_16x16x32_bf16 v[60:63], v[98:101], v[86:89], v[60:63]
	s_waitcnt lgkmcnt(6)
	v_mfma_f32_16x16x32_bf16 v[60:63], v[102:105], v[90:93], v[60:63]
	s_waitcnt lgkmcnt(5)
	v_mfma_f32_16x16x32_bf16 v[60:63], v[106:109], v[94:97], v[60:63]
	s_waitcnt lgkmcnt(4)
	v_mfma_f32_16x16x32_bf16 v[60:63], v[110:113], v[118:121], v[60:63]
	ds_read_b128 v[98:101], v114 offset:8704
	ds_read_b128 v[102:105], v114 offset:8768
	ds_read_b128 v[106:109], v114 offset:8832
	ds_read_b128 v[110:113], v114 offset:8896
	s_waitcnt lgkmcnt(7)
	v_mfma_f32_16x16x32_bf16 v[126:129], v[126:129], v[86:89], 0
	s_waitcnt lgkmcnt(6)
	v_mfma_f32_16x16x32_bf16 v[126:129], v[130:133], v[90:93], v[126:129]
	s_waitcnt lgkmcnt(5)
	v_mfma_f32_16x16x32_bf16 v[126:129], v[134:137], v[94:97], v[126:129]
	s_waitcnt lgkmcnt(4)
	v_mfma_f32_16x16x32_bf16 v[126:129], v[138:141], v[118:121], v[126:129]
	ds_read_b128 v[130:133], v114 offset:26112
	ds_read_b128 v[134:137], v114 offset:26176
	ds_read_b128 v[138:141], v114 offset:26240
	ds_read_b128 v[146:149], v114 offset:26304
	s_waitcnt lgkmcnt(7)
	v_mfma_f32_16x16x32_bf16 v[56:59], v[98:101], v[86:89], v[56:59]
	s_waitcnt lgkmcnt(6)
	v_mfma_f32_16x16x32_bf16 v[56:59], v[102:105], v[90:93], v[56:59]
	s_waitcnt lgkmcnt(5)
	v_mfma_f32_16x16x32_bf16 v[56:59], v[106:109], v[94:97], v[56:59]
	s_waitcnt lgkmcnt(4)
	v_mfma_f32_16x16x32_bf16 v[56:59], v[110:113], v[118:121], v[56:59]
	v_add_u32_e32 v115, s15, v80
	v_add_u32_e32 v114, v115, v79
	ds_read_b128 v[98:101], v114
	ds_read_b128 v[102:105], v114 offset:64
	ds_read_b128 v[106:109], v114 offset:128
	ds_read_b128 v[110:113], v114 offset:192
	s_waitcnt lgkmcnt(7)
	v_mfma_f32_16x16x32_bf16 v[130:133], v[130:133], v[86:89], 0
	s_waitcnt lgkmcnt(6)
	v_mfma_f32_16x16x32_bf16 v[130:133], v[134:137], v[90:93], v[130:133]
	s_waitcnt lgkmcnt(5)
	v_mfma_f32_16x16x32_bf16 v[130:133], v[138:141], v[94:97], v[130:133]
	s_waitcnt lgkmcnt(4)
	v_mfma_f32_16x16x32_bf16 v[130:133], v[146:149], v[118:121], v[130:133]
	ds_read_b128 v[134:137], v114 offset:17408
	ds_read_b128 v[138:141], v114 offset:17472
	ds_read_b128 v[146:149], v114 offset:17536
	ds_read_b128 v[156:159], v114 offset:17600
	s_waitcnt lgkmcnt(7)
	v_mfma_f32_16x16x32_bf16 v[52:55], v[98:101], v[86:89], v[52:55]
	s_waitcnt lgkmcnt(6)
	v_mfma_f32_16x16x32_bf16 v[52:55], v[102:105], v[90:93], v[52:55]
	s_waitcnt lgkmcnt(5)
	v_mfma_f32_16x16x32_bf16 v[52:55], v[106:109], v[94:97], v[52:55]
	s_waitcnt lgkmcnt(4)
	v_mfma_f32_16x16x32_bf16 v[52:55], v[110:113], v[118:121], v[52:55]
	s_waitcnt lgkmcnt(3)
	v_mfma_f32_16x16x32_bf16 v[86:89], v[134:137], v[86:89], 0
	s_waitcnt lgkmcnt(2)
	v_mfma_f32_16x16x32_bf16 v[86:89], v[138:141], v[90:93], v[86:89]
	s_waitcnt lgkmcnt(1)
	v_mfma_f32_16x16x32_bf16 v[86:89], v[146:149], v[94:97], v[86:89]
	s_waitcnt lgkmcnt(0)
; __device__ __forceinline__ bf16x8 packB(const f32x4& a, const f32x4& b) { u32x4 v = {pk2(a[0], a[1]), pk2(a[2], a[3]), pk2(b[0], b[1]), pk2(b[2], b[3])}; return __builtin_bit_cast(bf16x8, v); }
; #define SBAR() __builtin_amdgcn_sched_barrier(0)
; #define LDK(d, dt0) do { d[0] = frag1(Kl + ((dt0) * 16 + r) * TS + q8 * 8); d[1] = frag1(Kl + ((dt0) * 16 + r) * TS + 32 + q8 * 8); d[2] = frag1(Kl + (((dt0) + 1) * 16 + r) * TS + q8 * 8); d[3] = frag1(Kl + (((dt0) + 1) * 16 + r) * TS + 32 + q8 * 8); } while (0)
; __device__ __forceinline__ void scan_bh(LAS unsigned char* lds, const ScanP& P, int b, int h, int half, int tid, int lane, int wave) {
;     ...
;         bf16x8 Ub[2];
;         Ub[0] = packB(u[0], u[1]); Ub[1] = packB(u[2], u[3]);
;         const float gl = __shfl(glv, n);
;     ...
;         {
;             bf16x8 aA[6], kA[4], kB[4];
;             aA[0] = frag1(Al + (0 * 16 + r) * TS + q8 * 8); aA[1] = frag1(Al + (1 * 16 + r) * TS + q8 * 8);
;             aA[2] = frag1(Al + (2 * 16 + r) * TS + q8 * 8); aA[3] = frag1(Al + (2 * 16 + r) * TS + 32 + q8 * 8);
;             aA[4] = frag1(Al + (3 * 16 + r) * TS + q8 * 8); aA[5] = frag1(Al + (3 * 16 + r) * TS + 32 + q8 * 8);
;             SBAR(); LDK(kA, 0); SBAR();
;             o[0] = __builtin_amdgcn_mfma_f32_16x16x32_bf16(aA[0], Ub[0], o[0], 0, 0, 0); o[1] = __builtin_amdgcn_mfma_f32_16x16x32_bf16(aA[1], Ub[0], o[1], 0, 0, 0);
;             o[2] = __builtin_amdgcn_mfma_f32_16x16x32_bf16(aA[2], Ub[0], o[2], 0, 0, 0); o[3] = __builtin_amdgcn_mfma_f32_16x16x32_bf16(aA[4], Ub[0], o[3], 0, 0, 0);
;             o[2] = __builtin_amdgcn_mfma_f32_16x16x32_bf16(aA[3], Ub[1], o[2], 0, 0, 0); o[3] = __builtin_amdgcn_mfma_f32_16x16x32_bf16(aA[5], Ub[1], o[3], 0, 0, 0);
;             SBAR(); LDK(kB, 2); SBAR(); MMK(kA, 0); SBAR(); LDK(kA, 4); SBAR(); MMK(kB, 2); SBAR(); LDK(kB, 6); SBAR(); MMK(kA, 4); SBAR(); MMK(kB, 6); SBAR();
	v_mfma_f32_16x16x32_bf16 v[86:89], v[156:159], v[118:121], v[86:89]
	v_cvt_pk_bf16_f32 v56, v56, v57
	v_cvt_pk_bf16_f32 v57, v58, v59
	v_cvt_pk_bf16_f32 v58, v52, v53
	v_lshlrev_b32_e32 v52, 2, v192
	v_and_b32_e32 v52, 0x100, v52
	v_add_u32_e32 v52, s10, v52
	v_add3_u32 v138, s15, v84, v85
	v_cvt_pk_bf16_f32 v64, v64, v65
	v_cvt_pk_bf16_f32 v65, v66, v67
	v_cvt_pk_bf16_f32 v66, v60, v61
	v_cvt_pk_bf16_f32 v67, v62, v63
	v_cvt_pk_bf16_f32 v59, v54, v55
	ds_bpermute_b32 v114, v52, v76
	ds_read_b128 v[52:55], v138 offset:34816
	ds_read_b128 v[60:63], v138 offset:37120
	ds_read_b128 v[90:93], v138 offset:39424
	ds_read_b128 v[94:97], v138 offset:39488
	v_add3_u32 v115, v115, v83, v85
	ds_read_b128 v[98:101], v115 offset:34816
	ds_read_b128 v[102:105], v115 offset:34880
	ds_read_b128 v[106:109], v138 offset:44032
	ds_read_b128 v[110:113], v138 offset:44096
	ds_read_b128 v[118:121], v138 offset:46336
	ds_read_b128 v[134:137], v138 offset:46400
	s_waitcnt lgkmcnt(9)
	v_mfma_f32_16x16x32_bf16 v[52:55], v[52:55], v[64:67], v[122:125]
	s_waitcnt lgkmcnt(8)
	v_mfma_f32_16x16x32_bf16 v[60:63], v[60:63], v[64:67], v[126:129]
	s_waitcnt lgkmcnt(7)
	v_mfma_f32_16x16x32_bf16 v[90:93], v[90:93], v[64:67], v[130:133]
	s_waitcnt lgkmcnt(5)
	v_mfma_f32_16x16x32_bf16 v[86:89], v[98:101], v[64:67], v[86:89]
	v_mfma_f32_16x16x32_bf16 v[90:93], v[94:97], v[56:59], v[90:93]
	s_waitcnt lgkmcnt(4)
	v_mfma_f32_16x16x32_bf16 v[86:89], v[102:105], v[56:59], v[86:89]
	ds_read_b128 v[94:97], v138 offset:48640
	ds_read_b128 v[98:101], v138 offset:48704
	ds_read_b128 v[102:105], v115 offset:44032
	ds_read_b128 v[122:125], v115 offset:44096
	v_pk_mul_f32 v[6:7], v[6:7], v[114:115] op_sel_hi:[1,0]
	v_pk_mul_f32 v[4:5], v[4:5], v[114:115] op_sel_hi:[1,0]
	v_pk_mul_f32 v[30:31], v[30:31], v[114:115] op_sel_hi:[1,0]
	v_pk_mul_f32 v[28:29], v[28:29], v[114:115] op_sel_hi:[1,0]
	s_waitcnt lgkmcnt(7)
	v_mfma_f32_16x16x32_bf16 v[4:7], v[106:109], v[64:67], v[4:7]
	s_waitcnt lgkmcnt(5)
	v_mfma_f32_16x16x32_bf16 v[28:31], v[118:121], v[64:67], v[28:31]
	v_mfma_f32_16x16x32_bf16 v[4:7], v[110:113], v[56:59], v[4:7]
	s_waitcnt lgkmcnt(4)
	v_mfma_f32_16x16x32_bf16 v[28:31], v[134:137], v[56:59], v[28:31]
	ds_read_b128 v[106:109], v138 offset:53248
	ds_read_b128 v[110:113], v138 offset:53312
	ds_read_b128 v[118:121], v138 offset:55552
	ds_read_b128 v[126:129], v138 offset:55616
	v_pk_mul_f32 v[34:35], v[34:35], v[114:115] op_sel_hi:[1,0]
	v_pk_mul_f32 v[32:33], v[32:33], v[114:115] op_sel_hi:[1,0]
	v_pk_mul_f32 v[14:15], v[14:15], v[114:115] op_sel_hi:[1,0]
	v_pk_mul_f32 v[12:13], v[12:13], v[114:115] op_sel_hi:[1,0]
	s_waitcnt lgkmcnt(7)
	v_mfma_f32_16x16x32_bf16 v[32:35], v[94:97], v[64:67], v[32:35]
	s_waitcnt lgkmcnt(5)
	v_mfma_f32_16x16x32_bf16 v[12:15], v[102:105], v[64:67], v[12:15]
	v_mfma_f32_16x16x32_bf16 v[32:35], v[98:101], v[56:59], v[32:35]
	s_waitcnt lgkmcnt(4)
	v_mfma_f32_16x16x32_bf16 v[12:15], v[122:125], v[56:59], v[12:15]
	v_add3_u32 v115, s15, v81, v85
	ds_read_b128 v[94:97], v138 offset:57856
	ds_read_b128 v[98:101], v138 offset:57920
	ds_read_b128 v[102:105], v115 offset:44032
	ds_read_b128 v[122:125], v115 offset:44096
	v_pk_mul_f32 v[22:23], v[22:23], v[114:115] op_sel_hi:[1,0]
	v_pk_mul_f32 v[20:21], v[20:21], v[114:115] op_sel_hi:[1,0]
	v_pk_mul_f32 v[10:11], v[10:11], v[114:115] op_sel_hi:[1,0]
	v_pk_mul_f32 v[8:9], v[8:9], v[114:115] op_sel_hi:[1,0]
	s_waitcnt lgkmcnt(7)
	v_mfma_f32_16x16x32_bf16 v[20:23], v[106:109], v[64:67], v[20:23]
	s_waitcnt lgkmcnt(5)
	v_mfma_f32_16x16x32_bf16 v[8:11], v[118:121], v[64:67], v[8:11]
	v_mfma_f32_16x16x32_bf16 v[20:23], v[110:113], v[56:59], v[20:23]
	s_waitcnt lgkmcnt(4)
	v_mfma_f32_16x16x32_bf16 v[8:11], v[126:129], v[56:59], v[8:11]
	v_mul_f32_e64 v26, v26, v114
	v_mul_f32_e64 v27, v27, v114
	v_pk_mul_f32 v[24:25], v[24:25], v[114:115] op_sel_hi:[1,0]
	v_pk_mul_f32 v[18:19], v[18:19], v[114:115] op_sel_hi:[1,0]
	v_pk_mul_f32 v[16:17], v[16:17], v[114:115] op_sel_hi:[1,0]
	s_waitcnt lgkmcnt(3)
	v_mfma_f32_16x16x32_bf16 v[24:27], v[94:97], v[64:67], v[24:27]
	s_waitcnt lgkmcnt(1)
	v_mfma_f32_16x16x32_bf16 v[16:19], v[102:105], v[64:67], v[16:19]
	v_mfma_f32_16x16x32_bf16 v[24:27], v[98:101], v[56:59], v[24:27]
	s_waitcnt lgkmcnt(0)
; #define LAS __attribute__((address_space(3)))
; #define LBAR() do { asm volatile("s_waitcnt lgkmcnt(0)" ::: "memory"); __builtin_amdgcn_s_barrier(); asm volatile("" ::: "memory"); } while (0)
; __device__ __forceinline__ bf16x8 packB(const f32x4& a, const f32x4& b) { u32x4 v = {pk2(a[0], a[1]), pk2(a[2], a[3]), pk2(b[0], b[1]), pk2(b[2], b[3])}; return __builtin_bit_cast(bf16x8, v); }
; #define SBAR() __builtin_amdgcn_sched_barrier(0)
; #define LD4(d, base, mt, stride) do { _Pragma("unroll") for (int ks = 0; ks < 4; ++ks) d[ks] = frag1((base) + ((mt) * 16 + r) * (stride) + ks * 32 + q8 * 8); } while (0)
; __device__ __forceinline__ void scan_bh(LAS unsigned char* lds, const ScanP& P, int b, int h, int half, int tid, int lane, int wave) {
;     ...
;         U_LOAD(0);
;         __syncthreads();
; #pragma unroll 1
;         for (int n = 0; n < 32; ++n) {
;             LAS unsigned char* buf = lds + (n & 1) * SB_SZ;
;             const LAS bf16_t* Wl = (const LAS bf16_t*)(buf + SB_W); const LAS bf16_t* Ql = (const LAS bf16_t*)(buf + SB_Q);
;             const LAS bf16_t* Al = (const LAS bf16_t*)(buf + SB_A); const LAS bf16_t* Kl = (const LAS bf16_t*)(buf + SB_K);
;             f32x4 u[4], o[4];
; #pragma unroll
;             for (int mt = 0; mt < 4; ++mt) { u[mt] = ubn[mt]; o[mt] = (f32x4){0.f, 0.f, 0.f, 0.f}; }
;             if (n + 1 < 32) U_LOAD(n + 1);
;         bf16x8 Sb[4];
; #pragma unroll
;         for (int ks = 0; ks < 4; ++ks) Sb[ks] = packB(S[2 * ks], S[2 * ks + 1]);
;     ...
;         {
;             bf16x8 fA[4], fB[4];
;             LD4(fA, Wl, 0, PS); SBAR(); LD4(fB, Ql, 0, PS); SBAR();
;             MM4(u[0], fA); SBAR(); LD4(fA, Wl, 1, PS); SBAR(); MM4(o[0], fB); SBAR(); LD4(fB, Ql, 1, PS); SBAR();
;             MM4(u[1], fA); SBAR(); LD4(fA, Wl, 2, PS); SBAR(); MM4(o[1], fB); SBAR(); LD4(fB, Ql, 2, PS); SBAR();
;             MM4(u[2], fA); SBAR(); LD4(fA, Wl, 3, PS); SBAR(); MM4(o[2], fB); SBAR(); LD4(fB, Ql, 3, PS); SBAR();
;     ...
;         { unsigned oO = (unsigned)((q8 * 4) * 1024 + c0 + r) * 4u; asm volatile("" : "+v"(oO));
;           unsigned char* ob = (unsigned char*)(P.obuf + (size_t)(b * SEQ + n * 64) * 1024 + h * 128);
; #pragma unroll
;           for (int mt = 0; mt < 4; ++mt)
; #pragma unroll
;               for (int j = 0; j < 4; ++j) *(float*)(ob + (oO + (unsigned)(mt * 16 + j) * 4096u)) = o[mt][j]; }
;             LBAR();
;         }
	v_mfma_f32_16x16x32_bf16 v[16:19], v[122:125], v[56:59], v[16:19]
	v_mov_b32_e32 v152, v82
	v_mov_b64_e32 v[66:67], v[214:215]
	v_lshl_add_u64 v[56:57], s[4:5], 0, v[152:153]
	v_lshl_add_u64 v[56:57], v[2:3], 0, v[56:57]
	global_store_dword v[56:57], v52, off
	v_add_u32_e32 v56, 0x1000, v152
	v_mov_b32_e32 v57, v153
	v_lshl_add_u64 v[56:57], s[4:5], 0, v[56:57]
	v_lshl_add_u64 v[56:57], v[2:3], 0, v[56:57]
	global_store_dword v[56:57], v53, off
	v_add_u32_e32 v52, 0x2000, v152
	v_mov_b32_e32 v53, v153
	v_lshl_add_u64 v[52:53], s[4:5], 0, v[52:53]
	v_lshl_add_u64 v[52:53], v[2:3], 0, v[52:53]
	global_store_dword v[52:53], v54, off
	v_add_u32_e32 v52, 0x3000, v152
	v_mov_b32_e32 v53, v153
	v_lshl_add_u64 v[52:53], s[4:5], 0, v[52:53]
	v_lshl_add_u64 v[52:53], v[2:3], 0, v[52:53]
	global_store_dword v[52:53], v55, off
	v_add_u32_e32 v52, 0x10000, v152
	v_mov_b32_e32 v53, v153
	v_lshl_add_u64 v[52:53], s[4:5], 0, v[52:53]
	v_lshl_add_u64 v[52:53], v[2:3], 0, v[52:53]
	global_store_dword v[52:53], v60, off
	v_add_u32_e32 v52, 0x11000, v152
	v_mov_b32_e32 v53, v153
	v_lshl_add_u64 v[52:53], s[4:5], 0, v[52:53]
	v_lshl_add_u64 v[52:53], v[2:3], 0, v[52:53]
	global_store_dword v[52:53], v61, off
	v_add_u32_e32 v52, 0x12000, v152
	v_mov_b32_e32 v53, v153
	v_lshl_add_u64 v[52:53], s[4:5], 0, v[52:53]
	v_lshl_add_u64 v[52:53], v[2:3], 0, v[52:53]
	global_store_dword v[52:53], v62, off
	v_add_u32_e32 v52, 0x13000, v152
	v_mov_b32_e32 v53, v153
	v_lshl_add_u64 v[52:53], s[4:5], 0, v[52:53]
	v_lshl_add_u64 v[52:53], v[2:3], 0, v[52:53]
	global_store_dword v[52:53], v63, off
	v_add_u32_e32 v52, 0x20000, v152
	v_mov_b32_e32 v53, v153
	v_lshl_add_u64 v[52:53], s[4:5], 0, v[52:53]
	v_lshl_add_u64 v[52:53], v[2:3], 0, v[52:53]
	global_store_dword v[52:53], v90, off
	v_add_u32_e32 v52, 0x21000, v152
	v_mov_b32_e32 v53, v153
	v_lshl_add_u64 v[52:53], s[4:5], 0, v[52:53]
	v_lshl_add_u64 v[52:53], v[2:3], 0, v[52:53]
	global_store_dword v[52:53], v91, off
	v_add_u32_e32 v52, 0x22000, v152
	v_mov_b32_e32 v53, v153
	v_lshl_add_u64 v[52:53], s[4:5], 0, v[52:53]
	v_lshl_add_u64 v[52:53], v[2:3], 0, v[52:53]
	global_store_dword v[52:53], v92, off
	v_add_u32_e32 v52, 0x23000, v152
	v_mov_b32_e32 v53, v153
	v_lshl_add_u64 v[52:53], s[4:5], 0, v[52:53]
	v_lshl_add_u64 v[52:53], v[2:3], 0, v[52:53]
	global_store_dword v[52:53], v93, off
	v_add_u32_e32 v52, 0x30000, v152
	v_mov_b32_e32 v53, v153
	v_lshl_add_u64 v[52:53], s[4:5], 0, v[52:53]
	v_lshl_add_u64 v[52:53], v[2:3], 0, v[52:53]
	global_store_dword v[52:53], v86, off
	v_add_u32_e32 v52, 0x31000, v152
	v_mov_b32_e32 v53, v153
	v_lshl_add_u64 v[52:53], s[4:5], 0, v[52:53]
	v_lshl_add_u64 v[52:53], v[2:3], 0, v[52:53]
	global_store_dword v[52:53], v87, off
	v_add_u32_e32 v52, 0x32000, v152
	v_mov_b32_e32 v53, v153
	v_lshl_add_u64 v[52:53], s[4:5], 0, v[52:53]
	v_lshl_add_u64 v[52:53], v[2:3], 0, v[52:53]
	v_add_u32_e32 v152, 0x33000, v152
	global_store_dword v[52:53], v88, off
	v_lshl_add_u64 v[52:53], s[4:5], 0, v[152:153]
	v_lshl_add_u64 v[52:53], v[2:3], 0, v[52:53]
	global_store_dword v[52:53], v89, off
	s_waitcnt lgkmcnt(0)
	s_barrier
	s_add_u32 s4, s4, 0x40000
	s_addc_u32 s5, s5, 0
	s_add_i32 s10, s10, 4
	s_add_i32 s11, s11, 8
	s_add_i32 s14, s14, 1
	v_mov_b64_e32 v[54:55], v[202:203]
	v_mov_b64_e32 v[58:59], v[206:207]
	v_mov_b64_e32 v[62:63], v[210:211]
	s_cmp_eq_u32 s4, 0x800000
	v_mov_b64_e32 v[52:53], v[200:201]
	v_mov_b64_e32 v[56:57], v[204:205]
	v_mov_b64_e32 v[60:61], v[208:209]
	v_mov_b64_e32 v[64:65], v[212:213]
.Lscan_c2:
	s_add_i32 s15, s11, 24
	s_min_u32 s15, s15, 0xf8
	s_or_b32 s15, s15, s6
	v_mad_i64_i32 v[44:45], s[16:17], s15, v199, v[116:117]
	v_lshl_add_u64 v[36:37], v[44:45], 0, v[74:75]
	v_lshl_add_u64 v[38:39], v[44:45], 0, v[72:73]
	v_lshl_add_u64 v[46:47], v[44:45], 0, v[70:71]
	v_lshl_add_u64 v[44:45], v[44:45], 0, v[68:69]
	global_load_dwordx4 v[200:203], v[36:37], off
	global_load_dwordx4 v[204:207], v[38:39], off
	global_load_dwordx4 v[208:211], v[46:47], off
	global_load_dwordx4 v[212:215], v[44:45], off
	s_waitcnt vmcnt(60)
	s_bitcmp1_b32 s14, 0
	s_cselect_b32 s15, 0xf400, 0
	s_add_i32 s15, s15, 0
	v_add3_u32 v114, s15, v78, v79
	ds_read_b128 v[98:101], v114
	ds_read_b128 v[102:105], v114 offset:64
	ds_read_b128 v[106:109], v114 offset:128
	ds_read_b128 v[110:113], v114 offset:192
	v_cvt_pk_bf16_f32 v86, v4, v5
	v_cvt_pk_bf16_f32 v87, v6, v7
	v_cvt_pk_bf16_f32 v88, v28, v29
	v_cvt_pk_bf16_f32 v89, v30, v31
	v_cvt_pk_bf16_f32 v90, v32, v33
	v_cvt_pk_bf16_f32 v91, v34, v35
	v_cvt_pk_bf16_f32 v92, v12, v13
	v_cvt_pk_bf16_f32 v93, v14, v15
	v_cvt_pk_bf16_f32 v94, v20, v21
	v_cvt_pk_bf16_f32 v95, v22, v23
	v_cvt_pk_bf16_f32 v96, v8, v9
	v_cvt_pk_bf16_f32 v97, v10, v11
	v_cvt_pk_bf16_f32 v118, v24, v25
	v_cvt_pk_bf16_f32 v119, v26, v27
	v_cvt_pk_bf16_f32 v120, v16, v17
	v_cvt_pk_bf16_f32 v121, v18, v19
	ds_read_b128 v[122:125], v114 offset:17408
	ds_read_b128 v[126:129], v114 offset:17472
	ds_read_b128 v[130:133], v114 offset:17536
	ds_read_b128 v[134:137], v114 offset:17600
	s_waitcnt lgkmcnt(7)
	v_mfma_f32_16x16x32_bf16 v[64:67], v[98:101], v[86:89], v[64:67]
	s_waitcnt lgkmcnt(6)
	v_mfma_f32_16x16x32_bf16 v[64:67], v[102:105], v[90:93], v[64:67]
	s_waitcnt lgkmcnt(5)
	v_mfma_f32_16x16x32_bf16 v[64:67], v[106:109], v[94:97], v[64:67]
	s_waitcnt lgkmcnt(4)
	v_mfma_f32_16x16x32_bf16 v[64:67], v[110:113], v[118:121], v[64:67]
	ds_read_b128 v[98:101], v114 offset:4352
	ds_read_b128 v[102:105], v114 offset:4416
	ds_read_b128 v[106:109], v114 offset:4480
	ds_read_b128 v[110:113], v114 offset:4544
	s_waitcnt lgkmcnt(7)
	v_mfma_f32_16x16x32_bf16 v[122:125], v[122:125], v[86:89], 0
	s_waitcnt lgkmcnt(6)
; __device__ __forceinline__ bf16x8 packB(const f32x4& a, const f32x4& b) { u32x4 v = {pk2(a[0], a[1]), pk2(a[2], a[3]), pk2(b[0], b[1]), pk2(b[2], b[3])}; return __builtin_bit_cast(bf16x8, v); }
; #define SBAR() __builtin_amdgcn_sched_barrier(0)
; #define LD4(d, base, mt, stride) do { _Pragma("unroll") for (int ks = 0; ks < 4; ++ks) d[ks] = frag1((base) + ((mt) * 16 + r) * (stride) + ks * 32 + q8 * 8); } while (0)
; __device__ __forceinline__ void scan_bh(LAS unsigned char* lds, const ScanP& P, int b, int h, int half, int tid, int lane, int wave) {
;     ...
;         {
;             bf16x8 fA[4], fB[4];
;             LD4(fA, Wl, 0, PS); SBAR(); LD4(fB, Ql, 0, PS); SBAR();
;             MM4(u[0], fA); SBAR(); LD4(fA, Wl, 1, PS); SBAR(); MM4(o[0], fB); SBAR(); LD4(fB, Ql, 1, PS); SBAR();
;             MM4(u[1], fA); SBAR(); LD4(fA, Wl, 2, PS); SBAR(); MM4(o[1], fB); SBAR(); LD4(fB, Ql, 2, PS); SBAR();
;             MM4(u[2], fA); SBAR(); LD4(fA, Wl, 3, PS); SBAR(); MM4(o[2], fB); SBAR(); LD4(fB, Ql, 3, PS); SBAR();
;             MM4(u[3], fA); SBAR(); MM4(o[3], fB); SBAR();
;         }
;         bf16x8 Ub[2];
;         Ub[0] = packB(u[0], u[1]); Ub[1] = packB(u[2], u[3]);
;         const float gl = __shfl(glv, n);
;     ...
;         {
;             bf16x8 aA[6], kA[4], kB[4];
;             aA[0] = frag1(Al + (0 * 16 + r) * TS + q8 * 8); aA[1] = frag1(Al + (1 * 16 + r) * TS + q8 * 8);
;             aA[2] = frag1(Al + (2 * 16 + r) * TS + q8 * 8); aA[3] = frag1(Al + (2 * 16 + r) * TS + 32 + q8 * 8);
;             aA[4] = frag1(Al + (3 * 16 + r) * TS + q8 * 8); aA[5] = frag1(Al + (3 * 16 + r) * TS + 32 + q8 * 8);
;             SBAR(); LDK(kA, 0); SBAR();
;             o[0] = __builtin_amdgcn_mfma_f32_16x16x32_bf16(aA[0], Ub[0], o[0], 0, 0, 0); o[1] = __builtin_amdgcn_mfma_f32_16x16x32_bf16(aA[1], Ub[0], o[1], 0, 0, 0);
;             o[2] = __builtin_amdgcn_mfma_f32_16x16x32_bf16(aA[2], Ub[0], o[2], 0, 0, 0); o[3] = __builtin_amdgcn_mfma_f32_16x16x32_bf16(aA[4], Ub[0], o[3], 0, 0, 0);
;             o[2] = __builtin_amdgcn_mfma_f32_16x16x32_bf16(aA[3], Ub[1], o[2], 0, 0, 0); o[3] = __builtin_amdgcn_mfma_f32_16x16x32_bf16(aA[5], Ub[1], o[3], 0, 0, 0);
;             SBAR(); LDK(kB, 2); SBAR(); MMK(kA, 0); SBAR(); LDK(kA, 4); SBAR(); MMK(kB, 2); SBAR(); LDK(kB, 6); SBAR(); MMK(kA, 4); SBAR(); MMK(kB, 6); SBAR();
	v_mfma_f32_16x16x32_bf16 v[122:125], v[126:129], v[90:93], v[122:125]
	s_waitcnt lgkmcnt(5)
	v_mfma_f32_16x16x32_bf16 v[122:125], v[130:133], v[94:97], v[122:125]
	s_waitcnt lgkmcnt(4)
	v_mfma_f32_16x16x32_bf16 v[122:125], v[134:137], v[118:121], v[122:125]
	ds_read_b128 v[126:129], v114 offset:21760
	ds_read_b128 v[130:133], v114 offset:21824
	ds_read_b128 v[134:137], v114 offset:21888
	ds_read_b128 v[138:141], v114 offset:21952
	s_waitcnt lgkmcnt(7)
	v_mfma_f32_16x16x32_bf16 v[60:63], v[98:101], v[86:89], v[60:63]
	s_waitcnt lgkmcnt(6)
	v_mfma_f32_16x16x32_bf16 v[60:63], v[102:105], v[90:93], v[60:63]
	s_waitcnt lgkmcnt(5)
	v_mfma_f32_16x16x32_bf16 v[60:63], v[106:109], v[94:97], v[60:63]
	s_waitcnt lgkmcnt(4)
	v_mfma_f32_16x16x32_bf16 v[60:63], v[110:113], v[118:121], v[60:63]
	ds_read_b128 v[98:101], v114 offset:8704
	ds_read_b128 v[102:105], v114 offset:8768
	ds_read_b128 v[106:109], v114 offset:8832
	ds_read_b128 v[110:113], v114 offset:8896
	s_waitcnt lgkmcnt(7)
	v_mfma_f32_16x16x32_bf16 v[126:129], v[126:129], v[86:89], 0
	s_waitcnt lgkmcnt(6)
	v_mfma_f32_16x16x32_bf16 v[126:129], v[130:133], v[90:93], v[126:129]
	s_waitcnt lgkmcnt(5)
	v_mfma_f32_16x16x32_bf16 v[126:129], v[134:137], v[94:97], v[126:129]
	s_waitcnt lgkmcnt(4)
	v_mfma_f32_16x16x32_bf16 v[126:129], v[138:141], v[118:121], v[126:129]
	ds_read_b128 v[130:133], v114 offset:26112
	ds_read_b128 v[134:137], v114 offset:26176
	ds_read_b128 v[138:141], v114 offset:26240
	ds_read_b128 v[146:149], v114 offset:26304
	s_waitcnt lgkmcnt(7)
	v_mfma_f32_16x16x32_bf16 v[56:59], v[98:101], v[86:89], v[56:59]
	s_waitcnt lgkmcnt(6)
	v_mfma_f32_16x16x32_bf16 v[56:59], v[102:105], v[90:93], v[56:59]
	s_waitcnt lgkmcnt(5)
	v_mfma_f32_16x16x32_bf16 v[56:59], v[106:109], v[94:97], v[56:59]
	s_waitcnt lgkmcnt(4)
	v_mfma_f32_16x16x32_bf16 v[56:59], v[110:113], v[118:121], v[56:59]
	v_add_u32_e32 v115, s15, v80
	v_add_u32_e32 v114, v115, v79
	ds_read_b128 v[98:101], v114
	ds_read_b128 v[102:105], v114 offset:64
	ds_read_b128 v[106:109], v114 offset:128
	ds_read_b128 v[110:113], v114 offset:192
	s_waitcnt lgkmcnt(7)
	v_mfma_f32_16x16x32_bf16 v[130:133], v[130:133], v[86:89], 0
	s_waitcnt lgkmcnt(6)
	v_mfma_f32_16x16x32_bf16 v[130:133], v[134:137], v[90:93], v[130:133]
	s_waitcnt lgkmcnt(5)
	v_mfma_f32_16x16x32_bf16 v[130:133], v[138:141], v[94:97], v[130:133]
	s_waitcnt lgkmcnt(4)
	v_mfma_f32_16x16x32_bf16 v[130:133], v[146:149], v[118:121], v[130:133]
	ds_read_b128 v[134:137], v114 offset:17408
	ds_read_b128 v[138:141], v114 offset:17472
	ds_read_b128 v[146:149], v114 offset:17536
	ds_read_b128 v[156:159], v114 offset:17600
	s_waitcnt lgkmcnt(7)
	v_mfma_f32_16x16x32_bf16 v[52:55], v[98:101], v[86:89], v[52:55]
	s_waitcnt lgkmcnt(6)
	v_mfma_f32_16x16x32_bf16 v[52:55], v[102:105], v[90:93], v[52:55]
	s_waitcnt lgkmcnt(5)
	v_mfma_f32_16x16x32_bf16 v[52:55], v[106:109], v[94:97], v[52:55]
	s_waitcnt lgkmcnt(4)
	v_mfma_f32_16x16x32_bf16 v[52:55], v[110:113], v[118:121], v[52:55]
	s_waitcnt lgkmcnt(3)
	v_mfma_f32_16x16x32_bf16 v[86:89], v[134:137], v[86:89], 0
	s_waitcnt lgkmcnt(2)
	v_mfma_f32_16x16x32_bf16 v[86:89], v[138:141], v[90:93], v[86:89]
	s_waitcnt lgkmcnt(1)
	v_mfma_f32_16x16x32_bf16 v[86:89], v[146:149], v[94:97], v[86:89]
	s_waitcnt lgkmcnt(0)
	v_mfma_f32_16x16x32_bf16 v[86:89], v[156:159], v[118:121], v[86:89]
	v_cvt_pk_bf16_f32 v56, v56, v57
	v_cvt_pk_bf16_f32 v57, v58, v59
	v_cvt_pk_bf16_f32 v58, v52, v53
	v_lshlrev_b32_e32 v52, 2, v192
	v_and_b32_e32 v52, 0x100, v52
	v_add_u32_e32 v52, s10, v52
	v_add3_u32 v138, s15, v84, v85
	v_cvt_pk_bf16_f32 v64, v64, v65
	v_cvt_pk_bf16_f32 v65, v66, v67
	v_cvt_pk_bf16_f32 v66, v60, v61
	v_cvt_pk_bf16_f32 v67, v62, v63
	v_cvt_pk_bf16_f32 v59, v54, v55
	ds_bpermute_b32 v114, v52, v76
	ds_read_b128 v[52:55], v138 offset:34816
	ds_read_b128 v[60:63], v138 offset:37120
	ds_read_b128 v[90:93], v138 offset:39424
	ds_read_b128 v[94:97], v138 offset:39488
	v_add3_u32 v115, v115, v83, v85
	ds_read_b128 v[98:101], v115 offset:34816
	ds_read_b128 v[102:105], v115 offset:34880
	ds_read_b128 v[106:109], v138 offset:44032
	ds_read_b128 v[110:113], v138 offset:44096
	ds_read_b128 v[118:121], v138 offset:46336
	ds_read_b128 v[134:137], v138 offset:46400
	s_waitcnt lgkmcnt(9)
	v_mfma_f32_16x16x32_bf16 v[52:55], v[52:55], v[64:67], v[122:125]
	s_waitcnt lgkmcnt(8)
	v_mfma_f32_16x16x32_bf16 v[60:63], v[60:63], v[64:67], v[126:129]
	s_waitcnt lgkmcnt(7)
	v_mfma_f32_16x16x32_bf16 v[90:93], v[90:93], v[64:67], v[130:133]
	s_waitcnt lgkmcnt(5)
	v_mfma_f32_16x16x32_bf16 v[86:89], v[98:101], v[64:67], v[86:89]
	v_mfma_f32_16x16x32_bf16 v[90:93], v[94:97], v[56:59], v[90:93]
	s_waitcnt lgkmcnt(4)
	v_mfma_f32_16x16x32_bf16 v[86:89], v[102:105], v[56:59], v[86:89]
	ds_read_b128 v[94:97], v138 offset:48640
	ds_read_b128 v[98:101], v138 offset:48704
	ds_read_b128 v[102:105], v115 offset:44032
	ds_read_b128 v[122:125], v115 offset:44096
	v_pk_mul_f32 v[6:7], v[6:7], v[114:115] op_sel_hi:[1,0]
	v_pk_mul_f32 v[4:5], v[4:5], v[114:115] op_sel_hi:[1,0]
	v_pk_mul_f32 v[30:31], v[30:31], v[114:115] op_sel_hi:[1,0]
	v_pk_mul_f32 v[28:29], v[28:29], v[114:115] op_sel_hi:[1,0]
	s_waitcnt lgkmcnt(7)
	v_mfma_f32_16x16x32_bf16 v[4:7], v[106:109], v[64:67], v[4:7]
	s_waitcnt lgkmcnt(5)
	v_mfma_f32_16x16x32_bf16 v[28:31], v[118:121], v[64:67], v[28:31]
	v_mfma_f32_16x16x32_bf16 v[4:7], v[110:113], v[56:59], v[4:7]
	s_waitcnt lgkmcnt(4)
; #define LBAR() do { asm volatile("s_waitcnt lgkmcnt(0)" ::: "memory"); __builtin_amdgcn_s_barrier(); asm volatile("" ::: "memory"); } while (0)
; #define SBAR() __builtin_amdgcn_sched_barrier(0)
; #define LDK(d, dt0) do { d[0] = frag1(Kl + ((dt0) * 16 + r) * TS + q8 * 8); d[1] = frag1(Kl + ((dt0) * 16 + r) * TS + 32 + q8 * 8); d[2] = frag1(Kl + (((dt0) + 1) * 16 + r) * TS + q8 * 8); d[3] = frag1(Kl + (((dt0) + 1) * 16 + r) * TS + 32 + q8 * 8); } while (0)
; __device__ __forceinline__ void scan_bh(LAS unsigned char* lds, const ScanP& P, int b, int h, int half, int tid, int lane, int wave) {
;     ...
;         {
;             bf16x8 aA[6], kA[4], kB[4];
;             aA[0] = frag1(Al + (0 * 16 + r) * TS + q8 * 8); aA[1] = frag1(Al + (1 * 16 + r) * TS + q8 * 8);
;             aA[2] = frag1(Al + (2 * 16 + r) * TS + q8 * 8); aA[3] = frag1(Al + (2 * 16 + r) * TS + 32 + q8 * 8);
;             aA[4] = frag1(Al + (3 * 16 + r) * TS + q8 * 8); aA[5] = frag1(Al + (3 * 16 + r) * TS + 32 + q8 * 8);
;             SBAR(); LDK(kA, 0); SBAR();
;             o[0] = __builtin_amdgcn_mfma_f32_16x16x32_bf16(aA[0], Ub[0], o[0], 0, 0, 0); o[1] = __builtin_amdgcn_mfma_f32_16x16x32_bf16(aA[1], Ub[0], o[1], 0, 0, 0);
;             o[2] = __builtin_amdgcn_mfma_f32_16x16x32_bf16(aA[2], Ub[0], o[2], 0, 0, 0); o[3] = __builtin_amdgcn_mfma_f32_16x16x32_bf16(aA[4], Ub[0], o[3], 0, 0, 0);
;             o[2] = __builtin_amdgcn_mfma_f32_16x16x32_bf16(aA[3], Ub[1], o[2], 0, 0, 0); o[3] = __builtin_amdgcn_mfma_f32_16x16x32_bf16(aA[5], Ub[1], o[3], 0, 0, 0);
;             SBAR(); LDK(kB, 2); SBAR(); MMK(kA, 0); SBAR(); LDK(kA, 4); SBAR(); MMK(kB, 2); SBAR(); LDK(kB, 6); SBAR(); MMK(kA, 4); SBAR(); MMK(kB, 6); SBAR();
;         }
;     ...
;         { unsigned oO = (unsigned)((q8 * 4) * 1024 + c0 + r) * 4u; asm volatile("" : "+v"(oO));
;           unsigned char* ob = (unsigned char*)(P.obuf + (size_t)(b * SEQ + n * 64) * 1024 + h * 128);
; #pragma unroll
;           for (int mt = 0; mt < 4; ++mt)
; #pragma unroll
;               for (int j = 0; j < 4; ++j) *(float*)(ob + (oO + (unsigned)(mt * 16 + j) * 4096u)) = o[mt][j]; }
;             LBAR();
;         }
	v_mfma_f32_16x16x32_bf16 v[28:31], v[134:137], v[56:59], v[28:31]
	ds_read_b128 v[106:109], v138 offset:53248
	ds_read_b128 v[110:113], v138 offset:53312
	ds_read_b128 v[118:121], v138 offset:55552
	ds_read_b128 v[126:129], v138 offset:55616
	v_pk_mul_f32 v[34:35], v[34:35], v[114:115] op_sel_hi:[1,0]
	v_pk_mul_f32 v[32:33], v[32:33], v[114:115] op_sel_hi:[1,0]
	v_pk_mul_f32 v[14:15], v[14:15], v[114:115] op_sel_hi:[1,0]
	v_pk_mul_f32 v[12:13], v[12:13], v[114:115] op_sel_hi:[1,0]
	s_waitcnt lgkmcnt(7)
	v_mfma_f32_16x16x32_bf16 v[32:35], v[94:97], v[64:67], v[32:35]
	s_waitcnt lgkmcnt(5)
	v_mfma_f32_16x16x32_bf16 v[12:15], v[102:105], v[64:67], v[12:15]
	v_mfma_f32_16x16x32_bf16 v[32:35], v[98:101], v[56:59], v[32:35]
	s_waitcnt lgkmcnt(4)
	v_mfma_f32_16x16x32_bf16 v[12:15], v[122:125], v[56:59], v[12:15]
	v_add3_u32 v115, s15, v81, v85
	ds_read_b128 v[94:97], v138 offset:57856
	ds_read_b128 v[98:101], v138 offset:57920
	ds_read_b128 v[102:105], v115 offset:44032
	ds_read_b128 v[122:125], v115 offset:44096
	v_pk_mul_f32 v[22:23], v[22:23], v[114:115] op_sel_hi:[1,0]
	v_pk_mul_f32 v[20:21], v[20:21], v[114:115] op_sel_hi:[1,0]
	v_pk_mul_f32 v[10:11], v[10:11], v[114:115] op_sel_hi:[1,0]
	v_pk_mul_f32 v[8:9], v[8:9], v[114:115] op_sel_hi:[1,0]
	s_waitcnt lgkmcnt(7)
	v_mfma_f32_16x16x32_bf16 v[20:23], v[106:109], v[64:67], v[20:23]
	s_waitcnt lgkmcnt(5)
	v_mfma_f32_16x16x32_bf16 v[8:11], v[118:121], v[64:67], v[8:11]
	v_mfma_f32_16x16x32_bf16 v[20:23], v[110:113], v[56:59], v[20:23]
	s_waitcnt lgkmcnt(4)
	v_mfma_f32_16x16x32_bf16 v[8:11], v[126:129], v[56:59], v[8:11]
	v_mul_f32_e64 v26, v26, v114
	v_mul_f32_e64 v27, v27, v114
	v_pk_mul_f32 v[24:25], v[24:25], v[114:115] op_sel_hi:[1,0]
	v_pk_mul_f32 v[18:19], v[18:19], v[114:115] op_sel_hi:[1,0]
	v_pk_mul_f32 v[16:17], v[16:17], v[114:115] op_sel_hi:[1,0]
	s_waitcnt lgkmcnt(3)
	v_mfma_f32_16x16x32_bf16 v[24:27], v[94:97], v[64:67], v[24:27]
	s_waitcnt lgkmcnt(1)
	v_mfma_f32_16x16x32_bf16 v[16:19], v[102:105], v[64:67], v[16:19]
	v_mfma_f32_16x16x32_bf16 v[24:27], v[98:101], v[56:59], v[24:27]
	s_waitcnt lgkmcnt(0)
	v_mfma_f32_16x16x32_bf16 v[16:19], v[122:125], v[56:59], v[16:19]
	v_mov_b32_e32 v152, v82
	v_mov_b64_e32 v[66:67], v[230:231]
	v_lshl_add_u64 v[56:57], s[4:5], 0, v[152:153]
	v_lshl_add_u64 v[56:57], v[2:3], 0, v[56:57]
	global_store_dword v[56:57], v52, off
	v_add_u32_e32 v56, 0x1000, v152
	v_mov_b32_e32 v57, v153
	v_lshl_add_u64 v[56:57], s[4:5], 0, v[56:57]
	v_lshl_add_u64 v[56:57], v[2:3], 0, v[56:57]
	global_store_dword v[56:57], v53, off
	v_add_u32_e32 v52, 0x2000, v152
	v_mov_b32_e32 v53, v153
	v_lshl_add_u64 v[52:53], s[4:5], 0, v[52:53]
	v_lshl_add_u64 v[52:53], v[2:3], 0, v[52:53]
	global_store_dword v[52:53], v54, off
	v_add_u32_e32 v52, 0x3000, v152
	v_mov_b32_e32 v53, v153
	v_lshl_add_u64 v[52:53], s[4:5], 0, v[52:53]
	v_lshl_add_u64 v[52:53], v[2:3], 0, v[52:53]
	global_store_dword v[52:53], v55, off
	v_add_u32_e32 v52, 0x10000, v152
	v_mov_b32_e32 v53, v153
	v_lshl_add_u64 v[52:53], s[4:5], 0, v[52:53]
	v_lshl_add_u64 v[52:53], v[2:3], 0, v[52:53]
	global_store_dword v[52:53], v60, off
	v_add_u32_e32 v52, 0x11000, v152
	v_mov_b32_e32 v53, v153
	v_lshl_add_u64 v[52:53], s[4:5], 0, v[52:53]
	v_lshl_add_u64 v[52:53], v[2:3], 0, v[52:53]
	global_store_dword v[52:53], v61, off
	v_add_u32_e32 v52, 0x12000, v152
	v_mov_b32_e32 v53, v153
	v_lshl_add_u64 v[52:53], s[4:5], 0, v[52:53]
	v_lshl_add_u64 v[52:53], v[2:3], 0, v[52:53]
	global_store_dword v[52:53], v62, off
	v_add_u32_e32 v52, 0x13000, v152
	v_mov_b32_e32 v53, v153
	v_lshl_add_u64 v[52:53], s[4:5], 0, v[52:53]
	v_lshl_add_u64 v[52:53], v[2:3], 0, v[52:53]
	global_store_dword v[52:53], v63, off
	v_add_u32_e32 v52, 0x20000, v152
	v_mov_b32_e32 v53, v153
	v_lshl_add_u64 v[52:53], s[4:5], 0, v[52:53]
	v_lshl_add_u64 v[52:53], v[2:3], 0, v[52:53]
	global_store_dword v[52:53], v90, off
	v_add_u32_e32 v52, 0x21000, v152
	v_mov_b32_e32 v53, v153
	v_lshl_add_u64 v[52:53], s[4:5], 0, v[52:53]
	v_lshl_add_u64 v[52:53], v[2:3], 0, v[52:53]
	global_store_dword v[52:53], v91, off
	v_add_u32_e32 v52, 0x22000, v152
	v_mov_b32_e32 v53, v153
	v_lshl_add_u64 v[52:53], s[4:5], 0, v[52:53]
	v_lshl_add_u64 v[52:53], v[2:3], 0, v[52:53]
	global_store_dword v[52:53], v92, off
	v_add_u32_e32 v52, 0x23000, v152
	v_mov_b32_e32 v53, v153
	v_lshl_add_u64 v[52:53], s[4:5], 0, v[52:53]
	v_lshl_add_u64 v[52:53], v[2:3], 0, v[52:53]
	global_store_dword v[52:53], v93, off
	v_add_u32_e32 v52, 0x30000, v152
	v_mov_b32_e32 v53, v153
	v_lshl_add_u64 v[52:53], s[4:5], 0, v[52:53]
	v_lshl_add_u64 v[52:53], v[2:3], 0, v[52:53]
	global_store_dword v[52:53], v86, off
	v_add_u32_e32 v52, 0x31000, v152
	v_mov_b32_e32 v53, v153
	v_lshl_add_u64 v[52:53], s[4:5], 0, v[52:53]
	v_lshl_add_u64 v[52:53], v[2:3], 0, v[52:53]
	global_store_dword v[52:53], v87, off
	v_add_u32_e32 v52, 0x32000, v152
	v_mov_b32_e32 v53, v153
	v_lshl_add_u64 v[52:53], s[4:5], 0, v[52:53]
	v_lshl_add_u64 v[52:53], v[2:3], 0, v[52:53]
	v_add_u32_e32 v152, 0x33000, v152
	global_store_dword v[52:53], v88, off
	v_lshl_add_u64 v[52:53], s[4:5], 0, v[152:153]
	v_lshl_add_u64 v[52:53], v[2:3], 0, v[52:53]
	global_store_dword v[52:53], v89, off
	s_waitcnt lgkmcnt(0)
	s_barrier
	s_add_u32 s4, s4, 0x40000
	s_addc_u32 s5, s5, 0
	s_add_i32 s10, s10, 4
	s_add_i32 s11, s11, 8
	s_add_i32 s14, s14, 1
	v_mov_b64_e32 v[54:55], v[218:219]
	v_mov_b64_e32 v[58:59], v[222:223]
	v_mov_b64_e32 v[62:63], v[226:227]
	s_cmp_eq_u32 s4, 0x800000
	v_mov_b64_e32 v[52:53], v[216:217]
	v_mov_b64_e32 v[56:57], v[220:221]
	v_mov_b64_e32 v[60:61], v[224:225]
	v_mov_b64_e32 v[64:65], v[228:229]
; #define LAS __attribute__((address_space(3)))
; __device__ __forceinline__ bf16x8 packB(const f32x4& a, const f32x4& b) { u32x4 v = {pk2(a[0], a[1]), pk2(a[2], a[3]), pk2(b[0], b[1]), pk2(b[2], b[3])}; return __builtin_bit_cast(bf16x8, v); }
; #define U_LOAD(nn) do { const unsigned char* tr_ = P.tr + (size_t)((b << 8) | ((nn) << 3) | h) * TR_SZ; \
;             _Pragma("unroll") for (int mt_ = 0; mt_ < 4; ++mt_) ubn[mt_] = *(const f32x4*)(tr_ + (oU + (unsigned)mt_ * 1024u)); } while (0)
; #define SBAR() __builtin_amdgcn_sched_barrier(0)
; #define LD4(d, base, mt, stride) do { _Pragma("unroll") for (int ks = 0; ks < 4; ++ks) d[ks] = frag1((base) + ((mt) * 16 + r) * (stride) + ks * 32 + q8 * 8); } while (0)
; #define MM4(acc, s_) do { _Pragma("unroll") for (int ks = 0; ks < 4; ++ks) acc = __builtin_amdgcn_mfma_f32_16x16x32_bf16(s_[ks], Sb[ks], acc, 0, 0, 0); } while (0)
; __device__ __forceinline__ void scan_bh(LAS unsigned char* lds, const ScanP& P, int b, int h, int half, int tid, int lane, int wave) {
;     ...
; #pragma unroll 1
;         for (int n = 0; n < 32; ++n) {
;             LAS unsigned char* buf = lds + (n & 1) * SB_SZ;
;             const LAS bf16_t* Wl = (const LAS bf16_t*)(buf + SB_W); const LAS bf16_t* Ql = (const LAS bf16_t*)(buf + SB_Q);
;             const LAS bf16_t* Al = (const LAS bf16_t*)(buf + SB_A); const LAS bf16_t* Kl = (const LAS bf16_t*)(buf + SB_K);
;             f32x4 u[4], o[4];
; #pragma unroll
;             for (int mt = 0; mt < 4; ++mt) { u[mt] = ubn[mt]; o[mt] = (f32x4){0.f, 0.f, 0.f, 0.f}; }
;             if (n + 1 < 32) U_LOAD(n + 1);
;         bf16x8 Sb[4];
; #pragma unroll
;         for (int ks = 0; ks < 4; ++ks) Sb[ks] = packB(S[2 * ks], S[2 * ks + 1]);
;     ...
;         {
;             bf16x8 fA[4], fB[4];
;             LD4(fA, Wl, 0, PS); SBAR(); LD4(fB, Ql, 0, PS); SBAR();
;             MM4(u[0], fA); SBAR(); LD4(fA, Wl, 1, PS); SBAR(); MM4(o[0], fB); SBAR(); LD4(fB, Ql, 1, PS); SBAR();
;             MM4(u[1], fA); SBAR(); LD4(fA, Wl, 2, PS); SBAR(); MM4(o[1], fB); SBAR(); LD4(fB, Ql, 2, PS); SBAR();
;             MM4(u[2], fA); SBAR(); LD4(fA, Wl, 3, PS); SBAR(); MM4(o[2], fB); SBAR(); LD4(fB, Ql, 3, PS); SBAR();
.Lscan_c3:
	s_add_i32 s15, s11, 24
	s_min_u32 s15, s15, 0xf8
	s_or_b32 s15, s15, s6
	v_mad_i64_i32 v[44:45], s[16:17], s15, v199, v[116:117]
	v_lshl_add_u64 v[36:37], v[44:45], 0, v[74:75]
	v_lshl_add_u64 v[38:39], v[44:45], 0, v[72:73]
	v_lshl_add_u64 v[46:47], v[44:45], 0, v[70:71]
	v_lshl_add_u64 v[44:45], v[44:45], 0, v[68:69]
	global_load_dwordx4 v[216:219], v[36:37], off
	global_load_dwordx4 v[220:223], v[38:39], off
	global_load_dwordx4 v[224:227], v[46:47], off
	global_load_dwordx4 v[228:231], v[44:45], off
	s_waitcnt vmcnt(60)
	s_bitcmp1_b32 s14, 0
	s_cselect_b32 s15, 0xf400, 0
	s_add_i32 s15, s15, 0
	v_add3_u32 v114, s15, v78, v79
	ds_read_b128 v[98:101], v114
	ds_read_b128 v[102:105], v114 offset:64
	ds_read_b128 v[106:109], v114 offset:128
	ds_read_b128 v[110:113], v114 offset:192
	v_cvt_pk_bf16_f32 v86, v4, v5
	v_cvt_pk_bf16_f32 v87, v6, v7
	v_cvt_pk_bf16_f32 v88, v28, v29
	v_cvt_pk_bf16_f32 v89, v30, v31
	v_cvt_pk_bf16_f32 v90, v32, v33
	v_cvt_pk_bf16_f32 v91, v34, v35
	v_cvt_pk_bf16_f32 v92, v12, v13
	v_cvt_pk_bf16_f32 v93, v14, v15
	v_cvt_pk_bf16_f32 v94, v20, v21
	v_cvt_pk_bf16_f32 v95, v22, v23
	v_cvt_pk_bf16_f32 v96, v8, v9
	v_cvt_pk_bf16_f32 v97, v10, v11
	v_cvt_pk_bf16_f32 v118, v24, v25
	v_cvt_pk_bf16_f32 v119, v26, v27
	v_cvt_pk_bf16_f32 v120, v16, v17
	v_cvt_pk_bf16_f32 v121, v18, v19
	ds_read_b128 v[122:125], v114 offset:17408
	ds_read_b128 v[126:129], v114 offset:17472
	ds_read_b128 v[130:133], v114 offset:17536
	ds_read_b128 v[134:137], v114 offset:17600
	s_waitcnt lgkmcnt(7)
	v_mfma_f32_16x16x32_bf16 v[64:67], v[98:101], v[86:89], v[64:67]
	s_waitcnt lgkmcnt(6)
	v_mfma_f32_16x16x32_bf16 v[64:67], v[102:105], v[90:93], v[64:67]
	s_waitcnt lgkmcnt(5)
	v_mfma_f32_16x16x32_bf16 v[64:67], v[106:109], v[94:97], v[64:67]
	s_waitcnt lgkmcnt(4)
	v_mfma_f32_16x16x32_bf16 v[64:67], v[110:113], v[118:121], v[64:67]
	ds_read_b128 v[98:101], v114 offset:4352
	ds_read_b128 v[102:105], v114 offset:4416
	ds_read_b128 v[106:109], v114 offset:4480
	ds_read_b128 v[110:113], v114 offset:4544
	s_waitcnt lgkmcnt(7)
	v_mfma_f32_16x16x32_bf16 v[122:125], v[122:125], v[86:89], 0
	s_waitcnt lgkmcnt(6)
	v_mfma_f32_16x16x32_bf16 v[122:125], v[126:129], v[90:93], v[122:125]
	s_waitcnt lgkmcnt(5)
	v_mfma_f32_16x16x32_bf16 v[122:125], v[130:133], v[94:97], v[122:125]
	s_waitcnt lgkmcnt(4)
	v_mfma_f32_16x16x32_bf16 v[122:125], v[134:137], v[118:121], v[122:125]
	ds_read_b128 v[126:129], v114 offset:21760
	ds_read_b128 v[130:133], v114 offset:21824
	ds_read_b128 v[134:137], v114 offset:21888
	ds_read_b128 v[138:141], v114 offset:21952
	s_waitcnt lgkmcnt(7)
	v_mfma_f32_16x16x32_bf16 v[60:63], v[98:101], v[86:89], v[60:63]
	s_waitcnt lgkmcnt(6)
	v_mfma_f32_16x16x32_bf16 v[60:63], v[102:105], v[90:93], v[60:63]
	s_waitcnt lgkmcnt(5)
	v_mfma_f32_16x16x32_bf16 v[60:63], v[106:109], v[94:97], v[60:63]
	s_waitcnt lgkmcnt(4)
	v_mfma_f32_16x16x32_bf16 v[60:63], v[110:113], v[118:121], v[60:63]
	ds_read_b128 v[98:101], v114 offset:8704
	ds_read_b128 v[102:105], v114 offset:8768
	ds_read_b128 v[106:109], v114 offset:8832
	ds_read_b128 v[110:113], v114 offset:8896
	s_waitcnt lgkmcnt(7)
	v_mfma_f32_16x16x32_bf16 v[126:129], v[126:129], v[86:89], 0
	s_waitcnt lgkmcnt(6)
	v_mfma_f32_16x16x32_bf16 v[126:129], v[130:133], v[90:93], v[126:129]
	s_waitcnt lgkmcnt(5)
	v_mfma_f32_16x16x32_bf16 v[126:129], v[134:137], v[94:97], v[126:129]
	s_waitcnt lgkmcnt(4)
	v_mfma_f32_16x16x32_bf16 v[126:129], v[138:141], v[118:121], v[126:129]
	ds_read_b128 v[130:133], v114 offset:26112
	ds_read_b128 v[134:137], v114 offset:26176
	ds_read_b128 v[138:141], v114 offset:26240
	ds_read_b128 v[146:149], v114 offset:26304
	s_waitcnt lgkmcnt(7)
	v_mfma_f32_16x16x32_bf16 v[56:59], v[98:101], v[86:89], v[56:59]
	s_waitcnt lgkmcnt(6)
	v_mfma_f32_16x16x32_bf16 v[56:59], v[102:105], v[90:93], v[56:59]
	s_waitcnt lgkmcnt(5)
	v_mfma_f32_16x16x32_bf16 v[56:59], v[106:109], v[94:97], v[56:59]
	s_waitcnt lgkmcnt(4)
	v_mfma_f32_16x16x32_bf16 v[56:59], v[110:113], v[118:121], v[56:59]
	v_add_u32_e32 v115, s15, v80
	v_add_u32_e32 v114, v115, v79
	ds_read_b128 v[98:101], v114
	ds_read_b128 v[102:105], v114 offset:64
	ds_read_b128 v[106:109], v114 offset:128
	ds_read_b128 v[110:113], v114 offset:192
	s_waitcnt lgkmcnt(7)
	v_mfma_f32_16x16x32_bf16 v[130:133], v[130:133], v[86:89], 0
	s_waitcnt lgkmcnt(6)
	v_mfma_f32_16x16x32_bf16 v[130:133], v[134:137], v[90:93], v[130:133]
	s_waitcnt lgkmcnt(5)
	v_mfma_f32_16x16x32_bf16 v[130:133], v[138:141], v[94:97], v[130:133]
	s_waitcnt lgkmcnt(4)
	v_mfma_f32_16x16x32_bf16 v[130:133], v[146:149], v[118:121], v[130:133]
	ds_read_b128 v[134:137], v114 offset:17408
	ds_read_b128 v[138:141], v114 offset:17472
	ds_read_b128 v[146:149], v114 offset:17536
	ds_read_b128 v[156:159], v114 offset:17600
	s_waitcnt lgkmcnt(7)
	v_mfma_f32_16x16x32_bf16 v[52:55], v[98:101], v[86:89], v[52:55]
	s_waitcnt lgkmcnt(6)
	v_mfma_f32_16x16x32_bf16 v[52:55], v[102:105], v[90:93], v[52:55]
	s_waitcnt lgkmcnt(5)
	v_mfma_f32_16x16x32_bf16 v[52:55], v[106:109], v[94:97], v[52:55]
	s_waitcnt lgkmcnt(4)
	v_mfma_f32_16x16x32_bf16 v[52:55], v[110:113], v[118:121], v[52:55]
	s_waitcnt lgkmcnt(3)
	v_mfma_f32_16x16x32_bf16 v[86:89], v[134:137], v[86:89], 0
	s_waitcnt lgkmcnt(2)
	v_mfma_f32_16x16x32_bf16 v[86:89], v[138:141], v[90:93], v[86:89]
	s_waitcnt lgkmcnt(1)
	v_mfma_f32_16x16x32_bf16 v[86:89], v[146:149], v[94:97], v[86:89]
	s_waitcnt lgkmcnt(0)
; __device__ __forceinline__ bf16x8 packB(const f32x4& a, const f32x4& b) { u32x4 v = {pk2(a[0], a[1]), pk2(a[2], a[3]), pk2(b[0], b[1]), pk2(b[2], b[3])}; return __builtin_bit_cast(bf16x8, v); }
; #define SBAR() __builtin_amdgcn_sched_barrier(0)
; #define LDK(d, dt0) do { d[0] = frag1(Kl + ((dt0) * 16 + r) * TS + q8 * 8); d[1] = frag1(Kl + ((dt0) * 16 + r) * TS + 32 + q8 * 8); d[2] = frag1(Kl + (((dt0) + 1) * 16 + r) * TS + q8 * 8); d[3] = frag1(Kl + (((dt0) + 1) * 16 + r) * TS + 32 + q8 * 8); } while (0)
; __device__ __forceinline__ void scan_bh(LAS unsigned char* lds, const ScanP& P, int b, int h, int half, int tid, int lane, int wave) {
;     ...
;         bf16x8 Ub[2];
;         Ub[0] = packB(u[0], u[1]); Ub[1] = packB(u[2], u[3]);
;         const float gl = __shfl(glv, n);
;     ...
;         {
;             bf16x8 aA[6], kA[4], kB[4];
;             aA[0] = frag1(Al + (0 * 16 + r) * TS + q8 * 8); aA[1] = frag1(Al + (1 * 16 + r) * TS + q8 * 8);
;             aA[2] = frag1(Al + (2 * 16 + r) * TS + q8 * 8); aA[3] = frag1(Al + (2 * 16 + r) * TS + 32 + q8 * 8);
;             aA[4] = frag1(Al + (3 * 16 + r) * TS + q8 * 8); aA[5] = frag1(Al + (3 * 16 + r) * TS + 32 + q8 * 8);
;             SBAR(); LDK(kA, 0); SBAR();
;             o[0] = __builtin_amdgcn_mfma_f32_16x16x32_bf16(aA[0], Ub[0], o[0], 0, 0, 0); o[1] = __builtin_amdgcn_mfma_f32_16x16x32_bf16(aA[1], Ub[0], o[1], 0, 0, 0);
;             o[2] = __builtin_amdgcn_mfma_f32_16x16x32_bf16(aA[2], Ub[0], o[2], 0, 0, 0); o[3] = __builtin_amdgcn_mfma_f32_16x16x32_bf16(aA[4], Ub[0], o[3], 0, 0, 0);
;             o[2] = __builtin_amdgcn_mfma_f32_16x16x32_bf16(aA[3], Ub[1], o[2], 0, 0, 0); o[3] = __builtin_amdgcn_mfma_f32_16x16x32_bf16(aA[5], Ub[1], o[3], 0, 0, 0);
;             SBAR(); LDK(kB, 2); SBAR(); MMK(kA, 0); SBAR(); LDK(kA, 4); SBAR(); MMK(kB, 2); SBAR(); LDK(kB, 6); SBAR(); MMK(kA, 4); SBAR(); MMK(kB, 6); SBAR();
	v_mfma_f32_16x16x32_bf16 v[86:89], v[156:159], v[118:121], v[86:89]
	v_cvt_pk_bf16_f32 v56, v56, v57
	v_cvt_pk_bf16_f32 v57, v58, v59
	v_cvt_pk_bf16_f32 v58, v52, v53
	v_lshlrev_b32_e32 v52, 2, v192
	v_and_b32_e32 v52, 0x100, v52
	v_add_u32_e32 v52, s10, v52
	v_add3_u32 v138, s15, v84, v85
	v_cvt_pk_bf16_f32 v64, v64, v65
	v_cvt_pk_bf16_f32 v65, v66, v67
	v_cvt_pk_bf16_f32 v66, v60, v61
	v_cvt_pk_bf16_f32 v67, v62, v63
	v_cvt_pk_bf16_f32 v59, v54, v55
	ds_bpermute_b32 v114, v52, v76
	ds_read_b128 v[52:55], v138 offset:34816
	ds_read_b128 v[60:63], v138 offset:37120
	ds_read_b128 v[90:93], v138 offset:39424
	ds_read_b128 v[94:97], v138 offset:39488
	v_add3_u32 v115, v115, v83, v85
	ds_read_b128 v[98:101], v115 offset:34816
	ds_read_b128 v[102:105], v115 offset:34880
	ds_read_b128 v[106:109], v138 offset:44032
	ds_read_b128 v[110:113], v138 offset:44096
	ds_read_b128 v[118:121], v138 offset:46336
	ds_read_b128 v[134:137], v138 offset:46400
	s_waitcnt lgkmcnt(9)
	v_mfma_f32_16x16x32_bf16 v[52:55], v[52:55], v[64:67], v[122:125]
	s_waitcnt lgkmcnt(8)
	v_mfma_f32_16x16x32_bf16 v[60:63], v[60:63], v[64:67], v[126:129]
	s_waitcnt lgkmcnt(7)
	v_mfma_f32_16x16x32_bf16 v[90:93], v[90:93], v[64:67], v[130:133]
	s_waitcnt lgkmcnt(5)
	v_mfma_f32_16x16x32_bf16 v[86:89], v[98:101], v[64:67], v[86:89]
	v_mfma_f32_16x16x32_bf16 v[90:93], v[94:97], v[56:59], v[90:93]
	s_waitcnt lgkmcnt(4)
	v_mfma_f32_16x16x32_bf16 v[86:89], v[102:105], v[56:59], v[86:89]
	ds_read_b128 v[94:97], v138 offset:48640
	ds_read_b128 v[98:101], v138 offset:48704
	ds_read_b128 v[102:105], v115 offset:44032
	ds_read_b128 v[122:125], v115 offset:44096
	v_pk_mul_f32 v[6:7], v[6:7], v[114:115] op_sel_hi:[1,0]
	v_pk_mul_f32 v[4:5], v[4:5], v[114:115] op_sel_hi:[1,0]
	v_pk_mul_f32 v[30:31], v[30:31], v[114:115] op_sel_hi:[1,0]
	v_pk_mul_f32 v[28:29], v[28:29], v[114:115] op_sel_hi:[1,0]
	s_waitcnt lgkmcnt(7)
	v_mfma_f32_16x16x32_bf16 v[4:7], v[106:109], v[64:67], v[4:7]
	s_waitcnt lgkmcnt(5)
	v_mfma_f32_16x16x32_bf16 v[28:31], v[118:121], v[64:67], v[28:31]
	v_mfma_f32_16x16x32_bf16 v[4:7], v[110:113], v[56:59], v[4:7]
	s_waitcnt lgkmcnt(4)
	v_mfma_f32_16x16x32_bf16 v[28:31], v[134:137], v[56:59], v[28:31]
	ds_read_b128 v[106:109], v138 offset:53248
	ds_read_b128 v[110:113], v138 offset:53312
	ds_read_b128 v[118:121], v138 offset:55552
	ds_read_b128 v[126:129], v138 offset:55616
	v_pk_mul_f32 v[34:35], v[34:35], v[114:115] op_sel_hi:[1,0]
	v_pk_mul_f32 v[32:33], v[32:33], v[114:115] op_sel_hi:[1,0]
	v_pk_mul_f32 v[14:15], v[14:15], v[114:115] op_sel_hi:[1,0]
	v_pk_mul_f32 v[12:13], v[12:13], v[114:115] op_sel_hi:[1,0]
	s_waitcnt lgkmcnt(7)
	v_mfma_f32_16x16x32_bf16 v[32:35], v[94:97], v[64:67], v[32:35]
	s_waitcnt lgkmcnt(5)
	v_mfma_f32_16x16x32_bf16 v[12:15], v[102:105], v[64:67], v[12:15]
	v_mfma_f32_16x16x32_bf16 v[32:35], v[98:101], v[56:59], v[32:35]
	s_waitcnt lgkmcnt(4)
	v_mfma_f32_16x16x32_bf16 v[12:15], v[122:125], v[56:59], v[12:15]
	v_add3_u32 v115, s15, v81, v85
	ds_read_b128 v[94:97], v138 offset:57856
	ds_read_b128 v[98:101], v138 offset:57920
	ds_read_b128 v[102:105], v115 offset:44032
	ds_read_b128 v[122:125], v115 offset:44096
	v_pk_mul_f32 v[22:23], v[22:23], v[114:115] op_sel_hi:[1,0]
	v_pk_mul_f32 v[20:21], v[20:21], v[114:115] op_sel_hi:[1,0]
	v_pk_mul_f32 v[10:11], v[10:11], v[114:115] op_sel_hi:[1,0]
	v_pk_mul_f32 v[8:9], v[8:9], v[114:115] op_sel_hi:[1,0]
	s_waitcnt lgkmcnt(7)
	v_mfma_f32_16x16x32_bf16 v[20:23], v[106:109], v[64:67], v[20:23]
	s_waitcnt lgkmcnt(5)
	v_mfma_f32_16x16x32_bf16 v[8:11], v[118:121], v[64:67], v[8:11]
	v_mfma_f32_16x16x32_bf16 v[20:23], v[110:113], v[56:59], v[20:23]
	s_waitcnt lgkmcnt(4)
	v_mfma_f32_16x16x32_bf16 v[8:11], v[126:129], v[56:59], v[8:11]
	v_mul_f32_e64 v26, v26, v114
	v_mul_f32_e64 v27, v27, v114
	v_pk_mul_f32 v[24:25], v[24:25], v[114:115] op_sel_hi:[1,0]
	v_pk_mul_f32 v[18:19], v[18:19], v[114:115] op_sel_hi:[1,0]
	v_pk_mul_f32 v[16:17], v[16:17], v[114:115] op_sel_hi:[1,0]
	s_waitcnt lgkmcnt(3)
; #define LBAR() do { asm volatile("s_waitcnt lgkmcnt(0)" ::: "memory"); __builtin_amdgcn_s_barrier(); asm volatile("" ::: "memory"); } while (0)
; #define SBAR() __builtin_amdgcn_sched_barrier(0)
; #define LDK(d, dt0) do { d[0] = frag1(Kl + ((dt0) * 16 + r) * TS + q8 * 8); d[1] = frag1(Kl + ((dt0) * 16 + r) * TS + 32 + q8 * 8); d[2] = frag1(Kl + (((dt0) + 1) * 16 + r) * TS + q8 * 8); d[3] = frag1(Kl + (((dt0) + 1) * 16 + r) * TS + 32 + q8 * 8); } while (0)
; __device__ __forceinline__ void scan_bh(LAS unsigned char* lds, const ScanP& P, int b, int h, int half, int tid, int lane, int wave) {
;     ...
;             SBAR(); LDK(kB, 2); SBAR(); MMK(kA, 0); SBAR(); LDK(kA, 4); SBAR(); MMK(kB, 2); SBAR(); LDK(kB, 6); SBAR(); MMK(kA, 4); SBAR(); MMK(kB, 6); SBAR();
;         }
;     ...
;         { unsigned oO = (unsigned)((q8 * 4) * 1024 + c0 + r) * 4u; asm volatile("" : "+v"(oO));
;           unsigned char* ob = (unsigned char*)(P.obuf + (size_t)(b * SEQ + n * 64) * 1024 + h * 128);
; #pragma unroll
;           for (int mt = 0; mt < 4; ++mt)
; #pragma unroll
;               for (int j = 0; j < 4; ++j) *(float*)(ob + (oO + (unsigned)(mt * 16 + j) * 4096u)) = o[mt][j]; }
;             LBAR();
;         }
	v_mfma_f32_16x16x32_bf16 v[24:27], v[94:97], v[64:67], v[24:27]
	s_waitcnt lgkmcnt(1)
	v_mfma_f32_16x16x32_bf16 v[16:19], v[102:105], v[64:67], v[16:19]
	v_mfma_f32_16x16x32_bf16 v[24:27], v[98:101], v[56:59], v[24:27]
	s_waitcnt lgkmcnt(0)
	v_mfma_f32_16x16x32_bf16 v[16:19], v[122:125], v[56:59], v[16:19]
	v_mov_b32_e32 v152, v82
	v_mov_b64_e32 v[66:67], v[174:175]
	v_lshl_add_u64 v[56:57], s[4:5], 0, v[152:153]
	v_lshl_add_u64 v[56:57], v[2:3], 0, v[56:57]
	global_store_dword v[56:57], v52, off
	v_add_u32_e32 v56, 0x1000, v152
	v_mov_b32_e32 v57, v153
	v_lshl_add_u64 v[56:57], s[4:5], 0, v[56:57]
	v_lshl_add_u64 v[56:57], v[2:3], 0, v[56:57]
	global_store_dword v[56:57], v53, off
	v_add_u32_e32 v52, 0x2000, v152
	v_mov_b32_e32 v53, v153
	v_lshl_add_u64 v[52:53], s[4:5], 0, v[52:53]
	v_lshl_add_u64 v[52:53], v[2:3], 0, v[52:53]
	global_store_dword v[52:53], v54, off
	v_add_u32_e32 v52, 0x3000, v152
	v_mov_b32_e32 v53, v153
	v_lshl_add_u64 v[52:53], s[4:5], 0, v[52:53]
	v_lshl_add_u64 v[52:53], v[2:3], 0, v[52:53]
	global_store_dword v[52:53], v55, off
	v_add_u32_e32 v52, 0x10000, v152
	v_mov_b32_e32 v53, v153
	v_lshl_add_u64 v[52:53], s[4:5], 0, v[52:53]
	v_lshl_add_u64 v[52:53], v[2:3], 0, v[52:53]
	global_store_dword v[52:53], v60, off
	v_add_u32_e32 v52, 0x11000, v152
	v_mov_b32_e32 v53, v153
	v_lshl_add_u64 v[52:53], s[4:5], 0, v[52:53]
	v_lshl_add_u64 v[52:53], v[2:3], 0, v[52:53]
	global_store_dword v[52:53], v61, off
	v_add_u32_e32 v52, 0x12000, v152
	v_mov_b32_e32 v53, v153
	v_lshl_add_u64 v[52:53], s[4:5], 0, v[52:53]
	v_lshl_add_u64 v[52:53], v[2:3], 0, v[52:53]
	global_store_dword v[52:53], v62, off
	v_add_u32_e32 v52, 0x13000, v152
	v_mov_b32_e32 v53, v153
	v_lshl_add_u64 v[52:53], s[4:5], 0, v[52:53]
	v_lshl_add_u64 v[52:53], v[2:3], 0, v[52:53]
	global_store_dword v[52:53], v63, off
	v_add_u32_e32 v52, 0x20000, v152
	v_mov_b32_e32 v53, v153
	v_lshl_add_u64 v[52:53], s[4:5], 0, v[52:53]
	v_lshl_add_u64 v[52:53], v[2:3], 0, v[52:53]
	global_store_dword v[52:53], v90, off
	v_add_u32_e32 v52, 0x21000, v152
	v_mov_b32_e32 v53, v153
	v_lshl_add_u64 v[52:53], s[4:5], 0, v[52:53]
	v_lshl_add_u64 v[52:53], v[2:3], 0, v[52:53]
	global_store_dword v[52:53], v91, off
	v_add_u32_e32 v52, 0x22000, v152
	v_mov_b32_e32 v53, v153
	v_lshl_add_u64 v[52:53], s[4:5], 0, v[52:53]
	v_lshl_add_u64 v[52:53], v[2:3], 0, v[52:53]
	global_store_dword v[52:53], v92, off
	v_add_u32_e32 v52, 0x23000, v152
	v_mov_b32_e32 v53, v153
	v_lshl_add_u64 v[52:53], s[4:5], 0, v[52:53]
	v_lshl_add_u64 v[52:53], v[2:3], 0, v[52:53]
	global_store_dword v[52:53], v93, off
	v_add_u32_e32 v52, 0x30000, v152
	v_mov_b32_e32 v53, v153
	v_lshl_add_u64 v[52:53], s[4:5], 0, v[52:53]
	v_lshl_add_u64 v[52:53], v[2:3], 0, v[52:53]
	global_store_dword v[52:53], v86, off
	v_add_u32_e32 v52, 0x31000, v152
	v_mov_b32_e32 v53, v153
	v_lshl_add_u64 v[52:53], s[4:5], 0, v[52:53]
	v_lshl_add_u64 v[52:53], v[2:3], 0, v[52:53]
	global_store_dword v[52:53], v87, off
	v_add_u32_e32 v52, 0x32000, v152
	v_mov_b32_e32 v53, v153
	v_lshl_add_u64 v[52:53], s[4:5], 0, v[52:53]
	v_lshl_add_u64 v[52:53], v[2:3], 0, v[52:53]
	v_add_u32_e32 v152, 0x33000, v152
	global_store_dword v[52:53], v88, off
	v_lshl_add_u64 v[52:53], s[4:5], 0, v[152:153]
	v_lshl_add_u64 v[52:53], v[2:3], 0, v[52:53]
	global_store_dword v[52:53], v89, off
	s_waitcnt lgkmcnt(0)
	s_barrier
	s_add_u32 s4, s4, 0x40000
	s_addc_u32 s5, s5, 0
	s_add_i32 s10, s10, 4
	s_add_i32 s11, s11, 8
	s_add_i32 s14, s14, 1
	v_mov_b64_e32 v[54:55], v[162:163]
	v_mov_b64_e32 v[58:59], v[166:167]
	v_mov_b64_e32 v[62:63], v[170:171]
	s_cmp_eq_u32 s4, 0x800000
	v_mov_b64_e32 v[52:53], v[160:161]
	v_mov_b64_e32 v[56:57], v[164:165]
	v_mov_b64_e32 v[60:61], v[168:169]
	v_mov_b64_e32 v[64:65], v[172:173]
	s_cbranch_scc0 .Lscan_c0
